# adds GEMM mainloops: the s_setprio 0 / s_setprio 1 pair in the middle of each 32-MFMA block removed
# speedup vs baseline: 1.0161x; 1.0007x over previous
; #define PG8_STAGE(bufoff, gbase, voff) do { _Pragma("unroll") for (int _i = 0; _i < 2; ++_i) \
;         __builtin_amdgcn_global_load_lds((const unsigned*)((const char*)(gbase) + (voff)[_i]), (PG8_LAS unsigned*)(lds + (bufoff) + ldsw + _i * 8192), 16, 0, 0); } while (0)
; #define PG8_LDA(dst, b, h) do { _Pragma("unroll") for (int m = 0; m < 4; ++m) _Pragma("unroll") for (int k = 0; k < 2; ++k) dst[m][k] = *(const PG8_LAS bf16x8*)(lds + PG8_SA(b, h) + aoff + m * 2048 + k * 1024); } while (0)
; #define PG8_LDB(dst, b, h) do { _Pragma("unroll") for (int n = 0; n < 2; ++n) _Pragma("unroll") for (int k = 0; k < 2; ++k) dst[n][k] = *(const PG8_LAS bf16x8*)(lds + PG8_SB(b, h) + boff + n * 2048 + k * 1024); } while (0)
; #define PG8_MMA(ai, bj, At, Bt) do { __builtin_amdgcn_s_setprio(1); _Pragma("unroll") for (int m = 0; m < 4; ++m) _Pragma("unroll") for (int n = 0; n < 2; ++n) _Pragma("unroll") for (int k = 0; k < 2; ++k) \
;         acc[ai][bj][m][n] = __builtin_amdgcn_mfma_f32_16x16x32_bf16(Bt[n][k], At[m][k], acc[ai][bj][m][n], 0, 0, 0); __builtin_amdgcn_s_setprio(0); } while (0)
; #define PG8_WAIT_V(n) asm volatile("s_waitcnt vmcnt(" #n ")" ::: "memory")
; #define PG8_WAIT_L(n) asm volatile("s_waitcnt lgkmcnt(" #n ")" ::: "memory")
; #define PG8_BAR __builtin_amdgcn_s_barrier()
; template <class Epi, class Sched, bool ALIGN_EPI = false, bool SP2 = false>
; __device__ __forceinline__ void gemm_phase(PG8_LAS unsigned char* lds, const Gemm g, const Sched& S, const Epi& E) {
;     ...
;             const char* a1 = cA + (size_t)(t + 1) * kstA;
;             const char* a2 = last ? nA : cA + (size_t)(t + 2) * kstA; const char* b2 = last ? nB : cB + (size_t)(t + 2) * kstep;
;             const char* a3 = a2 + kstA; const char* b3 = b2 + kstep;
;             if (last && has_next) S.a_ready(nxt);
;             if constexpr (SP2) {
;             PG8_LDB(B0, 0, 0); PG8_LDB(B1, 0, 1); PG8_SCHED; PG8_LDA(At, 0, 0); PG8_STAGE(PG8_SA(1, 1), a1 + hstepA, voffA);
;             PG8_WAIT_V(8); PG8_WAIT_L(0); PG8_BAR; PG8_MMA(0, 0, At, B0); PG8_MMA(0, 1, At, B1); PG8_BAR; PG8_SCHED;
;             PG8_LDA(At, 0, 1); PG8_STAGE(PG8_SB(0, 0), b2, voffB); PG8_STAGE(PG8_SB(0, 1), b2 + hstepB, voffB); PG8_STAGE(PG8_SA(0, 0), a2, voffA);
;             PG8_WAIT_V(8); PG8_WAIT_L(0); PG8_BAR; PG8_MMA(1, 0, At, B0); PG8_MMA(1, 1, At, B1); PG8_BAR; PG8_SCHED;
.LBB0_300:
	ds_read_b128 v[156:159], v152
	ds_read_b128 v[160:163], v152 offset:1024
	ds_read_b128 v[164:167], v152 offset:2048
	ds_read_b128 v[168:171], v152 offset:3072
	ds_read_b128 v[172:175], v153
	ds_read_b128 v[176:179], v153 offset:1024
	ds_read_b128 v[180:183], v153 offset:2048
	ds_read_b128 v[186:189], v153 offset:3072
	s_add_u32 s56, s50, 0xfff80080
	s_addc_u32 s57, s51, -1
	s_cmp_eq_u32 s61, 28
	s_cselect_b32 s59, s4, s57
	s_cselect_b32 s58, s5, s56
	s_cselect_b32 s57, s12, s43
	s_cselect_b32 s56, s13, s41
	v_lshl_add_u64 v[222:223], s[50:51], 0, v[142:143]
	s_add_i32 m0, s6, 0xc000
	ds_read_b128 v[190:193], v154
	ds_read_b128 v[194:197], v154 offset:1024
	ds_read_b128 v[198:201], v154 offset:2048
	ds_read_b128 v[202:205], v154 offset:3072
	ds_read_b128 v[206:209], v154 offset:4096
	ds_read_b128 v[210:213], v154 offset:5120
	ds_read_b128 v[214:217], v154 offset:6144
	ds_read_b128 v[218:221], v154 offset:7168
	global_load_lds_dwordx4 v[222:223], off
	v_lshl_add_u64 v[222:223], s[50:51], 0, v[144:145]
	s_add_i32 m0, s6, 0xe000
	s_nop 0
	global_load_lds_dwordx4 v[222:223], off
	s_waitcnt vmcnt(8)
	s_waitcnt lgkmcnt(0)
	s_setprio 1
	s_barrier
	v_mfma_f32_16x16x32_bf16 v[124:127], v[156:159], v[190:193], v[124:127]
	v_mfma_f32_16x16x32_bf16 v[120:123], v[164:167], v[190:193], v[120:123]
	v_mfma_f32_16x16x32_bf16 v[108:111], v[156:159], v[198:201], v[108:111]
	v_mfma_f32_16x16x32_bf16 v[104:107], v[164:167], v[198:201], v[104:107]
	v_mfma_f32_16x16x32_bf16 v[92:95], v[156:159], v[206:209], v[92:95]
	v_mfma_f32_16x16x32_bf16 v[88:91], v[164:167], v[206:209], v[88:91]
	v_mfma_f32_16x16x32_bf16 v[76:79], v[156:159], v[214:217], v[76:79]
	v_mfma_f32_16x16x32_bf16 v[72:75], v[164:167], v[214:217], v[72:75]
	v_mfma_f32_16x16x32_bf16 v[124:127], v[160:163], v[194:197], v[124:127]
	v_mfma_f32_16x16x32_bf16 v[120:123], v[168:171], v[194:197], v[120:123]
	v_mfma_f32_16x16x32_bf16 v[108:111], v[160:163], v[202:205], v[108:111]
	v_mfma_f32_16x16x32_bf16 v[104:107], v[168:171], v[202:205], v[104:107]
	v_mfma_f32_16x16x32_bf16 v[92:95], v[160:163], v[210:213], v[92:95]
	v_mfma_f32_16x16x32_bf16 v[88:91], v[168:171], v[210:213], v[88:91]
	v_mfma_f32_16x16x32_bf16 v[76:79], v[160:163], v[218:221], v[76:79]
	v_mfma_f32_16x16x32_bf16 v[72:75], v[168:171], v[218:221], v[72:75]
	v_mfma_f32_16x16x32_bf16 v[116:119], v[172:175], v[190:193], v[116:119]
	v_mfma_f32_16x16x32_bf16 v[112:115], v[180:183], v[190:193], v[112:115]
	v_mfma_f32_16x16x32_bf16 v[100:103], v[172:175], v[198:201], v[100:103]
	v_mfma_f32_16x16x32_bf16 v[96:99], v[180:183], v[198:201], v[96:99]
	v_mfma_f32_16x16x32_bf16 v[84:87], v[172:175], v[206:209], v[84:87]
	v_mfma_f32_16x16x32_bf16 v[80:83], v[180:183], v[206:209], v[80:83]
	v_mfma_f32_16x16x32_bf16 v[68:71], v[172:175], v[214:217], v[68:71]
	v_mfma_f32_16x16x32_bf16 v[64:67], v[180:183], v[214:217], v[64:67]
	v_mfma_f32_16x16x32_bf16 v[116:119], v[176:179], v[194:197], v[116:119]
	v_mfma_f32_16x16x32_bf16 v[112:115], v[186:189], v[194:197], v[112:115]
	v_mfma_f32_16x16x32_bf16 v[100:103], v[176:179], v[202:205], v[100:103]
	v_mfma_f32_16x16x32_bf16 v[96:99], v[186:189], v[202:205], v[96:99]
	v_mfma_f32_16x16x32_bf16 v[84:87], v[176:179], v[210:213], v[84:87]
	v_mfma_f32_16x16x32_bf16 v[80:83], v[186:189], v[210:213], v[80:83]
	v_mfma_f32_16x16x32_bf16 v[68:71], v[176:179], v[218:221], v[68:71]
	v_mfma_f32_16x16x32_bf16 v[64:67], v[186:189], v[218:221], v[64:67]
	s_barrier
	s_setprio 0
	s_add_i32 s62, s53, s3
	v_lshl_add_u64 v[222:223], s[56:57], 0, v[130:131]
	s_mov_b32 m0, s62
	ds_read_b128 v[190:193], v154 offset:16384
	ds_read_b128 v[194:197], v154 offset:17408
	ds_read_b128 v[198:201], v154 offset:18432
	ds_read_b128 v[202:205], v154 offset:19456
	ds_read_b128 v[206:209], v154 offset:20480
	ds_read_b128 v[210:213], v154 offset:21504
	ds_read_b128 v[214:217], v154 offset:22528
	ds_read_b128 v[218:221], v154 offset:23552
	global_load_lds_dwordx4 v[222:223], off
	s_add_i32 m0, s62, 0x2000
	s_add_u32 s62, s56, 0x80000
	v_lshl_add_u64 v[224:225], s[56:57], 0, v[134:135]
	s_addc_u32 s63, s57, 0
	s_add_i32 s64, s55, s3
	global_load_lds_dwordx4 v[224:225], off
	v_lshl_add_u64 v[226:227], s[62:63], 0, v[130:131]
	s_mov_b32 m0, s64
	v_lshl_add_u64 v[228:229], s[58:59], 0, v[132:133]
	global_load_lds_dwordx4 v[226:227], off
	v_lshl_add_u64 v[226:227], s[62:63], 0, v[134:135]
	s_add_i32 m0, s64, 0x2000
	s_nop 0
	global_load_lds_dwordx4 v[226:227], off
	v_lshl_add_u64 v[226:227], s[58:59], 0, v[128:129]
	s_mov_b32 m0, s6
	s_nop 0
	global_load_lds_dwordx4 v[226:227], off
	s_mov_b32 m0, s7
	s_nop 0
	global_load_lds_dwordx4 v[228:229], off
	s_waitcnt vmcnt(8)
	s_waitcnt lgkmcnt(0)
	s_setprio 1
	s_barrier
; #define PG8_STAGE(bufoff, gbase, voff) do { _Pragma("unroll") for (int _i = 0; _i < 2; ++_i) \
;         __builtin_amdgcn_global_load_lds((const unsigned*)((const char*)(gbase) + (voff)[_i]), (PG8_LAS unsigned*)(lds + (bufoff) + ldsw + _i * 8192), 16, 0, 0); } while (0)
; #define PG8_LDA(dst, b, h) do { _Pragma("unroll") for (int m = 0; m < 4; ++m) _Pragma("unroll") for (int k = 0; k < 2; ++k) dst[m][k] = *(const PG8_LAS bf16x8*)(lds + PG8_SA(b, h) + aoff + m * 2048 + k * 1024); } while (0)
; #define PG8_LDB(dst, b, h) do { _Pragma("unroll") for (int n = 0; n < 2; ++n) _Pragma("unroll") for (int k = 0; k < 2; ++k) dst[n][k] = *(const PG8_LAS bf16x8*)(lds + PG8_SB(b, h) + boff + n * 2048 + k * 1024); } while (0)
; #define PG8_MMA(ai, bj, At, Bt) do { __builtin_amdgcn_s_setprio(1); _Pragma("unroll") for (int m = 0; m < 4; ++m) _Pragma("unroll") for (int n = 0; n < 2; ++n) _Pragma("unroll") for (int k = 0; k < 2; ++k) \
;         acc[ai][bj][m][n] = __builtin_amdgcn_mfma_f32_16x16x32_bf16(Bt[n][k], At[m][k], acc[ai][bj][m][n], 0, 0, 0); __builtin_amdgcn_s_setprio(0); } while (0)
; #define PG8_WAIT_V(n) asm volatile("s_waitcnt vmcnt(" #n ")" ::: "memory")
; #define PG8_WAIT_L(n) asm volatile("s_waitcnt lgkmcnt(" #n ")" ::: "memory")
; #define PG8_BAR __builtin_amdgcn_s_barrier()
; #define PG8_SCHED __builtin_amdgcn_sched_barrier(0)
; template <class Epi, class Sched, bool ALIGN_EPI = false, bool SP2 = false>
; __device__ __forceinline__ void gemm_phase(PG8_LAS unsigned char* lds, const Gemm g, const Sched& S, const Epi& E) {
;     ...
;             PG8_WAIT_V(8); PG8_WAIT_L(0); PG8_BAR; PG8_MMA(1, 0, At, B0); PG8_MMA(1, 1, At, B1); PG8_BAR; PG8_SCHED;
;             PG8_LDB(B0, 1, 0); PG8_LDB(B1, 1, 1); PG8_SCHED; PG8_LDA(At, 1, 0); PG8_STAGE(PG8_SA(0, 1), a2 + hstepA, voffA);
;             PG8_WAIT_V(8); PG8_WAIT_L(0); PG8_BAR; PG8_MMA(0, 0, At, B0); PG8_MMA(0, 1, At, B1); PG8_BAR; PG8_SCHED;
	v_mfma_f32_16x16x32_bf16 v[60:63], v[156:159], v[190:193], v[60:63]
	v_mfma_f32_16x16x32_bf16 v[56:59], v[164:167], v[190:193], v[56:59]
	v_mfma_f32_16x16x32_bf16 v[44:47], v[156:159], v[198:201], v[44:47]
	v_mfma_f32_16x16x32_bf16 v[40:43], v[164:167], v[198:201], v[40:43]
	v_mfma_f32_16x16x32_bf16 v[28:31], v[156:159], v[206:209], v[28:31]
	v_mfma_f32_16x16x32_bf16 v[24:27], v[164:167], v[206:209], v[24:27]
	v_mfma_f32_16x16x32_bf16 v[12:15], v[156:159], v[214:217], v[12:15]
	v_mfma_f32_16x16x32_bf16 v[8:11], v[164:167], v[214:217], v[8:11]
	v_mfma_f32_16x16x32_bf16 v[60:63], v[160:163], v[194:197], v[60:63]
	v_mfma_f32_16x16x32_bf16 v[56:59], v[168:171], v[194:197], v[56:59]
	v_mfma_f32_16x16x32_bf16 v[44:47], v[160:163], v[202:205], v[44:47]
	v_mfma_f32_16x16x32_bf16 v[40:43], v[168:171], v[202:205], v[40:43]
	v_mfma_f32_16x16x32_bf16 v[28:31], v[160:163], v[210:213], v[28:31]
	v_mfma_f32_16x16x32_bf16 v[24:27], v[168:171], v[210:213], v[24:27]
	v_mfma_f32_16x16x32_bf16 v[12:15], v[160:163], v[218:221], v[12:15]
	v_mfma_f32_16x16x32_bf16 v[8:11], v[168:171], v[218:221], v[8:11]
	v_mfma_f32_16x16x32_bf16 v[52:55], v[172:175], v[190:193], v[52:55]
	v_mfma_f32_16x16x32_bf16 v[48:51], v[180:183], v[190:193], v[48:51]
	v_mfma_f32_16x16x32_bf16 v[36:39], v[172:175], v[198:201], v[36:39]
	v_mfma_f32_16x16x32_bf16 v[32:35], v[180:183], v[198:201], v[32:35]
	v_mfma_f32_16x16x32_bf16 v[20:23], v[172:175], v[206:209], v[20:23]
	v_mfma_f32_16x16x32_bf16 v[16:19], v[180:183], v[206:209], v[16:19]
	v_mfma_f32_16x16x32_bf16 v[4:7], v[172:175], v[214:217], v[4:7]
	v_mfma_f32_16x16x32_bf16 v[0:3], v[180:183], v[214:217], v[0:3]
	v_mfma_f32_16x16x32_bf16 v[52:55], v[176:179], v[194:197], v[52:55]
	v_mfma_f32_16x16x32_bf16 v[48:51], v[186:189], v[194:197], v[48:51]
	v_mfma_f32_16x16x32_bf16 v[36:39], v[176:179], v[202:205], v[36:39]
	v_mfma_f32_16x16x32_bf16 v[32:35], v[186:189], v[202:205], v[32:35]
	v_mfma_f32_16x16x32_bf16 v[20:23], v[176:179], v[210:213], v[20:23]
	v_mfma_f32_16x16x32_bf16 v[16:19], v[186:189], v[210:213], v[16:19]
	v_mfma_f32_16x16x32_bf16 v[4:7], v[176:179], v[218:221], v[4:7]
	v_mfma_f32_16x16x32_bf16 v[0:3], v[186:189], v[218:221], v[0:3]
	s_barrier
	s_setprio 0
	s_add_i32 s62, 0, 0x18000
	v_add_u32_e32 v155, s62, v150
	s_add_i32 s63, 0, 0x1c000
	ds_read_b128 v[156:159], v155
	ds_read_b128 v[160:163], v155 offset:1024
	ds_read_b128 v[164:167], v155 offset:2048
	ds_read_b128 v[168:171], v155 offset:3072
	v_add_u32_e32 v155, s63, v150
	ds_read_b128 v[172:175], v155
	ds_read_b128 v[176:179], v155 offset:1024
	ds_read_b128 v[180:183], v155 offset:2048
	ds_read_b128 v[186:189], v155 offset:3072
	s_add_u32 s58, s58, 0x80000
	s_addc_u32 s59, s59, 0
	s_mov_b32 m0, s8
	v_lshl_add_u64 v[230:231], s[58:59], 0, v[128:129]
	ds_read_b128 v[190:193], v154 offset:32768
	ds_read_b128 v[194:197], v154 offset:33792
	ds_read_b128 v[198:201], v154 offset:34816
	ds_read_b128 v[202:205], v154 offset:35840
	ds_read_b128 v[206:209], v154 offset:36864
	ds_read_b128 v[210:213], v154 offset:37888
	ds_read_b128 v[214:217], v154 offset:38912
	ds_read_b128 v[218:221], v154 offset:39936
	global_load_lds_dwordx4 v[230:231], off
	v_lshl_add_u64 v[230:231], s[58:59], 0, v[132:133]
	s_mov_b32 m0, s9
	s_nop 0
	global_load_lds_dwordx4 v[230:231], off
	s_waitcnt vmcnt(8)
	s_waitcnt lgkmcnt(0)
	s_setprio 1
	s_barrier
	v_mfma_f32_16x16x32_bf16 v[124:127], v[156:159], v[190:193], v[124:127]
	v_mfma_f32_16x16x32_bf16 v[120:123], v[164:167], v[190:193], v[120:123]
	v_mfma_f32_16x16x32_bf16 v[108:111], v[156:159], v[198:201], v[108:111]
	v_mfma_f32_16x16x32_bf16 v[104:107], v[164:167], v[198:201], v[104:107]
	v_mfma_f32_16x16x32_bf16 v[92:95], v[156:159], v[206:209], v[92:95]
	v_mfma_f32_16x16x32_bf16 v[88:91], v[164:167], v[206:209], v[88:91]
	v_mfma_f32_16x16x32_bf16 v[76:79], v[156:159], v[214:217], v[76:79]
	v_mfma_f32_16x16x32_bf16 v[72:75], v[164:167], v[214:217], v[72:75]
	v_mfma_f32_16x16x32_bf16 v[124:127], v[160:163], v[194:197], v[124:127]
	v_mfma_f32_16x16x32_bf16 v[120:123], v[168:171], v[194:197], v[120:123]
	v_mfma_f32_16x16x32_bf16 v[108:111], v[160:163], v[202:205], v[108:111]
	v_mfma_f32_16x16x32_bf16 v[104:107], v[168:171], v[202:205], v[104:107]
	v_mfma_f32_16x16x32_bf16 v[92:95], v[160:163], v[210:213], v[92:95]
	v_mfma_f32_16x16x32_bf16 v[88:91], v[168:171], v[210:213], v[88:91]
	v_mfma_f32_16x16x32_bf16 v[76:79], v[160:163], v[218:221], v[76:79]
	v_mfma_f32_16x16x32_bf16 v[72:75], v[168:171], v[218:221], v[72:75]
	v_mfma_f32_16x16x32_bf16 v[116:119], v[172:175], v[190:193], v[116:119]
	v_mfma_f32_16x16x32_bf16 v[112:115], v[180:183], v[190:193], v[112:115]
	v_mfma_f32_16x16x32_bf16 v[100:103], v[172:175], v[198:201], v[100:103]
	v_mfma_f32_16x16x32_bf16 v[96:99], v[180:183], v[198:201], v[96:99]
	v_mfma_f32_16x16x32_bf16 v[84:87], v[172:175], v[206:209], v[84:87]
	v_mfma_f32_16x16x32_bf16 v[80:83], v[180:183], v[206:209], v[80:83]
	v_mfma_f32_16x16x32_bf16 v[68:71], v[172:175], v[214:217], v[68:71]
	v_mfma_f32_16x16x32_bf16 v[64:67], v[180:183], v[214:217], v[64:67]
	v_mfma_f32_16x16x32_bf16 v[116:119], v[176:179], v[194:197], v[116:119]
	v_mfma_f32_16x16x32_bf16 v[112:115], v[186:189], v[194:197], v[112:115]
	v_mfma_f32_16x16x32_bf16 v[100:103], v[176:179], v[202:205], v[100:103]
	v_mfma_f32_16x16x32_bf16 v[96:99], v[186:189], v[202:205], v[96:99]
	v_mfma_f32_16x16x32_bf16 v[84:87], v[176:179], v[210:213], v[84:87]
	v_mfma_f32_16x16x32_bf16 v[80:83], v[186:189], v[210:213], v[80:83]
	v_mfma_f32_16x16x32_bf16 v[68:71], v[176:179], v[218:221], v[68:71]
	v_mfma_f32_16x16x32_bf16 v[64:67], v[186:189], v[218:221], v[64:67]
	s_barrier
; #define PG8_STAGE(bufoff, gbase, voff) do { _Pragma("unroll") for (int _i = 0; _i < 2; ++_i) \
;         __builtin_amdgcn_global_load_lds((const unsigned*)((const char*)(gbase) + (voff)[_i]), (PG8_LAS unsigned*)(lds + (bufoff) + ldsw + _i * 8192), 16, 0, 0); } while (0)
; #define PG8_LDA(dst, b, h) do { _Pragma("unroll") for (int m = 0; m < 4; ++m) _Pragma("unroll") for (int k = 0; k < 2; ++k) dst[m][k] = *(const PG8_LAS bf16x8*)(lds + PG8_SA(b, h) + aoff + m * 2048 + k * 1024); } while (0)
; #define PG8_MMA(ai, bj, At, Bt) do { __builtin_amdgcn_s_setprio(1); _Pragma("unroll") for (int m = 0; m < 4; ++m) _Pragma("unroll") for (int n = 0; n < 2; ++n) _Pragma("unroll") for (int k = 0; k < 2; ++k) \
;         acc[ai][bj][m][n] = __builtin_amdgcn_mfma_f32_16x16x32_bf16(Bt[n][k], At[m][k], acc[ai][bj][m][n], 0, 0, 0); __builtin_amdgcn_s_setprio(0); } while (0)
; #define PG8_WAIT_V(n) asm volatile("s_waitcnt vmcnt(" #n ")" ::: "memory")
; #define PG8_WAIT_L(n) asm volatile("s_waitcnt lgkmcnt(" #n ")" ::: "memory")
; #define PG8_BAR __builtin_amdgcn_s_barrier()
; #define PG8_SCHED __builtin_amdgcn_sched_barrier(0)
; template <class Epi, class Sched, bool ALIGN_EPI = false, bool SP2 = false>
; __device__ __forceinline__ void gemm_phase(PG8_LAS unsigned char* lds, const Gemm g, const Sched& S, const Epi& E) {
;     ...
;             PG8_LDA(At, 1, 1); PG8_STAGE(PG8_SB(1, 0), b3, voffB); PG8_STAGE(PG8_SB(1, 1), b3 + hstepB, voffB); PG8_STAGE(PG8_SA(1, 0), a3, voffA);
;             PG8_WAIT_V(8); PG8_WAIT_L(0); PG8_BAR; PG8_MMA(1, 0, At, B0); PG8_MMA(1, 1, At, B1); PG8_BAR; PG8_SCHED;
;     ...
;         if constexpr (ALIGN_EPI) { if (wr == 0) PG8_BAR; }
	s_setprio 0
	s_add_i32 s58, s62, s3
	v_lshl_add_u64 v[222:223], v[222:223], 0, s[36:37]
	s_mov_b32 m0, s58
	ds_read_b128 v[190:193], v154 offset:49152
	ds_read_b128 v[194:197], v154 offset:50176
	ds_read_b128 v[198:201], v154 offset:51200
	ds_read_b128 v[202:205], v154 offset:52224
	ds_read_b128 v[206:209], v154 offset:53248
	ds_read_b128 v[210:213], v154 offset:54272
	ds_read_b128 v[214:217], v154 offset:55296
	ds_read_b128 v[218:221], v154 offset:56320
	global_load_lds_dwordx4 v[222:223], off
	s_add_i32 m0, s58, 0x2000
	s_add_u32 s56, s56, 0x80080
	v_lshl_add_u64 v[222:223], v[224:225], 0, s[36:37]
	s_addc_u32 s57, s57, 0
	s_add_i32 s58, s63, s3
	global_load_lds_dwordx4 v[222:223], off
	v_lshl_add_u64 v[222:223], s[56:57], 0, v[130:131]
	s_mov_b32 m0, s58
	s_nop 0
	global_load_lds_dwordx4 v[222:223], off
	v_lshl_add_u64 v[222:223], s[56:57], 0, v[134:135]
	s_add_i32 m0, s58, 0x2000
	s_nop 0
	global_load_lds_dwordx4 v[222:223], off
	v_lshl_add_u64 v[222:223], v[226:227], 0, s[36:37]
	s_mov_b32 m0, s44
	s_nop 0
	global_load_lds_dwordx4 v[222:223], off
	v_lshl_add_u64 v[222:223], v[228:229], 0, s[36:37]
	s_mov_b32 m0, s45
	s_nop 0
	global_load_lds_dwordx4 v[222:223], off
	s_waitcnt vmcnt(8)
	s_waitcnt lgkmcnt(0)
	s_setprio 1
	s_barrier
	v_mfma_f32_16x16x32_bf16 v[60:63], v[156:159], v[190:193], v[60:63]
	v_mfma_f32_16x16x32_bf16 v[56:59], v[164:167], v[190:193], v[56:59]
	v_mfma_f32_16x16x32_bf16 v[44:47], v[156:159], v[198:201], v[44:47]
	v_mfma_f32_16x16x32_bf16 v[40:43], v[164:167], v[198:201], v[40:43]
	v_mfma_f32_16x16x32_bf16 v[28:31], v[156:159], v[206:209], v[28:31]
	v_mfma_f32_16x16x32_bf16 v[24:27], v[164:167], v[206:209], v[24:27]
	v_mfma_f32_16x16x32_bf16 v[12:15], v[156:159], v[214:217], v[12:15]
	v_mfma_f32_16x16x32_bf16 v[8:11], v[164:167], v[214:217], v[8:11]
	v_mfma_f32_16x16x32_bf16 v[60:63], v[160:163], v[194:197], v[60:63]
	v_mfma_f32_16x16x32_bf16 v[56:59], v[168:171], v[194:197], v[56:59]
	v_mfma_f32_16x16x32_bf16 v[44:47], v[160:163], v[202:205], v[44:47]
	v_mfma_f32_16x16x32_bf16 v[40:43], v[168:171], v[202:205], v[40:43]
	v_mfma_f32_16x16x32_bf16 v[28:31], v[160:163], v[210:213], v[28:31]
	v_mfma_f32_16x16x32_bf16 v[24:27], v[168:171], v[210:213], v[24:27]
	v_mfma_f32_16x16x32_bf16 v[12:15], v[160:163], v[218:221], v[12:15]
	v_mfma_f32_16x16x32_bf16 v[8:11], v[168:171], v[218:221], v[8:11]
	v_mfma_f32_16x16x32_bf16 v[52:55], v[172:175], v[190:193], v[52:55]
	v_mfma_f32_16x16x32_bf16 v[48:51], v[180:183], v[190:193], v[48:51]
	v_mfma_f32_16x16x32_bf16 v[36:39], v[172:175], v[198:201], v[36:39]
	v_mfma_f32_16x16x32_bf16 v[32:35], v[180:183], v[198:201], v[32:35]
	v_mfma_f32_16x16x32_bf16 v[20:23], v[172:175], v[206:209], v[20:23]
	v_mfma_f32_16x16x32_bf16 v[16:19], v[180:183], v[206:209], v[16:19]
	v_mfma_f32_16x16x32_bf16 v[4:7], v[172:175], v[214:217], v[4:7]
	v_mfma_f32_16x16x32_bf16 v[0:3], v[180:183], v[214:217], v[0:3]
	v_mfma_f32_16x16x32_bf16 v[52:55], v[176:179], v[194:197], v[52:55]
	v_mfma_f32_16x16x32_bf16 v[48:51], v[186:189], v[194:197], v[48:51]
	v_mfma_f32_16x16x32_bf16 v[36:39], v[176:179], v[202:205], v[36:39]
	v_mfma_f32_16x16x32_bf16 v[32:35], v[186:189], v[202:205], v[32:35]
	v_mfma_f32_16x16x32_bf16 v[20:23], v[176:179], v[210:213], v[20:23]
	v_mfma_f32_16x16x32_bf16 v[16:19], v[186:189], v[210:213], v[16:19]
	v_mfma_f32_16x16x32_bf16 v[4:7], v[176:179], v[218:221], v[4:7]
	v_mfma_f32_16x16x32_bf16 v[0:3], v[186:189], v[218:221], v[0:3]
	s_barrier
	s_setprio 0
	s_add_i32 s61, s61, 2
	s_add_u32 s50, s50, 0x100
	s_addc_u32 s51, s51, 0
	s_add_u32 s41, s41, 0x100
	s_addc_u32 s43, s43, 0
	s_cmp_gt_u32 s61, 29
	s_cbranch_scc0 .LBB0_300
	s_and_b64 vcc, exec, s[38:39]
	s_cbranch_vccz .LBB0_303
	s_barrier

; #define PG8_STAGE(bufoff, gbase, voff) do { _Pragma("unroll") for (int _i = 0; _i < 2; ++_i) \
;         __builtin_amdgcn_global_load_lds((const unsigned*)((const char*)(gbase) + (voff)[_i]), (PG8_LAS unsigned*)(lds + (bufoff) + ldsw + _i * 8192), 16, 0, 0); } while (0)
; #define PG8_LDA(dst, b, h) do { _Pragma("unroll") for (int m = 0; m < 4; ++m) _Pragma("unroll") for (int k = 0; k < 2; ++k) dst[m][k] = *(const PG8_LAS bf16x8*)(lds + PG8_SA(b, h) + aoff + m * 2048 + k * 1024); } while (0)
; #define PG8_LDB(dst, b, h) do { _Pragma("unroll") for (int n = 0; n < 2; ++n) _Pragma("unroll") for (int k = 0; k < 2; ++k) dst[n][k] = *(const PG8_LAS bf16x8*)(lds + PG8_SB(b, h) + boff + n * 2048 + k * 1024); } while (0)
; #define PG8_MMA(ai, bj, At, Bt) do { __builtin_amdgcn_s_setprio(1); _Pragma("unroll") for (int m = 0; m < 4; ++m) _Pragma("unroll") for (int n = 0; n < 2; ++n) _Pragma("unroll") for (int k = 0; k < 2; ++k) \
;         acc[ai][bj][m][n] = __builtin_amdgcn_mfma_f32_16x16x32_bf16(Bt[n][k], At[m][k], acc[ai][bj][m][n], 0, 0, 0); __builtin_amdgcn_s_setprio(0); } while (0)
; #define PG8_WAIT_V(n) asm volatile("s_waitcnt vmcnt(" #n ")" ::: "memory")
; #define PG8_BAR __builtin_amdgcn_s_barrier()
; template <class Epi, class Sched, bool ALIGN_EPI = false, bool SP2 = false>
; __device__ __forceinline__ void gemm_phase(PG8_LAS unsigned char* lds, const Gemm g, const Sched& S, const Epi& E) {
;     ...
;         for (int t = 0; t < nt; t += 2) {
;             const bool last = (t == nt - 2);
;             const char* a1 = cA + (size_t)(t + 1) * kstA;
;             const char* a2 = last ? nA : cA + (size_t)(t + 2) * kstA; const char* b2 = last ? nB : cB + (size_t)(t + 2) * kstep;
;             const char* a3 = a2 + kstA; const char* b3 = b2 + kstep;
;             if (last && has_next) S.a_ready(nxt);
;             if constexpr (SP2) {
;             PG8_LDB(B0, 0, 0); PG8_LDB(B1, 0, 1); PG8_SCHED; PG8_LDA(At, 0, 0); PG8_STAGE(PG8_SA(1, 1), a1 + hstepA, voffA);
;             PG8_WAIT_V(8); PG8_WAIT_L(0); PG8_BAR; PG8_MMA(0, 0, At, B0); PG8_MMA(0, 1, At, B1); PG8_BAR; PG8_SCHED;
;             PG8_LDA(At, 0, 1); PG8_STAGE(PG8_SB(0, 0), b2, voffB); PG8_STAGE(PG8_SB(0, 1), b2 + hstepB, voffB); PG8_STAGE(PG8_SA(0, 0), a2, voffA);
;             PG8_WAIT_V(8); PG8_WAIT_L(0); PG8_BAR; PG8_MMA(1, 0, At, B0); PG8_MMA(1, 1, At, B1); PG8_BAR; PG8_SCHED;
.LBB0_397:
	s_or_b32 s42, s74, 1
	s_add_i32 s74, s74, 2
	s_mov_b32 s75, s43
	s_lshl_b64 s[4:5], s[42:43], 15
	s_lshl_b64 s[12:13], s[74:75], 15
	s_add_u32 s42, s38, s12
	v_add_u32_e32 v170, s10, v177
	v_add_u32_e32 v174, s11, v177
	s_addc_u32 s46, s39, s13
	ds_read_b128 v[158:161], v170
	ds_read_b128 v[162:165], v170 offset:1024
	ds_read_b128 v[166:169], v170 offset:2048
	ds_read_b128 v[170:173], v170 offset:3072
	ds_read_b128 v[180:183], v174
	ds_read_b128 v[186:189], v174 offset:1024
	ds_read_b128 v[190:193], v174 offset:2048
	ds_read_b128 v[194:197], v174 offset:3072
	s_and_b64 s[12:13], s[50:51], exec
	s_cselect_b32 s59, s46, s61
	s_cselect_b32 s58, s42, s60
	s_lshl_b64 s[12:13], s[74:75], 7
	s_add_u32 s42, s40, s12
	s_addc_u32 s46, s41, s13
	s_and_b64 s[12:13], s[50:51], exec
	s_cselect_b32 s53, s46, s63
	s_cselect_b32 s52, s42, s62
	s_add_u32 s50, s58, 0x8000
	s_addc_u32 s51, s59, 0
	s_add_u32 s4, s35, s4
	s_addc_u32 s5, s65, s5
	v_lshl_add_u64 v[174:175], s[4:5], 0, v[128:129]
	s_add_i32 m0, s66, 0xc000
	ds_read_b128 v[198:201], v179
	ds_read_b128 v[202:205], v179 offset:1024
	ds_read_b128 v[206:209], v179 offset:2048
	ds_read_b128 v[210:213], v179 offset:3072
	ds_read_b128 v[214:217], v179 offset:4096
	ds_read_b128 v[218:221], v179 offset:5120
	ds_read_b128 v[222:225], v179 offset:6144
	ds_read_b128 v[226:229], v179 offset:7168
	global_load_lds_dwordx4 v[174:175], off
	v_lshl_add_u64 v[174:175], s[4:5], 0, v[132:133]
	s_add_i32 m0, s66, 0xe000
	s_nop 0
	global_load_lds_dwordx4 v[174:175], off
	s_waitcnt vmcnt(8)
	s_waitcnt lgkmcnt(0)
	s_setprio 1
	s_barrier
	v_mfma_f32_16x16x32_bf16 v[124:127], v[158:161], v[198:201], v[124:127]
	v_mfma_f32_16x16x32_bf16 v[120:123], v[166:169], v[198:201], v[120:123]
	v_mfma_f32_16x16x32_bf16 v[116:119], v[158:161], v[206:209], v[116:119]
	v_mfma_f32_16x16x32_bf16 v[112:115], v[166:169], v[206:209], v[112:115]
	v_mfma_f32_16x16x32_bf16 v[108:111], v[158:161], v[214:217], v[108:111]
	v_mfma_f32_16x16x32_bf16 v[104:107], v[166:169], v[214:217], v[104:107]
	v_mfma_f32_16x16x32_bf16 v[100:103], v[158:161], v[222:225], v[100:103]
	v_mfma_f32_16x16x32_bf16 v[96:99], v[166:169], v[222:225], v[96:99]
	v_mfma_f32_16x16x32_bf16 v[124:127], v[162:165], v[202:205], v[124:127]
	v_mfma_f32_16x16x32_bf16 v[120:123], v[170:173], v[202:205], v[120:123]
	v_mfma_f32_16x16x32_bf16 v[116:119], v[162:165], v[210:213], v[116:119]
	v_mfma_f32_16x16x32_bf16 v[112:115], v[170:173], v[210:213], v[112:115]
	v_mfma_f32_16x16x32_bf16 v[108:111], v[162:165], v[218:221], v[108:111]
	v_mfma_f32_16x16x32_bf16 v[104:107], v[170:173], v[218:221], v[104:107]
	v_mfma_f32_16x16x32_bf16 v[100:103], v[162:165], v[226:229], v[100:103]
	v_mfma_f32_16x16x32_bf16 v[96:99], v[170:173], v[226:229], v[96:99]
	v_mfma_f32_16x16x32_bf16 v[92:95], v[180:183], v[198:201], v[92:95]
	v_mfma_f32_16x16x32_bf16 v[88:91], v[190:193], v[198:201], v[88:91]
	v_mfma_f32_16x16x32_bf16 v[84:87], v[180:183], v[206:209], v[84:87]
	v_mfma_f32_16x16x32_bf16 v[80:83], v[190:193], v[206:209], v[80:83]
	v_mfma_f32_16x16x32_bf16 v[76:79], v[180:183], v[214:217], v[76:79]
	v_mfma_f32_16x16x32_bf16 v[72:75], v[190:193], v[214:217], v[72:75]
	v_mfma_f32_16x16x32_bf16 v[68:71], v[180:183], v[222:225], v[68:71]
	v_mfma_f32_16x16x32_bf16 v[64:67], v[190:193], v[222:225], v[64:67]
	v_mfma_f32_16x16x32_bf16 v[92:95], v[186:189], v[202:205], v[92:95]
	v_mfma_f32_16x16x32_bf16 v[88:91], v[194:197], v[202:205], v[88:91]
	v_mfma_f32_16x16x32_bf16 v[84:87], v[186:189], v[210:213], v[84:87]
	v_mfma_f32_16x16x32_bf16 v[80:83], v[194:197], v[210:213], v[80:83]
	v_mfma_f32_16x16x32_bf16 v[76:79], v[186:189], v[218:221], v[76:79]
	v_mfma_f32_16x16x32_bf16 v[72:75], v[194:197], v[218:221], v[72:75]
	v_mfma_f32_16x16x32_bf16 v[68:71], v[186:189], v[226:229], v[68:71]
	v_mfma_f32_16x16x32_bf16 v[64:67], v[194:197], v[226:229], v[64:67]
	s_barrier
	s_setprio 0
	s_add_i32 s4, s10, s9
	v_lshl_add_u64 v[174:175], s[52:53], 0, v[130:131]
	s_mov_b32 m0, s4
	ds_read_b128 v[198:201], v179 offset:16384
	ds_read_b128 v[202:205], v179 offset:17408
	ds_read_b128 v[206:209], v179 offset:18432
	ds_read_b128 v[210:213], v179 offset:19456
	ds_read_b128 v[214:217], v179 offset:20480
	ds_read_b128 v[218:221], v179 offset:21504
	ds_read_b128 v[222:225], v179 offset:22528
	ds_read_b128 v[226:229], v179 offset:23552
	global_load_lds_dwordx4 v[174:175], off
	s_add_i32 m0, s4, 0x2000
	s_add_u32 s4, s52, 0x160000
	v_lshl_add_u64 v[230:231], s[52:53], 0, v[134:135]
	s_addc_u32 s5, s53, 0
	s_add_i32 s12, s11, s9
	global_load_lds_dwordx4 v[230:231], off
	v_lshl_add_u64 v[232:233], s[4:5], 0, v[130:131]
	s_mov_b32 m0, s12
	s_nop 0
	global_load_lds_dwordx4 v[232:233], off
	v_lshl_add_u64 v[232:233], s[4:5], 0, v[134:135]
	s_add_i32 m0, s12, 0x2000
	s_nop 0
	global_load_lds_dwordx4 v[232:233], off
	v_lshl_add_u64 v[232:233], s[58:59], 0, v[128:129]
	s_mov_b32 m0, s66
	s_nop 0
	global_load_lds_dwordx4 v[232:233], off
	v_lshl_add_u64 v[232:233], s[58:59], 0, v[132:133]
	s_mov_b32 m0, s67
	s_nop 0
	global_load_lds_dwordx4 v[232:233], off
	s_waitcnt vmcnt(8)
	s_waitcnt lgkmcnt(0)
	s_setprio 1
	s_barrier
; #define PG8_STAGE(bufoff, gbase, voff) do { _Pragma("unroll") for (int _i = 0; _i < 2; ++_i) \
;         __builtin_amdgcn_global_load_lds((const unsigned*)((const char*)(gbase) + (voff)[_i]), (PG8_LAS unsigned*)(lds + (bufoff) + ldsw + _i * 8192), 16, 0, 0); } while (0)
; #define PG8_LDA(dst, b, h) do { _Pragma("unroll") for (int m = 0; m < 4; ++m) _Pragma("unroll") for (int k = 0; k < 2; ++k) dst[m][k] = *(const PG8_LAS bf16x8*)(lds + PG8_SA(b, h) + aoff + m * 2048 + k * 1024); } while (0)
; #define PG8_LDB(dst, b, h) do { _Pragma("unroll") for (int n = 0; n < 2; ++n) _Pragma("unroll") for (int k = 0; k < 2; ++k) dst[n][k] = *(const PG8_LAS bf16x8*)(lds + PG8_SB(b, h) + boff + n * 2048 + k * 1024); } while (0)
; #define PG8_MMA(ai, bj, At, Bt) do { __builtin_amdgcn_s_setprio(1); _Pragma("unroll") for (int m = 0; m < 4; ++m) _Pragma("unroll") for (int n = 0; n < 2; ++n) _Pragma("unroll") for (int k = 0; k < 2; ++k) \
;         acc[ai][bj][m][n] = __builtin_amdgcn_mfma_f32_16x16x32_bf16(Bt[n][k], At[m][k], acc[ai][bj][m][n], 0, 0, 0); __builtin_amdgcn_s_setprio(0); } while (0)
; #define PG8_WAIT_V(n) asm volatile("s_waitcnt vmcnt(" #n ")" ::: "memory")
; #define PG8_WAIT_L(n) asm volatile("s_waitcnt lgkmcnt(" #n ")" ::: "memory")
; #define PG8_BAR __builtin_amdgcn_s_barrier()
; #define PG8_SCHED __builtin_amdgcn_sched_barrier(0)
; template <class Epi, class Sched, bool ALIGN_EPI = false, bool SP2 = false>
; __device__ __forceinline__ void gemm_phase(PG8_LAS unsigned char* lds, const Gemm g, const Sched& S, const Epi& E) {
;     ...
;             PG8_WAIT_V(8); PG8_WAIT_L(0); PG8_BAR; PG8_MMA(1, 0, At, B0); PG8_MMA(1, 1, At, B1); PG8_BAR; PG8_SCHED;
;             PG8_LDB(B0, 1, 0); PG8_LDB(B1, 1, 1); PG8_SCHED; PG8_LDA(At, 1, 0); PG8_STAGE(PG8_SA(0, 1), a2 + hstepA, voffA);
;             PG8_WAIT_V(8); PG8_WAIT_L(0); PG8_BAR; PG8_MMA(0, 0, At, B0); PG8_MMA(0, 1, At, B1); PG8_BAR; PG8_SCHED;
	v_mfma_f32_16x16x32_bf16 v[60:63], v[158:161], v[198:201], v[60:63]
	v_mfma_f32_16x16x32_bf16 v[56:59], v[166:169], v[198:201], v[56:59]
	v_mfma_f32_16x16x32_bf16 v[52:55], v[158:161], v[206:209], v[52:55]
	v_mfma_f32_16x16x32_bf16 v[48:51], v[166:169], v[206:209], v[48:51]
	v_mfma_f32_16x16x32_bf16 v[44:47], v[158:161], v[214:217], v[44:47]
	v_mfma_f32_16x16x32_bf16 v[40:43], v[166:169], v[214:217], v[40:43]
	v_mfma_f32_16x16x32_bf16 v[36:39], v[158:161], v[222:225], v[36:39]
	v_mfma_f32_16x16x32_bf16 v[32:35], v[166:169], v[222:225], v[32:35]
	v_mfma_f32_16x16x32_bf16 v[60:63], v[162:165], v[202:205], v[60:63]
	v_mfma_f32_16x16x32_bf16 v[56:59], v[170:173], v[202:205], v[56:59]
	v_mfma_f32_16x16x32_bf16 v[52:55], v[162:165], v[210:213], v[52:55]
	v_mfma_f32_16x16x32_bf16 v[48:51], v[170:173], v[210:213], v[48:51]
	v_mfma_f32_16x16x32_bf16 v[44:47], v[162:165], v[218:221], v[44:47]
	v_mfma_f32_16x16x32_bf16 v[40:43], v[170:173], v[218:221], v[40:43]
	v_mfma_f32_16x16x32_bf16 v[36:39], v[162:165], v[226:229], v[36:39]
	v_mfma_f32_16x16x32_bf16 v[32:35], v[170:173], v[226:229], v[32:35]
	v_mfma_f32_16x16x32_bf16 v[28:31], v[180:183], v[198:201], v[28:31]
	v_mfma_f32_16x16x32_bf16 v[24:27], v[190:193], v[198:201], v[24:27]
	v_mfma_f32_16x16x32_bf16 v[20:23], v[180:183], v[206:209], v[20:23]
	v_mfma_f32_16x16x32_bf16 v[16:19], v[190:193], v[206:209], v[16:19]
	v_mfma_f32_16x16x32_bf16 v[12:15], v[180:183], v[214:217], v[12:15]
	v_mfma_f32_16x16x32_bf16 v[8:11], v[190:193], v[214:217], v[8:11]
	v_mfma_f32_16x16x32_bf16 v[4:7], v[180:183], v[222:225], v[4:7]
	v_mfma_f32_16x16x32_bf16 v[0:3], v[190:193], v[222:225], v[0:3]
	v_mfma_f32_16x16x32_bf16 v[28:31], v[186:189], v[202:205], v[28:31]
	v_mfma_f32_16x16x32_bf16 v[24:27], v[194:197], v[202:205], v[24:27]
	v_mfma_f32_16x16x32_bf16 v[20:23], v[186:189], v[210:213], v[20:23]
	v_mfma_f32_16x16x32_bf16 v[16:19], v[194:197], v[210:213], v[16:19]
	v_mfma_f32_16x16x32_bf16 v[12:15], v[186:189], v[218:221], v[12:15]
	v_mfma_f32_16x16x32_bf16 v[8:11], v[194:197], v[218:221], v[8:11]
	v_mfma_f32_16x16x32_bf16 v[4:7], v[186:189], v[226:229], v[4:7]
	v_mfma_f32_16x16x32_bf16 v[0:3], v[194:197], v[226:229], v[0:3]
	s_barrier
	s_setprio 0
	s_add_i32 s12, 0, 0x18000
	s_add_i32 s13, 0, 0x1c000
	v_add_u32_e32 v170, s12, v177
	v_add_u32_e32 v185, s13, v177
	ds_read_b128 v[158:161], v170
	ds_read_b128 v[162:165], v170 offset:1024
	ds_read_b128 v[166:169], v170 offset:2048
	ds_read_b128 v[170:173], v170 offset:3072
	ds_read_b128 v[180:183], v185
	ds_read_b128 v[186:189], v185 offset:1024
	ds_read_b128 v[190:193], v185 offset:2048
	ds_read_b128 v[194:197], v185 offset:3072
	s_add_u32 s4, s58, 0x4000
	s_addc_u32 s5, s59, 0
	s_mov_b32 m0, s76
	v_lshl_add_u64 v[232:233], s[4:5], 0, v[128:129]
	ds_read_b128 v[198:201], v179 offset:32768
	ds_read_b128 v[202:205], v179 offset:33792
	ds_read_b128 v[206:209], v179 offset:34816
	ds_read_b128 v[210:213], v179 offset:35840
	ds_read_b128 v[214:217], v179 offset:36864
	ds_read_b128 v[218:221], v179 offset:37888
	ds_read_b128 v[222:225], v179 offset:38912
	ds_read_b128 v[226:229], v179 offset:39936
	global_load_lds_dwordx4 v[232:233], off
	v_lshl_add_u64 v[232:233], s[4:5], 0, v[132:133]
	s_mov_b32 m0, s77
	s_nop 0
	global_load_lds_dwordx4 v[232:233], off
	s_waitcnt vmcnt(8)
	s_waitcnt lgkmcnt(0)
	s_setprio 1
	s_barrier
	v_mfma_f32_16x16x32_bf16 v[124:127], v[158:161], v[198:201], v[124:127]
	v_mfma_f32_16x16x32_bf16 v[120:123], v[166:169], v[198:201], v[120:123]
	v_mfma_f32_16x16x32_bf16 v[116:119], v[158:161], v[206:209], v[116:119]
	v_mfma_f32_16x16x32_bf16 v[112:115], v[166:169], v[206:209], v[112:115]
	v_mfma_f32_16x16x32_bf16 v[108:111], v[158:161], v[214:217], v[108:111]
	v_mfma_f32_16x16x32_bf16 v[104:107], v[166:169], v[214:217], v[104:107]
	v_mfma_f32_16x16x32_bf16 v[100:103], v[158:161], v[222:225], v[100:103]
	v_mfma_f32_16x16x32_bf16 v[96:99], v[166:169], v[222:225], v[96:99]
	v_mfma_f32_16x16x32_bf16 v[124:127], v[162:165], v[202:205], v[124:127]
	v_mfma_f32_16x16x32_bf16 v[120:123], v[170:173], v[202:205], v[120:123]
	v_mfma_f32_16x16x32_bf16 v[116:119], v[162:165], v[210:213], v[116:119]
	v_mfma_f32_16x16x32_bf16 v[112:115], v[170:173], v[210:213], v[112:115]
	v_mfma_f32_16x16x32_bf16 v[108:111], v[162:165], v[218:221], v[108:111]
	v_mfma_f32_16x16x32_bf16 v[104:107], v[170:173], v[218:221], v[104:107]
	v_mfma_f32_16x16x32_bf16 v[100:103], v[162:165], v[226:229], v[100:103]
	v_mfma_f32_16x16x32_bf16 v[96:99], v[170:173], v[226:229], v[96:99]
	v_mfma_f32_16x16x32_bf16 v[92:95], v[180:183], v[198:201], v[92:95]
	v_mfma_f32_16x16x32_bf16 v[88:91], v[190:193], v[198:201], v[88:91]
	v_mfma_f32_16x16x32_bf16 v[84:87], v[180:183], v[206:209], v[84:87]
	v_mfma_f32_16x16x32_bf16 v[80:83], v[190:193], v[206:209], v[80:83]
	v_mfma_f32_16x16x32_bf16 v[76:79], v[180:183], v[214:217], v[76:79]
	v_mfma_f32_16x16x32_bf16 v[72:75], v[190:193], v[214:217], v[72:75]
	v_mfma_f32_16x16x32_bf16 v[68:71], v[180:183], v[222:225], v[68:71]
	v_mfma_f32_16x16x32_bf16 v[64:67], v[190:193], v[222:225], v[64:67]
	v_mfma_f32_16x16x32_bf16 v[92:95], v[186:189], v[202:205], v[92:95]
	v_mfma_f32_16x16x32_bf16 v[88:91], v[194:197], v[202:205], v[88:91]
	v_mfma_f32_16x16x32_bf16 v[84:87], v[186:189], v[210:213], v[84:87]
	v_mfma_f32_16x16x32_bf16 v[80:83], v[194:197], v[210:213], v[80:83]
	v_mfma_f32_16x16x32_bf16 v[76:79], v[186:189], v[218:221], v[76:79]
	v_mfma_f32_16x16x32_bf16 v[72:75], v[194:197], v[218:221], v[72:75]
	v_mfma_f32_16x16x32_bf16 v[68:71], v[186:189], v[226:229], v[68:71]
	v_mfma_f32_16x16x32_bf16 v[64:67], v[194:197], v[226:229], v[64:67]
	s_barrier
; #define PG8_STAGE(bufoff, gbase, voff) do { _Pragma("unroll") for (int _i = 0; _i < 2; ++_i) \
;         __builtin_amdgcn_global_load_lds((const unsigned*)((const char*)(gbase) + (voff)[_i]), (PG8_LAS unsigned*)(lds + (bufoff) + ldsw + _i * 8192), 16, 0, 0); } while (0)
; #define PG8_LDA(dst, b, h) do { _Pragma("unroll") for (int m = 0; m < 4; ++m) _Pragma("unroll") for (int k = 0; k < 2; ++k) dst[m][k] = *(const PG8_LAS bf16x8*)(lds + PG8_SA(b, h) + aoff + m * 2048 + k * 1024); } while (0)
; #define PG8_MMA(ai, bj, At, Bt) do { __builtin_amdgcn_s_setprio(1); _Pragma("unroll") for (int m = 0; m < 4; ++m) _Pragma("unroll") for (int n = 0; n < 2; ++n) _Pragma("unroll") for (int k = 0; k < 2; ++k) \
;         acc[ai][bj][m][n] = __builtin_amdgcn_mfma_f32_16x16x32_bf16(Bt[n][k], At[m][k], acc[ai][bj][m][n], 0, 0, 0); __builtin_amdgcn_s_setprio(0); } while (0)
; #define PG8_WAIT_V(n) asm volatile("s_waitcnt vmcnt(" #n ")" ::: "memory")
; #define PG8_WAIT_L(n) asm volatile("s_waitcnt lgkmcnt(" #n ")" ::: "memory")
; #define PG8_BAR __builtin_amdgcn_s_barrier()
; #define PG8_SCHED __builtin_amdgcn_sched_barrier(0)
; template <class Epi, class Sched, bool ALIGN_EPI = false, bool SP2 = false>
; __device__ __forceinline__ void gemm_phase(PG8_LAS unsigned char* lds, const Gemm g, const Sched& S, const Epi& E) {
;     ...
;         for (int t = 0; t < nt; t += 2) {
;     ...
;             PG8_LDA(At, 1, 1); PG8_STAGE(PG8_SB(1, 0), b3, voffB); PG8_STAGE(PG8_SB(1, 1), b3 + hstepB, voffB); PG8_STAGE(PG8_SA(1, 0), a3, voffA);
;             PG8_WAIT_V(8); PG8_WAIT_L(0); PG8_BAR; PG8_MMA(1, 0, At, B0); PG8_MMA(1, 1, At, B1); PG8_BAR; PG8_SCHED;
	s_setprio 0
	s_add_i32 s4, s12, s9
	v_lshl_add_u64 v[174:175], v[174:175], 0, s[54:55]
	s_mov_b32 m0, s4
	ds_read_b128 v[198:201], v179 offset:49152
	ds_read_b128 v[202:205], v179 offset:50176
	ds_read_b128 v[206:209], v179 offset:51200
	ds_read_b128 v[210:213], v179 offset:52224
	ds_read_b128 v[214:217], v179 offset:53248
	ds_read_b128 v[218:221], v179 offset:54272
	ds_read_b128 v[222:225], v179 offset:55296
	ds_read_b128 v[226:229], v179 offset:56320
	global_load_lds_dwordx4 v[174:175], off
	s_add_i32 m0, s4, 0x2000
	s_add_u32 s4, s52, 0x160080
	v_lshl_add_u64 v[174:175], v[230:231], 0, s[54:55]
	s_addc_u32 s5, s53, 0
	s_add_i32 s12, s13, s9
	global_load_lds_dwordx4 v[174:175], off
	v_lshl_add_u64 v[174:175], s[4:5], 0, v[130:131]
	s_mov_b32 m0, s12
	s_nop 0
	global_load_lds_dwordx4 v[174:175], off
	v_lshl_add_u64 v[174:175], s[4:5], 0, v[134:135]
	s_add_i32 m0, s12, 0x2000
	s_nop 0
	global_load_lds_dwordx4 v[174:175], off
	v_lshl_add_u64 v[174:175], s[50:51], 0, v[128:129]
	s_mov_b32 m0, s45
	s_nop 0
	global_load_lds_dwordx4 v[174:175], off
	v_lshl_add_u64 v[174:175], s[50:51], 0, v[132:133]
	s_mov_b32 m0, s56
	s_nop 0
	global_load_lds_dwordx4 v[174:175], off
	s_waitcnt vmcnt(8)
	s_waitcnt lgkmcnt(0)
	s_setprio 1
	s_barrier
	v_mfma_f32_16x16x32_bf16 v[60:63], v[158:161], v[198:201], v[60:63]
	v_mfma_f32_16x16x32_bf16 v[56:59], v[166:169], v[198:201], v[56:59]
	v_mfma_f32_16x16x32_bf16 v[52:55], v[158:161], v[206:209], v[52:55]
	v_mfma_f32_16x16x32_bf16 v[48:51], v[166:169], v[206:209], v[48:51]
	v_mfma_f32_16x16x32_bf16 v[44:47], v[158:161], v[214:217], v[44:47]
	v_mfma_f32_16x16x32_bf16 v[40:43], v[166:169], v[214:217], v[40:43]
	v_mfma_f32_16x16x32_bf16 v[36:39], v[158:161], v[222:225], v[36:39]
	v_mfma_f32_16x16x32_bf16 v[32:35], v[166:169], v[222:225], v[32:35]
	v_mfma_f32_16x16x32_bf16 v[60:63], v[162:165], v[202:205], v[60:63]
	v_mfma_f32_16x16x32_bf16 v[56:59], v[170:173], v[202:205], v[56:59]
	v_mfma_f32_16x16x32_bf16 v[52:55], v[162:165], v[210:213], v[52:55]
	v_mfma_f32_16x16x32_bf16 v[48:51], v[170:173], v[210:213], v[48:51]
	v_mfma_f32_16x16x32_bf16 v[44:47], v[162:165], v[218:221], v[44:47]
	v_mfma_f32_16x16x32_bf16 v[40:43], v[170:173], v[218:221], v[40:43]
	v_mfma_f32_16x16x32_bf16 v[36:39], v[162:165], v[226:229], v[36:39]
	v_mfma_f32_16x16x32_bf16 v[32:35], v[170:173], v[226:229], v[32:35]
	v_mfma_f32_16x16x32_bf16 v[28:31], v[180:183], v[198:201], v[28:31]
	v_mfma_f32_16x16x32_bf16 v[24:27], v[190:193], v[198:201], v[24:27]
	v_mfma_f32_16x16x32_bf16 v[20:23], v[180:183], v[206:209], v[20:23]
	v_mfma_f32_16x16x32_bf16 v[16:19], v[190:193], v[206:209], v[16:19]
	v_mfma_f32_16x16x32_bf16 v[12:15], v[180:183], v[214:217], v[12:15]
	v_mfma_f32_16x16x32_bf16 v[8:11], v[190:193], v[214:217], v[8:11]
	v_mfma_f32_16x16x32_bf16 v[4:7], v[180:183], v[222:225], v[4:7]
	v_mfma_f32_16x16x32_bf16 v[0:3], v[190:193], v[222:225], v[0:3]
	v_mfma_f32_16x16x32_bf16 v[28:31], v[186:189], v[202:205], v[28:31]
	v_mfma_f32_16x16x32_bf16 v[24:27], v[194:197], v[202:205], v[24:27]
	v_mfma_f32_16x16x32_bf16 v[20:23], v[186:189], v[210:213], v[20:23]
	v_mfma_f32_16x16x32_bf16 v[16:19], v[194:197], v[210:213], v[16:19]
	v_mfma_f32_16x16x32_bf16 v[12:15], v[186:189], v[218:221], v[12:15]
	v_mfma_f32_16x16x32_bf16 v[8:11], v[194:197], v[218:221], v[8:11]
	v_mfma_f32_16x16x32_bf16 v[4:7], v[186:189], v[226:229], v[4:7]
	v_mfma_f32_16x16x32_bf16 v[0:3], v[194:197], v[226:229], v[0:3]
	s_barrier
	s_setprio 0
	s_cmp_ge_i32 s74, s57
	s_cbranch_scc1 .LBB0_409

; #define PG8_STAGE(bufoff, gbase, voff) do { _Pragma("unroll") for (int _i = 0; _i < 2; ++_i) \
;         __builtin_amdgcn_global_load_lds((const unsigned*)((const char*)(gbase) + (voff)[_i]), (PG8_LAS unsigned*)(lds + (bufoff) + ldsw + _i * 8192), 16, 0, 0); } while (0)
; #define PG8_LDA(dst, b, h) do { _Pragma("unroll") for (int m = 0; m < 4; ++m) _Pragma("unroll") for (int k = 0; k < 2; ++k) dst[m][k] = *(const PG8_LAS bf16x8*)(lds + PG8_SA(b, h) + aoff + m * 2048 + k * 1024); } while (0)
; #define PG8_LDB(dst, b, h) do { _Pragma("unroll") for (int n = 0; n < 2; ++n) _Pragma("unroll") for (int k = 0; k < 2; ++k) dst[n][k] = *(const PG8_LAS bf16x8*)(lds + PG8_SB(b, h) + boff + n * 2048 + k * 1024); } while (0)
; #define PG8_MMA(ai, bj, At, Bt) do { __builtin_amdgcn_s_setprio(1); _Pragma("unroll") for (int m = 0; m < 4; ++m) _Pragma("unroll") for (int n = 0; n < 2; ++n) _Pragma("unroll") for (int k = 0; k < 2; ++k) \
;         acc[ai][bj][m][n] = __builtin_amdgcn_mfma_f32_16x16x32_bf16(Bt[n][k], At[m][k], acc[ai][bj][m][n], 0, 0, 0); __builtin_amdgcn_s_setprio(0); } while (0)
; #define PG8_WAIT_V(n) asm volatile("s_waitcnt vmcnt(" #n ")" ::: "memory")
; #define PG8_WAIT_L(n) asm volatile("s_waitcnt lgkmcnt(" #n ")" ::: "memory")
; #define PG8_BAR __builtin_amdgcn_s_barrier()
; #define PG8_SCHED __builtin_amdgcn_sched_barrier(0)
; template <class Epi, class Sched, bool ALIGN_EPI = false, bool SP2 = false>
; __device__ __forceinline__ void gemm_phase(PG8_LAS unsigned char* lds, const Gemm g, const Sched& S, const Epi& E) {
;     ...
;             const char* a1 = cA + (size_t)(t + 1) * kstA;
;             const char* a2 = last ? nA : cA + (size_t)(t + 2) * kstA; const char* b2 = last ? nB : cB + (size_t)(t + 2) * kstep;
;             const char* a3 = a2 + kstA; const char* b3 = b2 + kstep;
;             if (last && has_next) S.a_ready(nxt);
;             if constexpr (SP2) {
;             PG8_LDB(B0, 0, 0); PG8_LDB(B1, 0, 1); PG8_SCHED; PG8_LDA(At, 0, 0); PG8_STAGE(PG8_SA(1, 1), a1 + hstepA, voffA);
;             PG8_WAIT_V(8); PG8_WAIT_L(0); PG8_BAR; PG8_MMA(0, 0, At, B0); PG8_MMA(0, 1, At, B1); PG8_BAR; PG8_SCHED;
;             PG8_LDA(At, 0, 1); PG8_STAGE(PG8_SB(0, 0), b2, voffB); PG8_STAGE(PG8_SB(0, 1), b2 + hstepB, voffB); PG8_STAGE(PG8_SA(0, 0), a2, voffA);
.LBB0_656:
	ds_read_b128 v[166:169], v163
	ds_read_b128 v[170:173], v163 offset:1024
	ds_read_b128 v[174:177], v163 offset:2048
	ds_read_b128 v[178:181], v163 offset:3072
	ds_read_b128 v[186:189], v164
	ds_read_b128 v[190:193], v164 offset:1024
	ds_read_b128 v[194:197], v164 offset:2048
	ds_read_b128 v[198:201], v164 offset:3072
	s_add_u32 s47, s50, 0xfff80080
	s_addc_u32 s52, s51, -1
	s_cmp_eq_u32 s46, 28
	s_cselect_b32 s59, s63, s52
	s_cselect_b32 s58, s62, s47
	s_cselect_b32 s53, s65, s5
	s_cselect_b32 s52, s64, s4
	v_lshl_add_u64 v[158:159], s[50:51], 0, v[152:153]
	s_add_i32 m0, s9, 0xc000
	ds_read_b128 v[202:205], v165
	ds_read_b128 v[206:209], v165 offset:1024
	ds_read_b128 v[210:213], v165 offset:2048
	ds_read_b128 v[214:217], v165 offset:3072
	ds_read_b128 v[218:221], v165 offset:4096
	ds_read_b128 v[222:225], v165 offset:5120
	ds_read_b128 v[226:229], v165 offset:6144
	ds_read_b128 v[230:233], v165 offset:7168
	global_load_lds_dwordx4 v[158:159], off
	v_lshl_add_u64 v[158:159], s[50:51], 0, v[154:155]
	s_add_i32 m0, s9, 0xe000
	s_nop 0
	global_load_lds_dwordx4 v[158:159], off
	s_waitcnt vmcnt(8)
	s_waitcnt lgkmcnt(0)
	s_setprio 1
	s_barrier
	v_mfma_f32_16x16x32_bf16 v[124:127], v[166:169], v[202:205], v[124:127]
	v_mfma_f32_16x16x32_bf16 v[120:123], v[174:177], v[202:205], v[120:123]
	v_mfma_f32_16x16x32_bf16 v[112:115], v[166:169], v[210:213], v[112:115]
	v_mfma_f32_16x16x32_bf16 v[104:107], v[174:177], v[210:213], v[104:107]
	v_mfma_f32_16x16x32_bf16 v[96:99], v[166:169], v[218:221], v[96:99]
	v_mfma_f32_16x16x32_bf16 v[88:91], v[174:177], v[218:221], v[88:91]
	v_mfma_f32_16x16x32_bf16 v[80:83], v[166:169], v[226:229], v[80:83]
	v_mfma_f32_16x16x32_bf16 v[72:75], v[174:177], v[226:229], v[72:75]
	v_mfma_f32_16x16x32_bf16 v[124:127], v[170:173], v[206:209], v[124:127]
	v_mfma_f32_16x16x32_bf16 v[120:123], v[178:181], v[206:209], v[120:123]
	v_mfma_f32_16x16x32_bf16 v[112:115], v[170:173], v[214:217], v[112:115]
	v_mfma_f32_16x16x32_bf16 v[104:107], v[178:181], v[214:217], v[104:107]
	v_mfma_f32_16x16x32_bf16 v[96:99], v[170:173], v[222:225], v[96:99]
	v_mfma_f32_16x16x32_bf16 v[88:91], v[178:181], v[222:225], v[88:91]
	v_mfma_f32_16x16x32_bf16 v[80:83], v[170:173], v[230:233], v[80:83]
	v_mfma_f32_16x16x32_bf16 v[72:75], v[178:181], v[230:233], v[72:75]
	v_mfma_f32_16x16x32_bf16 v[116:119], v[186:189], v[202:205], v[116:119]
	v_mfma_f32_16x16x32_bf16 v[108:111], v[194:197], v[202:205], v[108:111]
	v_mfma_f32_16x16x32_bf16 v[100:103], v[186:189], v[210:213], v[100:103]
	v_mfma_f32_16x16x32_bf16 v[92:95], v[194:197], v[210:213], v[92:95]
	v_mfma_f32_16x16x32_bf16 v[84:87], v[186:189], v[218:221], v[84:87]
	v_mfma_f32_16x16x32_bf16 v[76:79], v[194:197], v[218:221], v[76:79]
	v_mfma_f32_16x16x32_bf16 v[68:71], v[186:189], v[226:229], v[68:71]
	v_mfma_f32_16x16x32_bf16 v[64:67], v[194:197], v[226:229], v[64:67]
	v_mfma_f32_16x16x32_bf16 v[116:119], v[190:193], v[206:209], v[116:119]
	v_mfma_f32_16x16x32_bf16 v[108:111], v[198:201], v[206:209], v[108:111]
	v_mfma_f32_16x16x32_bf16 v[100:103], v[190:193], v[214:217], v[100:103]
	v_mfma_f32_16x16x32_bf16 v[92:95], v[198:201], v[214:217], v[92:95]
	v_mfma_f32_16x16x32_bf16 v[84:87], v[190:193], v[222:225], v[84:87]
	v_mfma_f32_16x16x32_bf16 v[76:79], v[198:201], v[222:225], v[76:79]
	v_mfma_f32_16x16x32_bf16 v[68:71], v[190:193], v[230:233], v[68:71]
	v_mfma_f32_16x16x32_bf16 v[64:67], v[198:201], v[230:233], v[64:67]
	s_barrier
	s_setprio 0
	s_add_i32 s47, s44, s8
	v_lshl_add_u64 v[158:159], s[52:53], 0, v[130:131]
	s_mov_b32 m0, s47
	ds_read_b128 v[202:205], v165 offset:16384
	ds_read_b128 v[206:209], v165 offset:17408
	ds_read_b128 v[210:213], v165 offset:18432
	ds_read_b128 v[214:217], v165 offset:19456
	ds_read_b128 v[218:221], v165 offset:20480
	ds_read_b128 v[222:225], v165 offset:21504
	ds_read_b128 v[226:229], v165 offset:22528
	ds_read_b128 v[230:233], v165 offset:23552
	global_load_lds_dwordx4 v[158:159], off
	s_add_i32 m0, s47, 0x2000
	s_add_u32 s66, s52, 0x80000
	v_lshl_add_u64 v[182:183], s[52:53], 0, v[134:135]
	s_addc_u32 s67, s53, 0
	s_add_i32 s47, s45, s8
	global_load_lds_dwordx4 v[182:183], off
	v_lshl_add_u64 v[234:235], s[66:67], 0, v[130:131]
	s_mov_b32 m0, s47
	v_lshl_add_u64 v[236:237], s[58:59], 0, v[132:133]
	global_load_lds_dwordx4 v[234:235], off
	v_lshl_add_u64 v[234:235], s[66:67], 0, v[134:135]
	s_add_i32 m0, s47, 0x2000
	s_nop 0
	global_load_lds_dwordx4 v[234:235], off
	v_lshl_add_u64 v[234:235], s[58:59], 0, v[128:129]
	s_mov_b32 m0, s9
	s_nop 0
	global_load_lds_dwordx4 v[234:235], off
	s_mov_b32 m0, s10
	s_nop 0
	global_load_lds_dwordx4 v[236:237], off
	s_waitcnt vmcnt(8)
	s_waitcnt lgkmcnt(0)
	s_setprio 1
	s_barrier
; #define PG8_STAGE(bufoff, gbase, voff) do { _Pragma("unroll") for (int _i = 0; _i < 2; ++_i) \
;         __builtin_amdgcn_global_load_lds((const unsigned*)((const char*)(gbase) + (voff)[_i]), (PG8_LAS unsigned*)(lds + (bufoff) + ldsw + _i * 8192), 16, 0, 0); } while (0)
; #define PG8_LDA(dst, b, h) do { _Pragma("unroll") for (int m = 0; m < 4; ++m) _Pragma("unroll") for (int k = 0; k < 2; ++k) dst[m][k] = *(const PG8_LAS bf16x8*)(lds + PG8_SA(b, h) + aoff + m * 2048 + k * 1024); } while (0)
; #define PG8_LDB(dst, b, h) do { _Pragma("unroll") for (int n = 0; n < 2; ++n) _Pragma("unroll") for (int k = 0; k < 2; ++k) dst[n][k] = *(const PG8_LAS bf16x8*)(lds + PG8_SB(b, h) + boff + n * 2048 + k * 1024); } while (0)
; #define PG8_MMA(ai, bj, At, Bt) do { __builtin_amdgcn_s_setprio(1); _Pragma("unroll") for (int m = 0; m < 4; ++m) _Pragma("unroll") for (int n = 0; n < 2; ++n) _Pragma("unroll") for (int k = 0; k < 2; ++k) \
;         acc[ai][bj][m][n] = __builtin_amdgcn_mfma_f32_16x16x32_bf16(Bt[n][k], At[m][k], acc[ai][bj][m][n], 0, 0, 0); __builtin_amdgcn_s_setprio(0); } while (0)
; #define PG8_WAIT_V(n) asm volatile("s_waitcnt vmcnt(" #n ")" ::: "memory")
; #define PG8_WAIT_L(n) asm volatile("s_waitcnt lgkmcnt(" #n ")" ::: "memory")
; #define PG8_BAR __builtin_amdgcn_s_barrier()
; #define PG8_SCHED __builtin_amdgcn_sched_barrier(0)
; template <class Epi, class Sched, bool ALIGN_EPI = false, bool SP2 = false>
; __device__ __forceinline__ void gemm_phase(PG8_LAS unsigned char* lds, const Gemm g, const Sched& S, const Epi& E) {
;     ...
;             PG8_WAIT_V(8); PG8_WAIT_L(0); PG8_BAR; PG8_MMA(1, 0, At, B0); PG8_MMA(1, 1, At, B1); PG8_BAR; PG8_SCHED;
;             PG8_LDB(B0, 1, 0); PG8_LDB(B1, 1, 1); PG8_SCHED; PG8_LDA(At, 1, 0); PG8_STAGE(PG8_SA(0, 1), a2 + hstepA, voffA);
;             PG8_WAIT_V(8); PG8_WAIT_L(0); PG8_BAR; PG8_MMA(0, 0, At, B0); PG8_MMA(0, 1, At, B1); PG8_BAR; PG8_SCHED;
	v_mfma_f32_16x16x32_bf16 v[60:63], v[166:169], v[202:205], v[60:63]
	v_mfma_f32_16x16x32_bf16 v[56:59], v[174:177], v[202:205], v[56:59]
	v_mfma_f32_16x16x32_bf16 v[48:51], v[166:169], v[210:213], v[48:51]
	v_mfma_f32_16x16x32_bf16 v[40:43], v[174:177], v[210:213], v[40:43]
	v_mfma_f32_16x16x32_bf16 v[32:35], v[166:169], v[218:221], v[32:35]
	v_mfma_f32_16x16x32_bf16 v[24:27], v[174:177], v[218:221], v[24:27]
	v_mfma_f32_16x16x32_bf16 v[16:19], v[166:169], v[226:229], v[16:19]
	v_mfma_f32_16x16x32_bf16 v[8:11], v[174:177], v[226:229], v[8:11]
	v_mfma_f32_16x16x32_bf16 v[60:63], v[170:173], v[206:209], v[60:63]
	v_mfma_f32_16x16x32_bf16 v[56:59], v[178:181], v[206:209], v[56:59]
	v_mfma_f32_16x16x32_bf16 v[48:51], v[170:173], v[214:217], v[48:51]
	v_mfma_f32_16x16x32_bf16 v[40:43], v[178:181], v[214:217], v[40:43]
	v_mfma_f32_16x16x32_bf16 v[32:35], v[170:173], v[222:225], v[32:35]
	v_mfma_f32_16x16x32_bf16 v[24:27], v[178:181], v[222:225], v[24:27]
	v_mfma_f32_16x16x32_bf16 v[16:19], v[170:173], v[230:233], v[16:19]
	v_mfma_f32_16x16x32_bf16 v[8:11], v[178:181], v[230:233], v[8:11]
	v_mfma_f32_16x16x32_bf16 v[52:55], v[186:189], v[202:205], v[52:55]
	v_mfma_f32_16x16x32_bf16 v[44:47], v[194:197], v[202:205], v[44:47]
	v_mfma_f32_16x16x32_bf16 v[36:39], v[186:189], v[210:213], v[36:39]
	v_mfma_f32_16x16x32_bf16 v[28:31], v[194:197], v[210:213], v[28:31]
	v_mfma_f32_16x16x32_bf16 v[20:23], v[186:189], v[218:221], v[20:23]
	v_mfma_f32_16x16x32_bf16 v[12:15], v[194:197], v[218:221], v[12:15]
	v_mfma_f32_16x16x32_bf16 v[4:7], v[186:189], v[226:229], v[4:7]
	v_mfma_f32_16x16x32_bf16 v[0:3], v[194:197], v[226:229], v[0:3]
	v_mfma_f32_16x16x32_bf16 v[52:55], v[190:193], v[206:209], v[52:55]
	v_mfma_f32_16x16x32_bf16 v[44:47], v[198:201], v[206:209], v[44:47]
	v_mfma_f32_16x16x32_bf16 v[36:39], v[190:193], v[214:217], v[36:39]
	v_mfma_f32_16x16x32_bf16 v[28:31], v[198:201], v[214:217], v[28:31]
	v_mfma_f32_16x16x32_bf16 v[20:23], v[190:193], v[222:225], v[20:23]
	v_mfma_f32_16x16x32_bf16 v[12:15], v[198:201], v[222:225], v[12:15]
	v_mfma_f32_16x16x32_bf16 v[4:7], v[190:193], v[230:233], v[4:7]
	v_mfma_f32_16x16x32_bf16 v[0:3], v[198:201], v[230:233], v[0:3]
	s_barrier
	s_setprio 0
	s_add_i32 s47, 0, 0x18000
	s_add_i32 s55, 0, 0x1c000
	v_add_u32_e32 v178, s47, v160
	v_add_u32_e32 v185, s55, v160
	ds_read_b128 v[166:169], v178
	ds_read_b128 v[170:173], v178 offset:1024
	ds_read_b128 v[174:177], v178 offset:2048
	ds_read_b128 v[178:181], v178 offset:3072
	ds_read_b128 v[186:189], v185
	ds_read_b128 v[190:193], v185 offset:1024
	ds_read_b128 v[194:197], v185 offset:2048
	ds_read_b128 v[198:201], v185 offset:3072
	s_add_u32 s58, s58, 0x80000
	s_addc_u32 s59, s59, 0
	s_mov_b32 m0, s11
	v_lshl_add_u64 v[238:239], s[58:59], 0, v[128:129]
	ds_read_b128 v[202:205], v165 offset:32768
	ds_read_b128 v[206:209], v165 offset:33792
	ds_read_b128 v[210:213], v165 offset:34816
	ds_read_b128 v[214:217], v165 offset:35840
	ds_read_b128 v[218:221], v165 offset:36864
	ds_read_b128 v[222:225], v165 offset:37888
	ds_read_b128 v[226:229], v165 offset:38912
	ds_read_b128 v[230:233], v165 offset:39936
	global_load_lds_dwordx4 v[238:239], off
	v_lshl_add_u64 v[238:239], s[58:59], 0, v[132:133]
	s_mov_b32 m0, s12
	s_nop 0
	global_load_lds_dwordx4 v[238:239], off
	s_waitcnt vmcnt(8)
	s_waitcnt lgkmcnt(0)
	s_setprio 1
	s_barrier
	v_mfma_f32_16x16x32_bf16 v[124:127], v[166:169], v[202:205], v[124:127]
	v_mfma_f32_16x16x32_bf16 v[120:123], v[174:177], v[202:205], v[120:123]
	v_mfma_f32_16x16x32_bf16 v[112:115], v[166:169], v[210:213], v[112:115]
	v_mfma_f32_16x16x32_bf16 v[104:107], v[174:177], v[210:213], v[104:107]
	v_mfma_f32_16x16x32_bf16 v[96:99], v[166:169], v[218:221], v[96:99]
	v_mfma_f32_16x16x32_bf16 v[88:91], v[174:177], v[218:221], v[88:91]
	v_mfma_f32_16x16x32_bf16 v[80:83], v[166:169], v[226:229], v[80:83]
	v_mfma_f32_16x16x32_bf16 v[72:75], v[174:177], v[226:229], v[72:75]
	v_mfma_f32_16x16x32_bf16 v[124:127], v[170:173], v[206:209], v[124:127]
	v_mfma_f32_16x16x32_bf16 v[120:123], v[178:181], v[206:209], v[120:123]
	v_mfma_f32_16x16x32_bf16 v[112:115], v[170:173], v[214:217], v[112:115]
	v_mfma_f32_16x16x32_bf16 v[104:107], v[178:181], v[214:217], v[104:107]
	v_mfma_f32_16x16x32_bf16 v[96:99], v[170:173], v[222:225], v[96:99]
	v_mfma_f32_16x16x32_bf16 v[88:91], v[178:181], v[222:225], v[88:91]
	v_mfma_f32_16x16x32_bf16 v[80:83], v[170:173], v[230:233], v[80:83]
	v_mfma_f32_16x16x32_bf16 v[72:75], v[178:181], v[230:233], v[72:75]
	v_mfma_f32_16x16x32_bf16 v[116:119], v[186:189], v[202:205], v[116:119]
	v_mfma_f32_16x16x32_bf16 v[108:111], v[194:197], v[202:205], v[108:111]
	v_mfma_f32_16x16x32_bf16 v[100:103], v[186:189], v[210:213], v[100:103]
	v_mfma_f32_16x16x32_bf16 v[92:95], v[194:197], v[210:213], v[92:95]
	v_mfma_f32_16x16x32_bf16 v[84:87], v[186:189], v[218:221], v[84:87]
	v_mfma_f32_16x16x32_bf16 v[76:79], v[194:197], v[218:221], v[76:79]
	v_mfma_f32_16x16x32_bf16 v[68:71], v[186:189], v[226:229], v[68:71]
	v_mfma_f32_16x16x32_bf16 v[64:67], v[194:197], v[226:229], v[64:67]
	v_mfma_f32_16x16x32_bf16 v[116:119], v[190:193], v[206:209], v[116:119]
	v_mfma_f32_16x16x32_bf16 v[108:111], v[198:201], v[206:209], v[108:111]
	v_mfma_f32_16x16x32_bf16 v[100:103], v[190:193], v[214:217], v[100:103]
	v_mfma_f32_16x16x32_bf16 v[92:95], v[198:201], v[214:217], v[92:95]
	v_mfma_f32_16x16x32_bf16 v[84:87], v[190:193], v[222:225], v[84:87]
	v_mfma_f32_16x16x32_bf16 v[76:79], v[198:201], v[222:225], v[76:79]
	v_mfma_f32_16x16x32_bf16 v[68:71], v[190:193], v[230:233], v[68:71]
	v_mfma_f32_16x16x32_bf16 v[64:67], v[198:201], v[230:233], v[64:67]
	s_barrier
; #define PG8_STAGE(bufoff, gbase, voff) do { _Pragma("unroll") for (int _i = 0; _i < 2; ++_i) \
;         __builtin_amdgcn_global_load_lds((const unsigned*)((const char*)(gbase) + (voff)[_i]), (PG8_LAS unsigned*)(lds + (bufoff) + ldsw + _i * 8192), 16, 0, 0); } while (0)
; #define PG8_LDA(dst, b, h) do { _Pragma("unroll") for (int m = 0; m < 4; ++m) _Pragma("unroll") for (int k = 0; k < 2; ++k) dst[m][k] = *(const PG8_LAS bf16x8*)(lds + PG8_SA(b, h) + aoff + m * 2048 + k * 1024); } while (0)
; #define PG8_MMA(ai, bj, At, Bt) do { __builtin_amdgcn_s_setprio(1); _Pragma("unroll") for (int m = 0; m < 4; ++m) _Pragma("unroll") for (int n = 0; n < 2; ++n) _Pragma("unroll") for (int k = 0; k < 2; ++k) \
;         acc[ai][bj][m][n] = __builtin_amdgcn_mfma_f32_16x16x32_bf16(Bt[n][k], At[m][k], acc[ai][bj][m][n], 0, 0, 0); __builtin_amdgcn_s_setprio(0); } while (0)
; #define PG8_WAIT_V(n) asm volatile("s_waitcnt vmcnt(" #n ")" ::: "memory")
; #define PG8_WAIT_L(n) asm volatile("s_waitcnt lgkmcnt(" #n ")" ::: "memory")
; #define PG8_BAR __builtin_amdgcn_s_barrier()
; #define PG8_SCHED __builtin_amdgcn_sched_barrier(0)
; template <class Epi, class Sched, bool ALIGN_EPI = false, bool SP2 = false>
; __device__ __forceinline__ void gemm_phase(PG8_LAS unsigned char* lds, const Gemm g, const Sched& S, const Epi& E) {
;     ...
;         for (int t = 0; t < nt; t += 2) {
;     ...
;             PG8_LDA(At, 1, 1); PG8_STAGE(PG8_SB(1, 0), b3, voffB); PG8_STAGE(PG8_SB(1, 1), b3 + hstepB, voffB); PG8_STAGE(PG8_SA(1, 0), a3, voffA);
;             PG8_WAIT_V(8); PG8_WAIT_L(0); PG8_BAR; PG8_MMA(1, 0, At, B0); PG8_MMA(1, 1, At, B1); PG8_BAR; PG8_SCHED;
	s_setprio 0
	s_add_i32 s47, s47, s8
	v_lshl_add_u64 v[158:159], v[158:159], 0, s[38:39]
	s_mov_b32 m0, s47
	ds_read_b128 v[202:205], v165 offset:49152
	ds_read_b128 v[206:209], v165 offset:50176
	ds_read_b128 v[210:213], v165 offset:51200
	ds_read_b128 v[214:217], v165 offset:52224
	ds_read_b128 v[218:221], v165 offset:53248
	ds_read_b128 v[222:225], v165 offset:54272
	ds_read_b128 v[226:229], v165 offset:55296
	ds_read_b128 v[230:233], v165 offset:56320
	global_load_lds_dwordx4 v[158:159], off
	s_add_i32 m0, s47, 0x2000
	s_add_u32 s52, s52, 0x80080
	v_lshl_add_u64 v[158:159], v[182:183], 0, s[38:39]
	s_addc_u32 s53, s53, 0
	s_add_i32 s47, s55, s8
	global_load_lds_dwordx4 v[158:159], off
	v_lshl_add_u64 v[158:159], s[52:53], 0, v[130:131]
	s_mov_b32 m0, s47
	s_nop 0
	global_load_lds_dwordx4 v[158:159], off
	v_lshl_add_u64 v[158:159], s[52:53], 0, v[134:135]
	s_add_i32 m0, s47, 0x2000
	s_nop 0
	global_load_lds_dwordx4 v[158:159], off
	v_lshl_add_u64 v[158:159], v[234:235], 0, s[38:39]
	s_mov_b32 m0, s13
	s_nop 0
	global_load_lds_dwordx4 v[158:159], off
	v_lshl_add_u64 v[158:159], v[236:237], 0, s[38:39]
	s_mov_b32 m0, s33
	s_nop 0
	global_load_lds_dwordx4 v[158:159], off
	s_waitcnt vmcnt(8)
	s_waitcnt lgkmcnt(0)
	s_setprio 1
	s_barrier
	v_mfma_f32_16x16x32_bf16 v[60:63], v[166:169], v[202:205], v[60:63]
	v_mfma_f32_16x16x32_bf16 v[56:59], v[174:177], v[202:205], v[56:59]
	v_mfma_f32_16x16x32_bf16 v[48:51], v[166:169], v[210:213], v[48:51]
	v_mfma_f32_16x16x32_bf16 v[40:43], v[174:177], v[210:213], v[40:43]
	v_mfma_f32_16x16x32_bf16 v[32:35], v[166:169], v[218:221], v[32:35]
	v_mfma_f32_16x16x32_bf16 v[24:27], v[174:177], v[218:221], v[24:27]
	v_mfma_f32_16x16x32_bf16 v[16:19], v[166:169], v[226:229], v[16:19]
	v_mfma_f32_16x16x32_bf16 v[8:11], v[174:177], v[226:229], v[8:11]
	v_mfma_f32_16x16x32_bf16 v[60:63], v[170:173], v[206:209], v[60:63]
	v_mfma_f32_16x16x32_bf16 v[56:59], v[178:181], v[206:209], v[56:59]
	v_mfma_f32_16x16x32_bf16 v[48:51], v[170:173], v[214:217], v[48:51]
	v_mfma_f32_16x16x32_bf16 v[40:43], v[178:181], v[214:217], v[40:43]
	v_mfma_f32_16x16x32_bf16 v[32:35], v[170:173], v[222:225], v[32:35]
	v_mfma_f32_16x16x32_bf16 v[24:27], v[178:181], v[222:225], v[24:27]
	v_mfma_f32_16x16x32_bf16 v[16:19], v[170:173], v[230:233], v[16:19]
	v_mfma_f32_16x16x32_bf16 v[8:11], v[178:181], v[230:233], v[8:11]
	v_mfma_f32_16x16x32_bf16 v[52:55], v[186:189], v[202:205], v[52:55]
	v_mfma_f32_16x16x32_bf16 v[44:47], v[194:197], v[202:205], v[44:47]
	v_mfma_f32_16x16x32_bf16 v[36:39], v[186:189], v[210:213], v[36:39]
	v_mfma_f32_16x16x32_bf16 v[28:31], v[194:197], v[210:213], v[28:31]
	v_mfma_f32_16x16x32_bf16 v[20:23], v[186:189], v[218:221], v[20:23]
	v_mfma_f32_16x16x32_bf16 v[12:15], v[194:197], v[218:221], v[12:15]
	v_mfma_f32_16x16x32_bf16 v[4:7], v[186:189], v[226:229], v[4:7]
	v_mfma_f32_16x16x32_bf16 v[0:3], v[194:197], v[226:229], v[0:3]
	v_mfma_f32_16x16x32_bf16 v[52:55], v[190:193], v[206:209], v[52:55]
	v_mfma_f32_16x16x32_bf16 v[44:47], v[198:201], v[206:209], v[44:47]
	v_mfma_f32_16x16x32_bf16 v[36:39], v[190:193], v[214:217], v[36:39]
	v_mfma_f32_16x16x32_bf16 v[28:31], v[198:201], v[214:217], v[28:31]
	v_mfma_f32_16x16x32_bf16 v[20:23], v[190:193], v[222:225], v[20:23]
	v_mfma_f32_16x16x32_bf16 v[12:15], v[198:201], v[222:225], v[12:15]
	v_mfma_f32_16x16x32_bf16 v[4:7], v[190:193], v[230:233], v[4:7]
	v_mfma_f32_16x16x32_bf16 v[0:3], v[198:201], v[230:233], v[0:3]
	s_barrier
	s_setprio 0
	s_add_i32 s46, s46, 2
	s_add_u32 s50, s50, 0x100
	s_addc_u32 s51, s51, 0
	s_add_u32 s4, s4, 0x100
	s_addc_u32 s5, s5, 0
	s_cmp_gt_u32 s46, 29
	s_cbranch_scc0 .LBB0_656
	s_and_b64 vcc, exec, s[40:41]
	s_cbranch_vccz .LBB0_659
	s_barrier

; #define PG8_STAGE(bufoff, gbase, voff) do { _Pragma("unroll") for (int _i = 0; _i < 2; ++_i) \
;         __builtin_amdgcn_global_load_lds((const unsigned*)((const char*)(gbase) + (voff)[_i]), (PG8_LAS unsigned*)(lds + (bufoff) + ldsw + _i * 8192), 16, 0, 0); } while (0)
; #define PG8_LDA(dst, b, h) do { _Pragma("unroll") for (int m = 0; m < 4; ++m) _Pragma("unroll") for (int k = 0; k < 2; ++k) dst[m][k] = *(const PG8_LAS bf16x8*)(lds + PG8_SA(b, h) + aoff + m * 2048 + k * 1024); } while (0)
; #define PG8_LDB(dst, b, h) do { _Pragma("unroll") for (int n = 0; n < 2; ++n) _Pragma("unroll") for (int k = 0; k < 2; ++k) dst[n][k] = *(const PG8_LAS bf16x8*)(lds + PG8_SB(b, h) + boff + n * 2048 + k * 1024); } while (0)
; #define PG8_WAIT_V(n) asm volatile("s_waitcnt vmcnt(" #n ")" ::: "memory")
; #define PG8_WAIT_L(n) asm volatile("s_waitcnt lgkmcnt(" #n ")" ::: "memory")
; #define PG8_BAR __builtin_amdgcn_s_barrier()
; #define PG8_SCHED __builtin_amdgcn_sched_barrier(0)
; template <class Epi, class Sched, bool ALIGN_EPI = false, bool SP2 = false>
; __device__ __forceinline__ void gemm_phase(PG8_LAS unsigned char* lds, const Gemm g, const Sched& S, const Epi& E) {
;     ...
;             const char* a1 = cA + (size_t)(t + 1) * kstA;
;             const char* a2 = last ? nA : cA + (size_t)(t + 2) * kstA; const char* b2 = last ? nB : cB + (size_t)(t + 2) * kstep;
;             const char* a3 = a2 + kstA; const char* b3 = b2 + kstep;
;             if (last && has_next) S.a_ready(nxt);
;             if constexpr (SP2) {
;             PG8_LDB(B0, 0, 0); PG8_LDB(B1, 0, 1); PG8_SCHED; PG8_LDA(At, 0, 0); PG8_STAGE(PG8_SA(1, 1), a1 + hstepA, voffA);
;             PG8_WAIT_V(8); PG8_WAIT_L(0); PG8_BAR; PG8_MMA(0, 0, At, B0); PG8_MMA(0, 1, At, B1); PG8_BAR; PG8_SCHED;
;             PG8_LDA(At, 0, 1); PG8_STAGE(PG8_SB(0, 0), b2, voffB); PG8_STAGE(PG8_SB(0, 1), b2 + hstepB, voffB); PG8_STAGE(PG8_SA(0, 0), a2, voffA);
;             PG8_WAIT_V(8); PG8_WAIT_L(0); PG8_BAR; PG8_MMA(1, 0, At, B0); PG8_MMA(1, 1, At, B1); PG8_BAR; PG8_SCHED;
;             PG8_LDB(B0, 1, 0); PG8_LDB(B1, 1, 1); PG8_SCHED; PG8_LDA(At, 1, 0); PG8_STAGE(PG8_SA(0, 1), a2 + hstepA, voffA);
;             PG8_WAIT_V(8); PG8_WAIT_L(0); PG8_BAR; PG8_MMA(0, 0, At, B0); PG8_MMA(0, 1, At, B1); PG8_BAR; PG8_SCHED;
.LBB0_1048:
	s_or_b32 s58, s66, 1
	s_add_i32 s66, s66, 2
	s_mov_b32 s67, s59
	v_add_u32_e32 v140, s10, v179
	v_add_u32_e32 v182, s11, v179
	s_lshl_b64 s[4:5], s[58:59], 7
	s_lshl_b64 s[6:7], s[66:67], 7
	ds_read_b128 v[128:131], v140
	ds_read_b128 v[132:135], v140 offset:1024
	ds_read_b128 v[136:139], v140 offset:2048
	ds_read_b128 v[140:143], v140 offset:3072
	ds_read_b128 v[174:177], v182
	ds_read_b128 v[190:193], v182 offset:1024
	ds_read_b128 v[194:197], v182 offset:2048
	ds_read_b128 v[198:201], v182 offset:3072
	s_add_u32 s46, s60, s6
	s_addc_u32 s47, s61, s7
	s_and_b64 s[12:13], s[76:77], exec
	s_cselect_b32 vcc_hi, s47, s49
	s_cselect_b32 vcc_lo, s46, s48
	s_add_u32 s12, s62, s6
	s_addc_u32 s13, s63, s7
	s_and_b64 s[6:7], s[76:77], exec
	s_cselect_b32 s77, s13, s55
	s_cselect_b32 s76, s12, s54
	s_add_u32 s4, s35, s4
	s_addc_u32 s5, s39, s5
	v_lshl_add_u64 v[182:183], s[4:5], 0, v[144:145]
	s_add_i32 m0, s21, 0xc000
	ds_read_b128 v[202:205], v181
	ds_read_b128 v[206:209], v181 offset:1024
	ds_read_b128 v[210:213], v181 offset:2048
	ds_read_b128 v[214:217], v181 offset:3072
	ds_read_b128 v[218:221], v181 offset:4096
	ds_read_b128 v[222:225], v181 offset:5120
	ds_read_b128 v[226:229], v181 offset:6144
	ds_read_b128 v[230:233], v181 offset:7168
	global_load_lds_dwordx4 v[182:183], off
	v_lshl_add_u64 v[182:183], s[4:5], 0, v[148:149]
	s_add_i32 m0, s21, 0xe000
	s_nop 0
	global_load_lds_dwordx4 v[182:183], off
	s_waitcnt vmcnt(8)
	s_waitcnt lgkmcnt(0)
	s_setprio 1
	s_barrier
	v_mfma_f32_16x16x32_bf16 v[124:127], v[128:131], v[202:205], v[124:127]
	v_mfma_f32_16x16x32_bf16 v[120:123], v[136:139], v[202:205], v[120:123]
	v_mfma_f32_16x16x32_bf16 v[116:119], v[128:131], v[210:213], v[116:119]
	v_mfma_f32_16x16x32_bf16 v[112:115], v[136:139], v[210:213], v[112:115]
	v_mfma_f32_16x16x32_bf16 v[108:111], v[128:131], v[218:221], v[108:111]
	v_mfma_f32_16x16x32_bf16 v[104:107], v[136:139], v[218:221], v[104:107]
	v_mfma_f32_16x16x32_bf16 v[100:103], v[128:131], v[226:229], v[100:103]
	v_mfma_f32_16x16x32_bf16 v[96:99], v[136:139], v[226:229], v[96:99]
	v_mfma_f32_16x16x32_bf16 v[124:127], v[132:135], v[206:209], v[124:127]
	v_mfma_f32_16x16x32_bf16 v[120:123], v[140:143], v[206:209], v[120:123]
	v_mfma_f32_16x16x32_bf16 v[116:119], v[132:135], v[214:217], v[116:119]
	v_mfma_f32_16x16x32_bf16 v[112:115], v[140:143], v[214:217], v[112:115]
	v_mfma_f32_16x16x32_bf16 v[108:111], v[132:135], v[222:225], v[108:111]
	v_mfma_f32_16x16x32_bf16 v[104:107], v[140:143], v[222:225], v[104:107]
	v_mfma_f32_16x16x32_bf16 v[100:103], v[132:135], v[230:233], v[100:103]
	v_mfma_f32_16x16x32_bf16 v[96:99], v[140:143], v[230:233], v[96:99]
	v_mfma_f32_16x16x32_bf16 v[92:95], v[174:177], v[202:205], v[92:95]
	v_mfma_f32_16x16x32_bf16 v[88:91], v[194:197], v[202:205], v[88:91]
	v_mfma_f32_16x16x32_bf16 v[84:87], v[174:177], v[210:213], v[84:87]
	v_mfma_f32_16x16x32_bf16 v[80:83], v[194:197], v[210:213], v[80:83]
	v_mfma_f32_16x16x32_bf16 v[76:79], v[174:177], v[218:221], v[76:79]
	v_mfma_f32_16x16x32_bf16 v[72:75], v[194:197], v[218:221], v[72:75]
	v_mfma_f32_16x16x32_bf16 v[68:71], v[174:177], v[226:229], v[68:71]
	v_mfma_f32_16x16x32_bf16 v[64:67], v[194:197], v[226:229], v[64:67]
	v_mfma_f32_16x16x32_bf16 v[92:95], v[190:193], v[206:209], v[92:95]
	v_mfma_f32_16x16x32_bf16 v[88:91], v[198:201], v[206:209], v[88:91]
	v_mfma_f32_16x16x32_bf16 v[84:87], v[190:193], v[214:217], v[84:87]
	v_mfma_f32_16x16x32_bf16 v[80:83], v[198:201], v[214:217], v[80:83]
	v_mfma_f32_16x16x32_bf16 v[76:79], v[190:193], v[222:225], v[76:79]
	v_mfma_f32_16x16x32_bf16 v[72:75], v[198:201], v[222:225], v[72:75]
	v_mfma_f32_16x16x32_bf16 v[68:71], v[190:193], v[230:233], v[68:71]
	v_mfma_f32_16x16x32_bf16 v[64:67], v[198:201], v[230:233], v[64:67]
	s_barrier
	s_setprio 0
	s_add_i32 s4, s10, s94
	v_lshl_add_u64 v[182:183], s[76:77], 0, v[146:147]
	s_mov_b32 m0, s4
	ds_read_b128 v[202:205], v181 offset:16384
	ds_read_b128 v[206:209], v181 offset:17408
	ds_read_b128 v[210:213], v181 offset:18432
	ds_read_b128 v[214:217], v181 offset:19456
	ds_read_b128 v[218:221], v181 offset:20480
	ds_read_b128 v[222:225], v181 offset:21504
	ds_read_b128 v[226:229], v181 offset:22528
	ds_read_b128 v[230:233], v181 offset:23552
	global_load_lds_dwordx4 v[182:183], off
	s_add_i32 m0, s4, 0x2000
	s_add_u32 s4, s76, 0x80000
	v_lshl_add_u64 v[234:235], s[76:77], 0, v[150:151]
	s_addc_u32 s5, s77, 0
	s_add_i32 s6, s11, s94
	global_load_lds_dwordx4 v[234:235], off
	v_lshl_add_u64 v[236:237], s[4:5], 0, v[146:147]
	s_mov_b32 m0, s6
	v_lshl_add_u64 v[238:239], vcc, 0, v[148:149]
	global_load_lds_dwordx4 v[236:237], off
	v_lshl_add_u64 v[236:237], s[4:5], 0, v[150:151]
	s_add_i32 m0, s6, 0x2000
	s_nop 0
	global_load_lds_dwordx4 v[236:237], off
	v_lshl_add_u64 v[236:237], vcc, 0, v[144:145]
	s_mov_b32 m0, s21
	s_nop 0
	global_load_lds_dwordx4 v[236:237], off
	s_mov_b32 m0, s95
	s_nop 0
	global_load_lds_dwordx4 v[238:239], off
	s_waitcnt vmcnt(8)
	s_waitcnt lgkmcnt(0)
	s_setprio 1
	s_barrier
; #define PG8_STAGE(bufoff, gbase, voff) do { _Pragma("unroll") for (int _i = 0; _i < 2; ++_i) \
;         __builtin_amdgcn_global_load_lds((const unsigned*)((const char*)(gbase) + (voff)[_i]), (PG8_LAS unsigned*)(lds + (bufoff) + ldsw + _i * 8192), 16, 0, 0); } while (0)
; #define PG8_LDA(dst, b, h) do { _Pragma("unroll") for (int m = 0; m < 4; ++m) _Pragma("unroll") for (int k = 0; k < 2; ++k) dst[m][k] = *(const PG8_LAS bf16x8*)(lds + PG8_SA(b, h) + aoff + m * 2048 + k * 1024); } while (0)
; #define PG8_LDB(dst, b, h) do { _Pragma("unroll") for (int n = 0; n < 2; ++n) _Pragma("unroll") for (int k = 0; k < 2; ++k) dst[n][k] = *(const PG8_LAS bf16x8*)(lds + PG8_SB(b, h) + boff + n * 2048 + k * 1024); } while (0)
; #define PG8_MMA(ai, bj, At, Bt) do { __builtin_amdgcn_s_setprio(1); _Pragma("unroll") for (int m = 0; m < 4; ++m) _Pragma("unroll") for (int n = 0; n < 2; ++n) _Pragma("unroll") for (int k = 0; k < 2; ++k) \
;         acc[ai][bj][m][n] = __builtin_amdgcn_mfma_f32_16x16x32_bf16(Bt[n][k], At[m][k], acc[ai][bj][m][n], 0, 0, 0); __builtin_amdgcn_s_setprio(0); } while (0)
; #define PG8_WAIT_V(n) asm volatile("s_waitcnt vmcnt(" #n ")" ::: "memory")
; #define PG8_WAIT_L(n) asm volatile("s_waitcnt lgkmcnt(" #n ")" ::: "memory")
; #define PG8_BAR __builtin_amdgcn_s_barrier()
; #define PG8_SCHED __builtin_amdgcn_sched_barrier(0)
; template <class Epi, class Sched, bool ALIGN_EPI = false, bool SP2 = false>
; __device__ __forceinline__ void gemm_phase(PG8_LAS unsigned char* lds, const Gemm g, const Sched& S, const Epi& E) {
;     ...
;             PG8_WAIT_V(8); PG8_WAIT_L(0); PG8_BAR; PG8_MMA(1, 0, At, B0); PG8_MMA(1, 1, At, B1); PG8_BAR; PG8_SCHED;
;             PG8_LDB(B0, 1, 0); PG8_LDB(B1, 1, 1); PG8_SCHED; PG8_LDA(At, 1, 0); PG8_STAGE(PG8_SA(0, 1), a2 + hstepA, voffA);
;             PG8_WAIT_V(8); PG8_WAIT_L(0); PG8_BAR; PG8_MMA(0, 0, At, B0); PG8_MMA(0, 1, At, B1); PG8_BAR; PG8_SCHED;
	v_mfma_f32_16x16x32_bf16 v[60:63], v[128:131], v[202:205], v[60:63]
	v_mfma_f32_16x16x32_bf16 v[56:59], v[136:139], v[202:205], v[56:59]
	v_mfma_f32_16x16x32_bf16 v[52:55], v[128:131], v[210:213], v[52:55]
	v_mfma_f32_16x16x32_bf16 v[48:51], v[136:139], v[210:213], v[48:51]
	v_mfma_f32_16x16x32_bf16 v[44:47], v[128:131], v[218:221], v[44:47]
	v_mfma_f32_16x16x32_bf16 v[40:43], v[136:139], v[218:221], v[40:43]
	v_mfma_f32_16x16x32_bf16 v[36:39], v[128:131], v[226:229], v[36:39]
	v_mfma_f32_16x16x32_bf16 v[32:35], v[136:139], v[226:229], v[32:35]
	v_mfma_f32_16x16x32_bf16 v[60:63], v[132:135], v[206:209], v[60:63]
	v_mfma_f32_16x16x32_bf16 v[56:59], v[140:143], v[206:209], v[56:59]
	v_mfma_f32_16x16x32_bf16 v[52:55], v[132:135], v[214:217], v[52:55]
	v_mfma_f32_16x16x32_bf16 v[48:51], v[140:143], v[214:217], v[48:51]
	v_mfma_f32_16x16x32_bf16 v[44:47], v[132:135], v[222:225], v[44:47]
	v_mfma_f32_16x16x32_bf16 v[40:43], v[140:143], v[222:225], v[40:43]
	v_mfma_f32_16x16x32_bf16 v[36:39], v[132:135], v[230:233], v[36:39]
	v_mfma_f32_16x16x32_bf16 v[32:35], v[140:143], v[230:233], v[32:35]
	v_mfma_f32_16x16x32_bf16 v[28:31], v[174:177], v[202:205], v[28:31]
	v_mfma_f32_16x16x32_bf16 v[24:27], v[194:197], v[202:205], v[24:27]
	v_mfma_f32_16x16x32_bf16 v[20:23], v[174:177], v[210:213], v[20:23]
	v_mfma_f32_16x16x32_bf16 v[16:19], v[194:197], v[210:213], v[16:19]
	v_mfma_f32_16x16x32_bf16 v[12:15], v[174:177], v[218:221], v[12:15]
	v_mfma_f32_16x16x32_bf16 v[8:11], v[194:197], v[218:221], v[8:11]
	v_mfma_f32_16x16x32_bf16 v[4:7], v[174:177], v[226:229], v[4:7]
	v_mfma_f32_16x16x32_bf16 v[0:3], v[194:197], v[226:229], v[0:3]
	v_mfma_f32_16x16x32_bf16 v[28:31], v[190:193], v[206:209], v[28:31]
	v_mfma_f32_16x16x32_bf16 v[24:27], v[198:201], v[206:209], v[24:27]
	v_mfma_f32_16x16x32_bf16 v[20:23], v[190:193], v[214:217], v[20:23]
	v_mfma_f32_16x16x32_bf16 v[16:19], v[198:201], v[214:217], v[16:19]
	v_mfma_f32_16x16x32_bf16 v[12:15], v[190:193], v[222:225], v[12:15]
	v_mfma_f32_16x16x32_bf16 v[8:11], v[198:201], v[222:225], v[8:11]
	v_mfma_f32_16x16x32_bf16 v[4:7], v[190:193], v[230:233], v[4:7]
	v_mfma_f32_16x16x32_bf16 v[0:3], v[198:201], v[230:233], v[0:3]
	s_barrier
	s_setprio 0
	s_add_i32 s6, 0, 0x18000
	s_add_i32 s7, 0, 0x1c000
	v_add_u32_e32 v140, s6, v179
	v_add_u32_e32 v198, s7, v179
	ds_read_b128 v[128:131], v140
	ds_read_b128 v[132:135], v140 offset:1024
	ds_read_b128 v[136:139], v140 offset:2048
	ds_read_b128 v[140:143], v140 offset:3072
	ds_read_b128 v[174:177], v198
	ds_read_b128 v[190:193], v198 offset:1024
	ds_read_b128 v[194:197], v198 offset:2048
	ds_read_b128 v[198:201], v198 offset:3072
	s_add_u32 s4, vcc_lo, 0x80000
	s_addc_u32 s5, vcc_hi, 0
	s_mov_b32 m0, s96
	v_lshl_add_u64 v[240:241], s[4:5], 0, v[144:145]
	ds_read_b128 v[202:205], v181 offset:32768
	ds_read_b128 v[206:209], v181 offset:33792
	ds_read_b128 v[210:213], v181 offset:34816
	ds_read_b128 v[214:217], v181 offset:35840
	ds_read_b128 v[218:221], v181 offset:36864
	ds_read_b128 v[222:225], v181 offset:37888
	ds_read_b128 v[226:229], v181 offset:38912
	ds_read_b128 v[230:233], v181 offset:39936
	global_load_lds_dwordx4 v[240:241], off
	v_lshl_add_u64 v[240:241], s[4:5], 0, v[148:149]
	s_mov_b32 m0, s97
	s_nop 0
	global_load_lds_dwordx4 v[240:241], off
	s_waitcnt vmcnt(8)
	s_waitcnt lgkmcnt(0)
	s_setprio 1
	s_barrier
	v_mfma_f32_16x16x32_bf16 v[124:127], v[128:131], v[202:205], v[124:127]
	v_mfma_f32_16x16x32_bf16 v[120:123], v[136:139], v[202:205], v[120:123]
	v_mfma_f32_16x16x32_bf16 v[116:119], v[128:131], v[210:213], v[116:119]
	v_mfma_f32_16x16x32_bf16 v[112:115], v[136:139], v[210:213], v[112:115]
	v_mfma_f32_16x16x32_bf16 v[108:111], v[128:131], v[218:221], v[108:111]
	v_mfma_f32_16x16x32_bf16 v[104:107], v[136:139], v[218:221], v[104:107]
	v_mfma_f32_16x16x32_bf16 v[100:103], v[128:131], v[226:229], v[100:103]
	v_mfma_f32_16x16x32_bf16 v[96:99], v[136:139], v[226:229], v[96:99]
	v_mfma_f32_16x16x32_bf16 v[124:127], v[132:135], v[206:209], v[124:127]
	v_mfma_f32_16x16x32_bf16 v[120:123], v[140:143], v[206:209], v[120:123]
	v_mfma_f32_16x16x32_bf16 v[116:119], v[132:135], v[214:217], v[116:119]
	v_mfma_f32_16x16x32_bf16 v[112:115], v[140:143], v[214:217], v[112:115]
	v_mfma_f32_16x16x32_bf16 v[108:111], v[132:135], v[222:225], v[108:111]
	v_mfma_f32_16x16x32_bf16 v[104:107], v[140:143], v[222:225], v[104:107]
	v_mfma_f32_16x16x32_bf16 v[100:103], v[132:135], v[230:233], v[100:103]
	v_mfma_f32_16x16x32_bf16 v[96:99], v[140:143], v[230:233], v[96:99]
	v_mfma_f32_16x16x32_bf16 v[92:95], v[174:177], v[202:205], v[92:95]
	v_mfma_f32_16x16x32_bf16 v[88:91], v[194:197], v[202:205], v[88:91]
	v_mfma_f32_16x16x32_bf16 v[84:87], v[174:177], v[210:213], v[84:87]
	v_mfma_f32_16x16x32_bf16 v[80:83], v[194:197], v[210:213], v[80:83]
	v_mfma_f32_16x16x32_bf16 v[76:79], v[174:177], v[218:221], v[76:79]
	v_mfma_f32_16x16x32_bf16 v[72:75], v[194:197], v[218:221], v[72:75]
	v_mfma_f32_16x16x32_bf16 v[68:71], v[174:177], v[226:229], v[68:71]
	v_mfma_f32_16x16x32_bf16 v[64:67], v[194:197], v[226:229], v[64:67]
	v_mfma_f32_16x16x32_bf16 v[92:95], v[190:193], v[206:209], v[92:95]
	v_mfma_f32_16x16x32_bf16 v[88:91], v[198:201], v[206:209], v[88:91]
	v_mfma_f32_16x16x32_bf16 v[84:87], v[190:193], v[214:217], v[84:87]
	v_mfma_f32_16x16x32_bf16 v[80:83], v[198:201], v[214:217], v[80:83]
	v_mfma_f32_16x16x32_bf16 v[76:79], v[190:193], v[222:225], v[76:79]
	v_mfma_f32_16x16x32_bf16 v[72:75], v[198:201], v[222:225], v[72:75]
	v_mfma_f32_16x16x32_bf16 v[68:71], v[190:193], v[230:233], v[68:71]
	v_mfma_f32_16x16x32_bf16 v[64:67], v[198:201], v[230:233], v[64:67]
	s_barrier
; #define PG8_STAGE(bufoff, gbase, voff) do { _Pragma("unroll") for (int _i = 0; _i < 2; ++_i) \
;         __builtin_amdgcn_global_load_lds((const unsigned*)((const char*)(gbase) + (voff)[_i]), (PG8_LAS unsigned*)(lds + (bufoff) + ldsw + _i * 8192), 16, 0, 0); } while (0)
; #define PG8_LDA(dst, b, h) do { _Pragma("unroll") for (int m = 0; m < 4; ++m) _Pragma("unroll") for (int k = 0; k < 2; ++k) dst[m][k] = *(const PG8_LAS bf16x8*)(lds + PG8_SA(b, h) + aoff + m * 2048 + k * 1024); } while (0)
; #define PG8_MMA(ai, bj, At, Bt) do { __builtin_amdgcn_s_setprio(1); _Pragma("unroll") for (int m = 0; m < 4; ++m) _Pragma("unroll") for (int n = 0; n < 2; ++n) _Pragma("unroll") for (int k = 0; k < 2; ++k) \
;         acc[ai][bj][m][n] = __builtin_amdgcn_mfma_f32_16x16x32_bf16(Bt[n][k], At[m][k], acc[ai][bj][m][n], 0, 0, 0); __builtin_amdgcn_s_setprio(0); } while (0)
; #define PG8_WAIT_V(n) asm volatile("s_waitcnt vmcnt(" #n ")" ::: "memory")
; #define PG8_WAIT_L(n) asm volatile("s_waitcnt lgkmcnt(" #n ")" ::: "memory")
; #define PG8_BAR __builtin_amdgcn_s_barrier()
; #define PG8_SCHED __builtin_amdgcn_sched_barrier(0)
; template <class Epi, class Sched, bool ALIGN_EPI = false, bool SP2 = false>
; __device__ __forceinline__ void gemm_phase(PG8_LAS unsigned char* lds, const Gemm g, const Sched& S, const Epi& E) {
;     ...
;         for (int t = 0; t < nt; t += 2) {
;     ...
;             PG8_LDA(At, 1, 1); PG8_STAGE(PG8_SB(1, 0), b3, voffB); PG8_STAGE(PG8_SB(1, 1), b3 + hstepB, voffB); PG8_STAGE(PG8_SA(1, 0), a3, voffA);
;             PG8_WAIT_V(8); PG8_WAIT_L(0); PG8_BAR; PG8_MMA(1, 0, At, B0); PG8_MMA(1, 1, At, B1); PG8_BAR; PG8_SCHED;
	s_setprio 0
	s_add_i32 s4, s6, s94
	v_lshl_add_u64 v[182:183], v[182:183], 0, s[70:71]
	s_mov_b32 m0, s4
	ds_read_b128 v[202:205], v181 offset:49152
	ds_read_b128 v[206:209], v181 offset:50176
	ds_read_b128 v[210:213], v181 offset:51200
	ds_read_b128 v[214:217], v181 offset:52224
	ds_read_b128 v[218:221], v181 offset:53248
	ds_read_b128 v[222:225], v181 offset:54272
	ds_read_b128 v[226:229], v181 offset:55296
	ds_read_b128 v[230:233], v181 offset:56320
	global_load_lds_dwordx4 v[182:183], off
	s_add_i32 m0, s4, 0x2000
	s_add_u32 s4, s76, 0x80080
	v_lshl_add_u64 v[182:183], v[234:235], 0, s[70:71]
	s_addc_u32 s5, s77, 0
	s_add_i32 s6, s7, s94
	global_load_lds_dwordx4 v[182:183], off
	v_lshl_add_u64 v[182:183], s[4:5], 0, v[146:147]
	s_mov_b32 m0, s6
	s_nop 0
	global_load_lds_dwordx4 v[182:183], off
	v_lshl_add_u64 v[182:183], s[4:5], 0, v[150:151]
	s_add_i32 m0, s6, 0x2000
	s_nop 0
	global_load_lds_dwordx4 v[182:183], off
	v_lshl_add_u64 v[182:183], v[236:237], 0, s[70:71]
	s_mov_b32 m0, s56
	s_nop 0
	global_load_lds_dwordx4 v[182:183], off
	v_lshl_add_u64 v[182:183], v[238:239], 0, s[70:71]
	s_mov_b32 m0, s57
	s_nop 0
	global_load_lds_dwordx4 v[182:183], off
	s_waitcnt vmcnt(8)
	s_waitcnt lgkmcnt(0)
	s_setprio 1
	s_barrier
	v_mfma_f32_16x16x32_bf16 v[60:63], v[128:131], v[202:205], v[60:63]
	v_mfma_f32_16x16x32_bf16 v[56:59], v[136:139], v[202:205], v[56:59]
	v_mfma_f32_16x16x32_bf16 v[52:55], v[128:131], v[210:213], v[52:55]
	v_mfma_f32_16x16x32_bf16 v[48:51], v[136:139], v[210:213], v[48:51]
	v_mfma_f32_16x16x32_bf16 v[44:47], v[128:131], v[218:221], v[44:47]
	v_mfma_f32_16x16x32_bf16 v[40:43], v[136:139], v[218:221], v[40:43]
	v_mfma_f32_16x16x32_bf16 v[36:39], v[128:131], v[226:229], v[36:39]
	v_mfma_f32_16x16x32_bf16 v[32:35], v[136:139], v[226:229], v[32:35]
	v_mfma_f32_16x16x32_bf16 v[60:63], v[132:135], v[206:209], v[60:63]
	v_mfma_f32_16x16x32_bf16 v[56:59], v[140:143], v[206:209], v[56:59]
	v_mfma_f32_16x16x32_bf16 v[52:55], v[132:135], v[214:217], v[52:55]
	v_mfma_f32_16x16x32_bf16 v[48:51], v[140:143], v[214:217], v[48:51]
	v_mfma_f32_16x16x32_bf16 v[44:47], v[132:135], v[222:225], v[44:47]
	v_mfma_f32_16x16x32_bf16 v[40:43], v[140:143], v[222:225], v[40:43]
	v_mfma_f32_16x16x32_bf16 v[36:39], v[132:135], v[230:233], v[36:39]
	v_mfma_f32_16x16x32_bf16 v[32:35], v[140:143], v[230:233], v[32:35]
	v_mfma_f32_16x16x32_bf16 v[28:31], v[174:177], v[202:205], v[28:31]
	v_mfma_f32_16x16x32_bf16 v[24:27], v[194:197], v[202:205], v[24:27]
	v_mfma_f32_16x16x32_bf16 v[20:23], v[174:177], v[210:213], v[20:23]
	v_mfma_f32_16x16x32_bf16 v[16:19], v[194:197], v[210:213], v[16:19]
	v_mfma_f32_16x16x32_bf16 v[12:15], v[174:177], v[218:221], v[12:15]
	v_mfma_f32_16x16x32_bf16 v[8:11], v[194:197], v[218:221], v[8:11]
	v_mfma_f32_16x16x32_bf16 v[4:7], v[174:177], v[226:229], v[4:7]
	v_mfma_f32_16x16x32_bf16 v[0:3], v[194:197], v[226:229], v[0:3]
	v_mfma_f32_16x16x32_bf16 v[28:31], v[190:193], v[206:209], v[28:31]
	v_mfma_f32_16x16x32_bf16 v[24:27], v[198:201], v[206:209], v[24:27]
	v_mfma_f32_16x16x32_bf16 v[20:23], v[190:193], v[214:217], v[20:23]
	v_mfma_f32_16x16x32_bf16 v[16:19], v[198:201], v[214:217], v[16:19]
	v_mfma_f32_16x16x32_bf16 v[12:15], v[190:193], v[222:225], v[12:15]
	v_mfma_f32_16x16x32_bf16 v[8:11], v[198:201], v[222:225], v[8:11]
	v_mfma_f32_16x16x32_bf16 v[4:7], v[190:193], v[230:233], v[4:7]
	v_mfma_f32_16x16x32_bf16 v[0:3], v[198:201], v[230:233], v[0:3]
	s_barrier
	s_setprio 0
	s_cmp_ge_i32 s66, s44
	s_cbranch_scc1 .LBB0_1066

; #define PG8_STAGE(bufoff, gbase, voff) do { _Pragma("unroll") for (int _i = 0; _i < 2; ++_i) \
;         __builtin_amdgcn_global_load_lds((const unsigned*)((const char*)(gbase) + (voff)[_i]), (PG8_LAS unsigned*)(lds + (bufoff) + ldsw + _i * 8192), 16, 0, 0); } while (0)
; #define PG8_LDA(dst, b, h) do { _Pragma("unroll") for (int m = 0; m < 4; ++m) _Pragma("unroll") for (int k = 0; k < 2; ++k) dst[m][k] = *(const PG8_LAS bf16x8*)(lds + PG8_SA(b, h) + aoff + m * 2048 + k * 1024); } while (0)
; #define PG8_LDB(dst, b, h) do { _Pragma("unroll") for (int n = 0; n < 2; ++n) _Pragma("unroll") for (int k = 0; k < 2; ++k) dst[n][k] = *(const PG8_LAS bf16x8*)(lds + PG8_SB(b, h) + boff + n * 2048 + k * 1024); } while (0)
; #define PG8_MMA(ai, bj, At, Bt) do { __builtin_amdgcn_s_setprio(1); _Pragma("unroll") for (int m = 0; m < 4; ++m) _Pragma("unroll") for (int n = 0; n < 2; ++n) _Pragma("unroll") for (int k = 0; k < 2; ++k) \
;         acc[ai][bj][m][n] = __builtin_amdgcn_mfma_f32_16x16x32_bf16(Bt[n][k], At[m][k], acc[ai][bj][m][n], 0, 0, 0); __builtin_amdgcn_s_setprio(0); } while (0)
; #define PG8_WAIT_V(n) asm volatile("s_waitcnt vmcnt(" #n ")" ::: "memory")
; #define PG8_WAIT_L(n) asm volatile("s_waitcnt lgkmcnt(" #n ")" ::: "memory")
; #define PG8_BAR __builtin_amdgcn_s_barrier()
; #define PG8_SCHED __builtin_amdgcn_sched_barrier(0)
; template <class Epi, class Sched, bool ALIGN_EPI = false, bool SP2 = false>
; __device__ __forceinline__ void gemm_phase(PG8_LAS unsigned char* lds, const Gemm g, const Sched& S, const Epi& E) {
;     ...
;             const char* a1 = cA + (size_t)(t + 1) * kstA;
;             const char* a2 = last ? nA : cA + (size_t)(t + 2) * kstA; const char* b2 = last ? nB : cB + (size_t)(t + 2) * kstep;
;             const char* a3 = a2 + kstA; const char* b3 = b2 + kstep;
;             if (last && has_next) S.a_ready(nxt);
;             if constexpr (SP2) {
;             PG8_LDB(B0, 0, 0); PG8_LDB(B1, 0, 1); PG8_SCHED; PG8_LDA(At, 0, 0); PG8_STAGE(PG8_SA(1, 1), a1 + hstepA, voffA);
;             PG8_WAIT_V(8); PG8_WAIT_L(0); PG8_BAR; PG8_MMA(0, 0, At, B0); PG8_MMA(0, 1, At, B1); PG8_BAR; PG8_SCHED;
;             PG8_LDA(At, 0, 1); PG8_STAGE(PG8_SB(0, 0), b2, voffB); PG8_STAGE(PG8_SB(0, 1), b2 + hstepB, voffB); PG8_STAGE(PG8_SA(0, 0), a2, voffA);
.LBB0_1307:
	ds_read_b128 v[156:159], v152
	ds_read_b128 v[160:163], v152 offset:1024
	ds_read_b128 v[164:167], v152 offset:2048
	ds_read_b128 v[168:171], v152 offset:3072
	ds_read_b128 v[172:175], v153
	ds_read_b128 v[176:179], v153 offset:1024
	ds_read_b128 v[180:183], v153 offset:2048
	ds_read_b128 v[190:193], v153 offset:3072
	s_add_u32 s52, s50, 0xfff80080
	s_addc_u32 s53, s51, -1
	s_cmp_eq_u32 s63, 28
	s_cselect_b32 s59, s4, s53
	s_cselect_b32 s58, s5, s52
	s_cselect_b32 s53, s12, s41
	s_cselect_b32 s52, s13, s39
	v_lshl_add_u64 v[226:227], s[50:51], 0, v[142:143]
	s_add_i32 m0, s7, 0xc000
	ds_read_b128 v[194:197], v154
	ds_read_b128 v[198:201], v154 offset:1024
	ds_read_b128 v[202:205], v154 offset:2048
	ds_read_b128 v[206:209], v154 offset:3072
	ds_read_b128 v[210:213], v154 offset:4096
	ds_read_b128 v[214:217], v154 offset:5120
	ds_read_b128 v[218:221], v154 offset:6144
	ds_read_b128 v[222:225], v154 offset:7168
	global_load_lds_dwordx4 v[226:227], off
	v_lshl_add_u64 v[226:227], s[50:51], 0, v[144:145]
	s_add_i32 m0, s7, 0xe000
	s_nop 0
	global_load_lds_dwordx4 v[226:227], off
	s_waitcnt vmcnt(8)
	s_waitcnt lgkmcnt(0)
	s_setprio 1
	s_barrier
	v_mfma_f32_16x16x32_bf16 v[124:127], v[156:159], v[194:197], v[124:127]
	v_mfma_f32_16x16x32_bf16 v[120:123], v[164:167], v[194:197], v[120:123]
	v_mfma_f32_16x16x32_bf16 v[108:111], v[156:159], v[202:205], v[108:111]
	v_mfma_f32_16x16x32_bf16 v[104:107], v[164:167], v[202:205], v[104:107]
	v_mfma_f32_16x16x32_bf16 v[92:95], v[156:159], v[210:213], v[92:95]
	v_mfma_f32_16x16x32_bf16 v[88:91], v[164:167], v[210:213], v[88:91]
	v_mfma_f32_16x16x32_bf16 v[76:79], v[156:159], v[218:221], v[76:79]
	v_mfma_f32_16x16x32_bf16 v[72:75], v[164:167], v[218:221], v[72:75]
	v_mfma_f32_16x16x32_bf16 v[124:127], v[160:163], v[198:201], v[124:127]
	v_mfma_f32_16x16x32_bf16 v[120:123], v[168:171], v[198:201], v[120:123]
	v_mfma_f32_16x16x32_bf16 v[108:111], v[160:163], v[206:209], v[108:111]
	v_mfma_f32_16x16x32_bf16 v[104:107], v[168:171], v[206:209], v[104:107]
	v_mfma_f32_16x16x32_bf16 v[92:95], v[160:163], v[214:217], v[92:95]
	v_mfma_f32_16x16x32_bf16 v[88:91], v[168:171], v[214:217], v[88:91]
	v_mfma_f32_16x16x32_bf16 v[76:79], v[160:163], v[222:225], v[76:79]
	v_mfma_f32_16x16x32_bf16 v[72:75], v[168:171], v[222:225], v[72:75]
	v_mfma_f32_16x16x32_bf16 v[116:119], v[172:175], v[194:197], v[116:119]
	v_mfma_f32_16x16x32_bf16 v[112:115], v[180:183], v[194:197], v[112:115]
	v_mfma_f32_16x16x32_bf16 v[100:103], v[172:175], v[202:205], v[100:103]
	v_mfma_f32_16x16x32_bf16 v[96:99], v[180:183], v[202:205], v[96:99]
	v_mfma_f32_16x16x32_bf16 v[84:87], v[172:175], v[210:213], v[84:87]
	v_mfma_f32_16x16x32_bf16 v[80:83], v[180:183], v[210:213], v[80:83]
	v_mfma_f32_16x16x32_bf16 v[68:71], v[172:175], v[218:221], v[68:71]
	v_mfma_f32_16x16x32_bf16 v[64:67], v[180:183], v[218:221], v[64:67]
	v_mfma_f32_16x16x32_bf16 v[116:119], v[176:179], v[198:201], v[116:119]
	v_mfma_f32_16x16x32_bf16 v[112:115], v[190:193], v[198:201], v[112:115]
	v_mfma_f32_16x16x32_bf16 v[100:103], v[176:179], v[206:209], v[100:103]
	v_mfma_f32_16x16x32_bf16 v[96:99], v[190:193], v[206:209], v[96:99]
	v_mfma_f32_16x16x32_bf16 v[84:87], v[176:179], v[214:217], v[84:87]
	v_mfma_f32_16x16x32_bf16 v[80:83], v[190:193], v[214:217], v[80:83]
	v_mfma_f32_16x16x32_bf16 v[68:71], v[176:179], v[222:225], v[68:71]
	v_mfma_f32_16x16x32_bf16 v[64:67], v[190:193], v[222:225], v[64:67]
	s_barrier
	s_setprio 0
	s_add_i32 s64, s57, s6
	v_lshl_add_u64 v[226:227], s[52:53], 0, v[130:131]
	s_mov_b32 m0, s64
	ds_read_b128 v[194:197], v154 offset:16384
	ds_read_b128 v[198:201], v154 offset:17408
	ds_read_b128 v[202:205], v154 offset:18432
	ds_read_b128 v[206:209], v154 offset:19456
	ds_read_b128 v[210:213], v154 offset:20480
	ds_read_b128 v[214:217], v154 offset:21504
	ds_read_b128 v[218:221], v154 offset:22528
	ds_read_b128 v[222:225], v154 offset:23552
	global_load_lds_dwordx4 v[226:227], off
	s_add_i32 m0, s64, 0x2000
	s_add_u32 s64, s52, 0x80000
	v_lshl_add_u64 v[228:229], s[52:53], 0, v[134:135]
	s_addc_u32 s65, s53, 0
	s_add_i32 s66, s61, s6
	global_load_lds_dwordx4 v[228:229], off
	v_lshl_add_u64 v[230:231], s[64:65], 0, v[130:131]
	s_mov_b32 m0, s66
	v_lshl_add_u64 v[232:233], s[58:59], 0, v[132:133]
	global_load_lds_dwordx4 v[230:231], off
	v_lshl_add_u64 v[230:231], s[64:65], 0, v[134:135]
	s_add_i32 m0, s66, 0x2000
	s_nop 0
	global_load_lds_dwordx4 v[230:231], off
	v_lshl_add_u64 v[230:231], s[58:59], 0, v[128:129]
	s_mov_b32 m0, s7
	s_nop 0
	global_load_lds_dwordx4 v[230:231], off
	s_mov_b32 m0, s8
	s_nop 0
	global_load_lds_dwordx4 v[232:233], off
	s_waitcnt vmcnt(8)
	s_waitcnt lgkmcnt(0)
	s_setprio 1
	s_barrier
; #define PG8_STAGE(bufoff, gbase, voff) do { _Pragma("unroll") for (int _i = 0; _i < 2; ++_i) \
;         __builtin_amdgcn_global_load_lds((const unsigned*)((const char*)(gbase) + (voff)[_i]), (PG8_LAS unsigned*)(lds + (bufoff) + ldsw + _i * 8192), 16, 0, 0); } while (0)
; #define PG8_LDA(dst, b, h) do { _Pragma("unroll") for (int m = 0; m < 4; ++m) _Pragma("unroll") for (int k = 0; k < 2; ++k) dst[m][k] = *(const PG8_LAS bf16x8*)(lds + PG8_SA(b, h) + aoff + m * 2048 + k * 1024); } while (0)
; #define PG8_LDB(dst, b, h) do { _Pragma("unroll") for (int n = 0; n < 2; ++n) _Pragma("unroll") for (int k = 0; k < 2; ++k) dst[n][k] = *(const PG8_LAS bf16x8*)(lds + PG8_SB(b, h) + boff + n * 2048 + k * 1024); } while (0)
; #define PG8_MMA(ai, bj, At, Bt) do { __builtin_amdgcn_s_setprio(1); _Pragma("unroll") for (int m = 0; m < 4; ++m) _Pragma("unroll") for (int n = 0; n < 2; ++n) _Pragma("unroll") for (int k = 0; k < 2; ++k) \
;         acc[ai][bj][m][n] = __builtin_amdgcn_mfma_f32_16x16x32_bf16(Bt[n][k], At[m][k], acc[ai][bj][m][n], 0, 0, 0); __builtin_amdgcn_s_setprio(0); } while (0)
; #define PG8_WAIT_V(n) asm volatile("s_waitcnt vmcnt(" #n ")" ::: "memory")
; #define PG8_WAIT_L(n) asm volatile("s_waitcnt lgkmcnt(" #n ")" ::: "memory")
; #define PG8_BAR __builtin_amdgcn_s_barrier()
; #define PG8_SCHED __builtin_amdgcn_sched_barrier(0)
; template <class Epi, class Sched, bool ALIGN_EPI = false, bool SP2 = false>
; __device__ __forceinline__ void gemm_phase(PG8_LAS unsigned char* lds, const Gemm g, const Sched& S, const Epi& E) {
;     ...
;             PG8_WAIT_V(8); PG8_WAIT_L(0); PG8_BAR; PG8_MMA(1, 0, At, B0); PG8_MMA(1, 1, At, B1); PG8_BAR; PG8_SCHED;
;             PG8_LDB(B0, 1, 0); PG8_LDB(B1, 1, 1); PG8_SCHED; PG8_LDA(At, 1, 0); PG8_STAGE(PG8_SA(0, 1), a2 + hstepA, voffA);
;             PG8_WAIT_V(8); PG8_WAIT_L(0); PG8_BAR; PG8_MMA(0, 0, At, B0); PG8_MMA(0, 1, At, B1); PG8_BAR; PG8_SCHED;
	v_mfma_f32_16x16x32_bf16 v[60:63], v[156:159], v[194:197], v[60:63]
	v_mfma_f32_16x16x32_bf16 v[56:59], v[164:167], v[194:197], v[56:59]
	v_mfma_f32_16x16x32_bf16 v[44:47], v[156:159], v[202:205], v[44:47]
	v_mfma_f32_16x16x32_bf16 v[40:43], v[164:167], v[202:205], v[40:43]
	v_mfma_f32_16x16x32_bf16 v[28:31], v[156:159], v[210:213], v[28:31]
	v_mfma_f32_16x16x32_bf16 v[24:27], v[164:167], v[210:213], v[24:27]
	v_mfma_f32_16x16x32_bf16 v[12:15], v[156:159], v[218:221], v[12:15]
	v_mfma_f32_16x16x32_bf16 v[8:11], v[164:167], v[218:221], v[8:11]
	v_mfma_f32_16x16x32_bf16 v[60:63], v[160:163], v[198:201], v[60:63]
	v_mfma_f32_16x16x32_bf16 v[56:59], v[168:171], v[198:201], v[56:59]
	v_mfma_f32_16x16x32_bf16 v[44:47], v[160:163], v[206:209], v[44:47]
	v_mfma_f32_16x16x32_bf16 v[40:43], v[168:171], v[206:209], v[40:43]
	v_mfma_f32_16x16x32_bf16 v[28:31], v[160:163], v[214:217], v[28:31]
	v_mfma_f32_16x16x32_bf16 v[24:27], v[168:171], v[214:217], v[24:27]
	v_mfma_f32_16x16x32_bf16 v[12:15], v[160:163], v[222:225], v[12:15]
	v_mfma_f32_16x16x32_bf16 v[8:11], v[168:171], v[222:225], v[8:11]
	v_mfma_f32_16x16x32_bf16 v[52:55], v[172:175], v[194:197], v[52:55]
	v_mfma_f32_16x16x32_bf16 v[48:51], v[180:183], v[194:197], v[48:51]
	v_mfma_f32_16x16x32_bf16 v[36:39], v[172:175], v[202:205], v[36:39]
	v_mfma_f32_16x16x32_bf16 v[32:35], v[180:183], v[202:205], v[32:35]
	v_mfma_f32_16x16x32_bf16 v[20:23], v[172:175], v[210:213], v[20:23]
	v_mfma_f32_16x16x32_bf16 v[16:19], v[180:183], v[210:213], v[16:19]
	v_mfma_f32_16x16x32_bf16 v[4:7], v[172:175], v[218:221], v[4:7]
	v_mfma_f32_16x16x32_bf16 v[0:3], v[180:183], v[218:221], v[0:3]
	v_mfma_f32_16x16x32_bf16 v[52:55], v[176:179], v[198:201], v[52:55]
	v_mfma_f32_16x16x32_bf16 v[48:51], v[190:193], v[198:201], v[48:51]
	v_mfma_f32_16x16x32_bf16 v[36:39], v[176:179], v[206:209], v[36:39]
	v_mfma_f32_16x16x32_bf16 v[32:35], v[190:193], v[206:209], v[32:35]
	v_mfma_f32_16x16x32_bf16 v[20:23], v[176:179], v[214:217], v[20:23]
	v_mfma_f32_16x16x32_bf16 v[16:19], v[190:193], v[214:217], v[16:19]
	v_mfma_f32_16x16x32_bf16 v[4:7], v[176:179], v[222:225], v[4:7]
	v_mfma_f32_16x16x32_bf16 v[0:3], v[190:193], v[222:225], v[0:3]
	s_barrier
	s_setprio 0
	s_add_i32 s64, 0, 0x18000
	v_add_u32_e32 v155, s64, v150
	s_add_i32 s65, 0, 0x1c000
	ds_read_b128 v[156:159], v155
	ds_read_b128 v[160:163], v155 offset:1024
	ds_read_b128 v[164:167], v155 offset:2048
	ds_read_b128 v[168:171], v155 offset:3072
	v_add_u32_e32 v155, s65, v150
	ds_read_b128 v[172:175], v155
	ds_read_b128 v[176:179], v155 offset:1024
	ds_read_b128 v[180:183], v155 offset:2048
	ds_read_b128 v[190:193], v155 offset:3072
	s_add_u32 s58, s58, 0x80000
	s_addc_u32 s59, s59, 0
	s_mov_b32 m0, s9
	v_lshl_add_u64 v[234:235], s[58:59], 0, v[128:129]
	ds_read_b128 v[194:197], v154 offset:32768
	ds_read_b128 v[198:201], v154 offset:33792
	ds_read_b128 v[202:205], v154 offset:34816
	ds_read_b128 v[206:209], v154 offset:35840
	ds_read_b128 v[210:213], v154 offset:36864
	ds_read_b128 v[214:217], v154 offset:37888
	ds_read_b128 v[218:221], v154 offset:38912
	ds_read_b128 v[222:225], v154 offset:39936
	global_load_lds_dwordx4 v[234:235], off
	v_lshl_add_u64 v[234:235], s[58:59], 0, v[132:133]
	s_mov_b32 m0, s11
	s_nop 0
	global_load_lds_dwordx4 v[234:235], off
	s_waitcnt vmcnt(8)
	s_waitcnt lgkmcnt(0)
	s_setprio 1
	s_barrier
	v_mfma_f32_16x16x32_bf16 v[124:127], v[156:159], v[194:197], v[124:127]
	v_mfma_f32_16x16x32_bf16 v[120:123], v[164:167], v[194:197], v[120:123]
	v_mfma_f32_16x16x32_bf16 v[108:111], v[156:159], v[202:205], v[108:111]
	v_mfma_f32_16x16x32_bf16 v[104:107], v[164:167], v[202:205], v[104:107]
	v_mfma_f32_16x16x32_bf16 v[92:95], v[156:159], v[210:213], v[92:95]
	v_mfma_f32_16x16x32_bf16 v[88:91], v[164:167], v[210:213], v[88:91]
	v_mfma_f32_16x16x32_bf16 v[76:79], v[156:159], v[218:221], v[76:79]
	v_mfma_f32_16x16x32_bf16 v[72:75], v[164:167], v[218:221], v[72:75]
	v_mfma_f32_16x16x32_bf16 v[124:127], v[160:163], v[198:201], v[124:127]
	v_mfma_f32_16x16x32_bf16 v[120:123], v[168:171], v[198:201], v[120:123]
	v_mfma_f32_16x16x32_bf16 v[108:111], v[160:163], v[206:209], v[108:111]
	v_mfma_f32_16x16x32_bf16 v[104:107], v[168:171], v[206:209], v[104:107]
	v_mfma_f32_16x16x32_bf16 v[92:95], v[160:163], v[214:217], v[92:95]
	v_mfma_f32_16x16x32_bf16 v[88:91], v[168:171], v[214:217], v[88:91]
	v_mfma_f32_16x16x32_bf16 v[76:79], v[160:163], v[222:225], v[76:79]
	v_mfma_f32_16x16x32_bf16 v[72:75], v[168:171], v[222:225], v[72:75]
	v_mfma_f32_16x16x32_bf16 v[116:119], v[172:175], v[194:197], v[116:119]
	v_mfma_f32_16x16x32_bf16 v[112:115], v[180:183], v[194:197], v[112:115]
	v_mfma_f32_16x16x32_bf16 v[100:103], v[172:175], v[202:205], v[100:103]
	v_mfma_f32_16x16x32_bf16 v[96:99], v[180:183], v[202:205], v[96:99]
	v_mfma_f32_16x16x32_bf16 v[84:87], v[172:175], v[210:213], v[84:87]
	v_mfma_f32_16x16x32_bf16 v[80:83], v[180:183], v[210:213], v[80:83]
	v_mfma_f32_16x16x32_bf16 v[68:71], v[172:175], v[218:221], v[68:71]
	v_mfma_f32_16x16x32_bf16 v[64:67], v[180:183], v[218:221], v[64:67]
	v_mfma_f32_16x16x32_bf16 v[116:119], v[176:179], v[198:201], v[116:119]
	v_mfma_f32_16x16x32_bf16 v[112:115], v[190:193], v[198:201], v[112:115]
	v_mfma_f32_16x16x32_bf16 v[100:103], v[176:179], v[206:209], v[100:103]
	v_mfma_f32_16x16x32_bf16 v[96:99], v[190:193], v[206:209], v[96:99]
	v_mfma_f32_16x16x32_bf16 v[84:87], v[176:179], v[214:217], v[84:87]
	v_mfma_f32_16x16x32_bf16 v[80:83], v[190:193], v[214:217], v[80:83]
	v_mfma_f32_16x16x32_bf16 v[68:71], v[176:179], v[222:225], v[68:71]
	v_mfma_f32_16x16x32_bf16 v[64:67], v[190:193], v[222:225], v[64:67]
	s_barrier
; #define PG8_STAGE(bufoff, gbase, voff) do { _Pragma("unroll") for (int _i = 0; _i < 2; ++_i) \
;         __builtin_amdgcn_global_load_lds((const unsigned*)((const char*)(gbase) + (voff)[_i]), (PG8_LAS unsigned*)(lds + (bufoff) + ldsw + _i * 8192), 16, 0, 0); } while (0)
; #define PG8_LDA(dst, b, h) do { _Pragma("unroll") for (int m = 0; m < 4; ++m) _Pragma("unroll") for (int k = 0; k < 2; ++k) dst[m][k] = *(const PG8_LAS bf16x8*)(lds + PG8_SA(b, h) + aoff + m * 2048 + k * 1024); } while (0)
; #define PG8_MMA(ai, bj, At, Bt) do { __builtin_amdgcn_s_setprio(1); _Pragma("unroll") for (int m = 0; m < 4; ++m) _Pragma("unroll") for (int n = 0; n < 2; ++n) _Pragma("unroll") for (int k = 0; k < 2; ++k) \
;         acc[ai][bj][m][n] = __builtin_amdgcn_mfma_f32_16x16x32_bf16(Bt[n][k], At[m][k], acc[ai][bj][m][n], 0, 0, 0); __builtin_amdgcn_s_setprio(0); } while (0)
; #define PG8_WAIT_V(n) asm volatile("s_waitcnt vmcnt(" #n ")" ::: "memory")
; #define PG8_WAIT_L(n) asm volatile("s_waitcnt lgkmcnt(" #n ")" ::: "memory")
; #define PG8_BAR __builtin_amdgcn_s_barrier()
; #define PG8_SCHED __builtin_amdgcn_sched_barrier(0)
; template <class Epi, class Sched, bool ALIGN_EPI = false, bool SP2 = false>
; __device__ __forceinline__ void gemm_phase(PG8_LAS unsigned char* lds, const Gemm g, const Sched& S, const Epi& E) {
;     ...
;         for (int t = 0; t < nt; t += 2) {
;     ...
;             PG8_LDA(At, 1, 1); PG8_STAGE(PG8_SB(1, 0), b3, voffB); PG8_STAGE(PG8_SB(1, 1), b3 + hstepB, voffB); PG8_STAGE(PG8_SA(1, 0), a3, voffA);
;             PG8_WAIT_V(8); PG8_WAIT_L(0); PG8_BAR; PG8_MMA(1, 0, At, B0); PG8_MMA(1, 1, At, B1); PG8_BAR; PG8_SCHED;
	s_setprio 0
	s_add_i32 s58, s64, s6
	v_lshl_add_u64 v[226:227], v[226:227], 0, s[20:21]
	s_mov_b32 m0, s58
	ds_read_b128 v[194:197], v154 offset:49152
	ds_read_b128 v[198:201], v154 offset:50176
	ds_read_b128 v[202:205], v154 offset:51200
	ds_read_b128 v[206:209], v154 offset:52224
	ds_read_b128 v[210:213], v154 offset:53248
	ds_read_b128 v[214:217], v154 offset:54272
	ds_read_b128 v[218:221], v154 offset:55296
	ds_read_b128 v[222:225], v154 offset:56320
	global_load_lds_dwordx4 v[226:227], off
	s_add_i32 m0, s58, 0x2000
	s_add_u32 s52, s52, 0x80080
	v_lshl_add_u64 v[226:227], v[228:229], 0, s[20:21]
	s_addc_u32 s53, s53, 0
	s_add_i32 s58, s65, s6
	global_load_lds_dwordx4 v[226:227], off
	v_lshl_add_u64 v[226:227], s[52:53], 0, v[130:131]
	s_mov_b32 m0, s58
	s_nop 0
	global_load_lds_dwordx4 v[226:227], off
	v_lshl_add_u64 v[226:227], s[52:53], 0, v[134:135]
	s_add_i32 m0, s58, 0x2000
	s_nop 0
	global_load_lds_dwordx4 v[226:227], off
	v_lshl_add_u64 v[226:227], v[230:231], 0, s[20:21]
	s_mov_b32 m0, s55
	s_nop 0
	global_load_lds_dwordx4 v[226:227], off
	v_lshl_add_u64 v[226:227], v[232:233], 0, s[20:21]
	s_mov_b32 m0, s56
	s_nop 0
	global_load_lds_dwordx4 v[226:227], off
	s_waitcnt vmcnt(8)
	s_waitcnt lgkmcnt(0)
	s_setprio 1
	s_barrier
	v_mfma_f32_16x16x32_bf16 v[60:63], v[156:159], v[194:197], v[60:63]
	v_mfma_f32_16x16x32_bf16 v[56:59], v[164:167], v[194:197], v[56:59]
	v_mfma_f32_16x16x32_bf16 v[44:47], v[156:159], v[202:205], v[44:47]
	v_mfma_f32_16x16x32_bf16 v[40:43], v[164:167], v[202:205], v[40:43]
	v_mfma_f32_16x16x32_bf16 v[28:31], v[156:159], v[210:213], v[28:31]
	v_mfma_f32_16x16x32_bf16 v[24:27], v[164:167], v[210:213], v[24:27]
	v_mfma_f32_16x16x32_bf16 v[12:15], v[156:159], v[218:221], v[12:15]
	v_mfma_f32_16x16x32_bf16 v[8:11], v[164:167], v[218:221], v[8:11]
	v_mfma_f32_16x16x32_bf16 v[60:63], v[160:163], v[198:201], v[60:63]
	v_mfma_f32_16x16x32_bf16 v[56:59], v[168:171], v[198:201], v[56:59]
	v_mfma_f32_16x16x32_bf16 v[44:47], v[160:163], v[206:209], v[44:47]
	v_mfma_f32_16x16x32_bf16 v[40:43], v[168:171], v[206:209], v[40:43]
	v_mfma_f32_16x16x32_bf16 v[28:31], v[160:163], v[214:217], v[28:31]
	v_mfma_f32_16x16x32_bf16 v[24:27], v[168:171], v[214:217], v[24:27]
	v_mfma_f32_16x16x32_bf16 v[12:15], v[160:163], v[222:225], v[12:15]
	v_mfma_f32_16x16x32_bf16 v[8:11], v[168:171], v[222:225], v[8:11]
	v_mfma_f32_16x16x32_bf16 v[52:55], v[172:175], v[194:197], v[52:55]
	v_mfma_f32_16x16x32_bf16 v[48:51], v[180:183], v[194:197], v[48:51]
	v_mfma_f32_16x16x32_bf16 v[36:39], v[172:175], v[202:205], v[36:39]
	v_mfma_f32_16x16x32_bf16 v[32:35], v[180:183], v[202:205], v[32:35]
	v_mfma_f32_16x16x32_bf16 v[20:23], v[172:175], v[210:213], v[20:23]
	v_mfma_f32_16x16x32_bf16 v[16:19], v[180:183], v[210:213], v[16:19]
	v_mfma_f32_16x16x32_bf16 v[4:7], v[172:175], v[218:221], v[4:7]
	v_mfma_f32_16x16x32_bf16 v[0:3], v[180:183], v[218:221], v[0:3]
	v_mfma_f32_16x16x32_bf16 v[52:55], v[176:179], v[198:201], v[52:55]
	v_mfma_f32_16x16x32_bf16 v[48:51], v[190:193], v[198:201], v[48:51]
	v_mfma_f32_16x16x32_bf16 v[36:39], v[176:179], v[206:209], v[36:39]
	v_mfma_f32_16x16x32_bf16 v[32:35], v[190:193], v[206:209], v[32:35]
	v_mfma_f32_16x16x32_bf16 v[20:23], v[176:179], v[214:217], v[20:23]
	v_mfma_f32_16x16x32_bf16 v[16:19], v[190:193], v[214:217], v[16:19]
	v_mfma_f32_16x16x32_bf16 v[4:7], v[176:179], v[222:225], v[4:7]
	v_mfma_f32_16x16x32_bf16 v[0:3], v[190:193], v[222:225], v[0:3]
	s_barrier
	s_setprio 0
	s_add_i32 s63, s63, 2
	s_add_u32 s50, s50, 0x100
	s_addc_u32 s51, s51, 0
	s_add_u32 s39, s39, 0x100
	s_addc_u32 s41, s41, 0
	s_cmp_gt_u32 s63, 29
	s_cbranch_scc0 .LBB0_1307
	s_and_b64 vcc, exec, s[34:35]
	s_cbranch_vccz .LBB0_1310
	s_barrier

; #define PG8_STAGE(bufoff, gbase, voff) do { _Pragma("unroll") for (int _i = 0; _i < 2; ++_i) \
;         __builtin_amdgcn_global_load_lds((const unsigned*)((const char*)(gbase) + (voff)[_i]), (PG8_LAS unsigned*)(lds + (bufoff) + ldsw + _i * 8192), 16, 0, 0); } while (0)
; #define PG8_LDA(dst, b, h) do { _Pragma("unroll") for (int m = 0; m < 4; ++m) _Pragma("unroll") for (int k = 0; k < 2; ++k) dst[m][k] = *(const PG8_LAS bf16x8*)(lds + PG8_SA(b, h) + aoff + m * 2048 + k * 1024); } while (0)
; #define PG8_LDB(dst, b, h) do { _Pragma("unroll") for (int n = 0; n < 2; ++n) _Pragma("unroll") for (int k = 0; k < 2; ++k) dst[n][k] = *(const PG8_LAS bf16x8*)(lds + PG8_SB(b, h) + boff + n * 2048 + k * 1024); } while (0)
; #define PG8_MMA(ai, bj, At, Bt) do { __builtin_amdgcn_s_setprio(1); _Pragma("unroll") for (int m = 0; m < 4; ++m) _Pragma("unroll") for (int n = 0; n < 2; ++n) _Pragma("unroll") for (int k = 0; k < 2; ++k) \
;         acc[ai][bj][m][n] = __builtin_amdgcn_mfma_f32_16x16x32_bf16(Bt[n][k], At[m][k], acc[ai][bj][m][n], 0, 0, 0); __builtin_amdgcn_s_setprio(0); } while (0)
; #define PG8_WAIT_V(n) asm volatile("s_waitcnt vmcnt(" #n ")" ::: "memory")
; #define PG8_WAIT_L(n) asm volatile("s_waitcnt lgkmcnt(" #n ")" ::: "memory")
; #define PG8_BAR __builtin_amdgcn_s_barrier()
; #define PG8_SCHED __builtin_amdgcn_sched_barrier(0)
; template <class Epi, class Sched, bool ALIGN_EPI = false, bool SP2 = false>
; __device__ __forceinline__ void gemm_phase(PG8_LAS unsigned char* lds, const Gemm g, const Sched& S, const Epi& E) {
;     ...
;             const char* a1 = cA + (size_t)(t + 1) * kstA;
;             const char* a2 = last ? nA : cA + (size_t)(t + 2) * kstA; const char* b2 = last ? nB : cB + (size_t)(t + 2) * kstep;
;             const char* a3 = a2 + kstA; const char* b3 = b2 + kstep;
;             if (last && has_next) S.a_ready(nxt);
;             if constexpr (SP2) {
;             PG8_LDB(B0, 0, 0); PG8_LDB(B1, 0, 1); PG8_SCHED; PG8_LDA(At, 0, 0); PG8_STAGE(PG8_SA(1, 1), a1 + hstepA, voffA);
;             PG8_WAIT_V(8); PG8_WAIT_L(0); PG8_BAR; PG8_MMA(0, 0, At, B0); PG8_MMA(0, 1, At, B1); PG8_BAR; PG8_SCHED;
;             PG8_LDA(At, 0, 1); PG8_STAGE(PG8_SB(0, 0), b2, voffB); PG8_STAGE(PG8_SB(0, 1), b2 + hstepB, voffB); PG8_STAGE(PG8_SA(0, 0), a2, voffA);
.LBB0_1404:
	s_or_b32 s48, s68, 1
	s_add_i32 s68, s68, 2
	s_mov_b32 s69, s49
	s_lshl_b64 s[4:5], s[48:49], 15
	s_lshl_b64 s[6:7], s[68:69], 15
	s_add_u32 s12, s34, s6
	v_add_u32_e32 v170, s10, v177
	v_add_u32_e32 v174, s11, v177
	s_addc_u32 s13, s35, s7
	ds_read_b128 v[158:161], v170
	ds_read_b128 v[162:165], v170 offset:1024
	ds_read_b128 v[166:169], v170 offset:2048
	ds_read_b128 v[170:173], v170 offset:3072
	ds_read_b128 v[180:183], v174
	ds_read_b128 v[190:193], v174 offset:1024
	ds_read_b128 v[194:197], v174 offset:2048
	ds_read_b128 v[198:201], v174 offset:3072
	s_and_b64 s[6:7], s[50:51], exec
	s_cselect_b32 s59, s13, s61
	s_cselect_b32 s58, s12, s60
	s_lshl_b64 s[6:7], s[68:69], 7
	s_add_u32 s12, s40, s6
	s_addc_u32 s13, s41, s7
	s_and_b64 s[6:7], s[50:51], exec
	s_cselect_b32 s53, s13, s63
	s_cselect_b32 s52, s12, s62
	s_add_u32 s50, s58, 0x8000
	s_addc_u32 s51, s59, 0
	s_add_u32 s4, s21, s4
	s_addc_u32 s5, s39, s5
	v_lshl_add_u64 v[174:175], s[4:5], 0, v[128:129]
	s_add_i32 m0, s74, 0xc000
	ds_read_b128 v[202:205], v179
	ds_read_b128 v[206:209], v179 offset:1024
	ds_read_b128 v[210:213], v179 offset:2048
	ds_read_b128 v[214:217], v179 offset:3072
	ds_read_b128 v[218:221], v179 offset:4096
	ds_read_b128 v[222:225], v179 offset:5120
	ds_read_b128 v[226:229], v179 offset:6144
	ds_read_b128 v[230:233], v179 offset:7168
	global_load_lds_dwordx4 v[174:175], off
	v_lshl_add_u64 v[174:175], s[4:5], 0, v[132:133]
	s_add_i32 m0, s74, 0xe000
	s_nop 0
	global_load_lds_dwordx4 v[174:175], off
	s_waitcnt vmcnt(8)
	s_waitcnt lgkmcnt(0)
	s_setprio 1
	s_barrier
	v_mfma_f32_16x16x32_bf16 v[124:127], v[158:161], v[202:205], v[124:127]
	v_mfma_f32_16x16x32_bf16 v[120:123], v[166:169], v[202:205], v[120:123]
	v_mfma_f32_16x16x32_bf16 v[116:119], v[158:161], v[210:213], v[116:119]
	v_mfma_f32_16x16x32_bf16 v[112:115], v[166:169], v[210:213], v[112:115]
	v_mfma_f32_16x16x32_bf16 v[108:111], v[158:161], v[218:221], v[108:111]
	v_mfma_f32_16x16x32_bf16 v[104:107], v[166:169], v[218:221], v[104:107]
	v_mfma_f32_16x16x32_bf16 v[100:103], v[158:161], v[226:229], v[100:103]
	v_mfma_f32_16x16x32_bf16 v[96:99], v[166:169], v[226:229], v[96:99]
	v_mfma_f32_16x16x32_bf16 v[124:127], v[162:165], v[206:209], v[124:127]
	v_mfma_f32_16x16x32_bf16 v[120:123], v[170:173], v[206:209], v[120:123]
	v_mfma_f32_16x16x32_bf16 v[116:119], v[162:165], v[214:217], v[116:119]
	v_mfma_f32_16x16x32_bf16 v[112:115], v[170:173], v[214:217], v[112:115]
	v_mfma_f32_16x16x32_bf16 v[108:111], v[162:165], v[222:225], v[108:111]
	v_mfma_f32_16x16x32_bf16 v[104:107], v[170:173], v[222:225], v[104:107]
	v_mfma_f32_16x16x32_bf16 v[100:103], v[162:165], v[230:233], v[100:103]
	v_mfma_f32_16x16x32_bf16 v[96:99], v[170:173], v[230:233], v[96:99]
	v_mfma_f32_16x16x32_bf16 v[92:95], v[180:183], v[202:205], v[92:95]
	v_mfma_f32_16x16x32_bf16 v[88:91], v[194:197], v[202:205], v[88:91]
	v_mfma_f32_16x16x32_bf16 v[84:87], v[180:183], v[210:213], v[84:87]
	v_mfma_f32_16x16x32_bf16 v[80:83], v[194:197], v[210:213], v[80:83]
	v_mfma_f32_16x16x32_bf16 v[76:79], v[180:183], v[218:221], v[76:79]
	v_mfma_f32_16x16x32_bf16 v[72:75], v[194:197], v[218:221], v[72:75]
	v_mfma_f32_16x16x32_bf16 v[68:71], v[180:183], v[226:229], v[68:71]
	v_mfma_f32_16x16x32_bf16 v[64:67], v[194:197], v[226:229], v[64:67]
	v_mfma_f32_16x16x32_bf16 v[92:95], v[190:193], v[206:209], v[92:95]
	v_mfma_f32_16x16x32_bf16 v[88:91], v[198:201], v[206:209], v[88:91]
	v_mfma_f32_16x16x32_bf16 v[84:87], v[190:193], v[214:217], v[84:87]
	v_mfma_f32_16x16x32_bf16 v[80:83], v[198:201], v[214:217], v[80:83]
	v_mfma_f32_16x16x32_bf16 v[76:79], v[190:193], v[222:225], v[76:79]
	v_mfma_f32_16x16x32_bf16 v[72:75], v[198:201], v[222:225], v[72:75]
	v_mfma_f32_16x16x32_bf16 v[68:71], v[190:193], v[230:233], v[68:71]
	v_mfma_f32_16x16x32_bf16 v[64:67], v[198:201], v[230:233], v[64:67]
	s_barrier
	s_setprio 0
	s_add_i32 s4, s10, s77
	v_lshl_add_u64 v[174:175], s[52:53], 0, v[130:131]
	s_mov_b32 m0, s4
	ds_read_b128 v[202:205], v179 offset:16384
	ds_read_b128 v[206:209], v179 offset:17408
	ds_read_b128 v[210:213], v179 offset:18432
	ds_read_b128 v[214:217], v179 offset:19456
	ds_read_b128 v[218:221], v179 offset:20480
	ds_read_b128 v[222:225], v179 offset:21504
	ds_read_b128 v[226:229], v179 offset:22528
	ds_read_b128 v[230:233], v179 offset:23552
	global_load_lds_dwordx4 v[174:175], off
	s_add_i32 m0, s4, 0x2000
	s_add_u32 s4, s52, 0x160000
	v_lshl_add_u64 v[234:235], s[52:53], 0, v[134:135]
	s_addc_u32 s5, s53, 0
	s_add_i32 s6, s11, s77
	global_load_lds_dwordx4 v[234:235], off
	v_lshl_add_u64 v[236:237], s[4:5], 0, v[130:131]
	s_mov_b32 m0, s6
	s_nop 0
	global_load_lds_dwordx4 v[236:237], off
	v_lshl_add_u64 v[236:237], s[4:5], 0, v[134:135]
	s_add_i32 m0, s6, 0x2000
	s_nop 0
	global_load_lds_dwordx4 v[236:237], off
	v_lshl_add_u64 v[236:237], s[58:59], 0, v[128:129]
	s_mov_b32 m0, s74
	s_nop 0
	global_load_lds_dwordx4 v[236:237], off
	v_lshl_add_u64 v[236:237], s[58:59], 0, v[132:133]
	s_mov_b32 m0, s96
	s_nop 0
	global_load_lds_dwordx4 v[236:237], off
	s_waitcnt vmcnt(8)
	s_waitcnt lgkmcnt(0)
	s_setprio 1
	s_barrier
; #define PG8_STAGE(bufoff, gbase, voff) do { _Pragma("unroll") for (int _i = 0; _i < 2; ++_i) \
;         __builtin_amdgcn_global_load_lds((const unsigned*)((const char*)(gbase) + (voff)[_i]), (PG8_LAS unsigned*)(lds + (bufoff) + ldsw + _i * 8192), 16, 0, 0); } while (0)
; #define PG8_LDA(dst, b, h) do { _Pragma("unroll") for (int m = 0; m < 4; ++m) _Pragma("unroll") for (int k = 0; k < 2; ++k) dst[m][k] = *(const PG8_LAS bf16x8*)(lds + PG8_SA(b, h) + aoff + m * 2048 + k * 1024); } while (0)
; #define PG8_LDB(dst, b, h) do { _Pragma("unroll") for (int n = 0; n < 2; ++n) _Pragma("unroll") for (int k = 0; k < 2; ++k) dst[n][k] = *(const PG8_LAS bf16x8*)(lds + PG8_SB(b, h) + boff + n * 2048 + k * 1024); } while (0)
; #define PG8_MMA(ai, bj, At, Bt) do { __builtin_amdgcn_s_setprio(1); _Pragma("unroll") for (int m = 0; m < 4; ++m) _Pragma("unroll") for (int n = 0; n < 2; ++n) _Pragma("unroll") for (int k = 0; k < 2; ++k) \
;         acc[ai][bj][m][n] = __builtin_amdgcn_mfma_f32_16x16x32_bf16(Bt[n][k], At[m][k], acc[ai][bj][m][n], 0, 0, 0); __builtin_amdgcn_s_setprio(0); } while (0)
; #define PG8_WAIT_V(n) asm volatile("s_waitcnt vmcnt(" #n ")" ::: "memory")
; #define PG8_WAIT_L(n) asm volatile("s_waitcnt lgkmcnt(" #n ")" ::: "memory")
; #define PG8_BAR __builtin_amdgcn_s_barrier()
; #define PG8_SCHED __builtin_amdgcn_sched_barrier(0)
; template <class Epi, class Sched, bool ALIGN_EPI = false, bool SP2 = false>
; __device__ __forceinline__ void gemm_phase(PG8_LAS unsigned char* lds, const Gemm g, const Sched& S, const Epi& E) {
;     ...
;             PG8_WAIT_V(8); PG8_WAIT_L(0); PG8_BAR; PG8_MMA(1, 0, At, B0); PG8_MMA(1, 1, At, B1); PG8_BAR; PG8_SCHED;
;             PG8_LDB(B0, 1, 0); PG8_LDB(B1, 1, 1); PG8_SCHED; PG8_LDA(At, 1, 0); PG8_STAGE(PG8_SA(0, 1), a2 + hstepA, voffA);
;             PG8_WAIT_V(8); PG8_WAIT_L(0); PG8_BAR; PG8_MMA(0, 0, At, B0); PG8_MMA(0, 1, At, B1); PG8_BAR; PG8_SCHED;
	v_mfma_f32_16x16x32_bf16 v[60:63], v[158:161], v[202:205], v[60:63]
	v_mfma_f32_16x16x32_bf16 v[56:59], v[166:169], v[202:205], v[56:59]
	v_mfma_f32_16x16x32_bf16 v[52:55], v[158:161], v[210:213], v[52:55]
	v_mfma_f32_16x16x32_bf16 v[48:51], v[166:169], v[210:213], v[48:51]
	v_mfma_f32_16x16x32_bf16 v[44:47], v[158:161], v[218:221], v[44:47]
	v_mfma_f32_16x16x32_bf16 v[40:43], v[166:169], v[218:221], v[40:43]
	v_mfma_f32_16x16x32_bf16 v[36:39], v[158:161], v[226:229], v[36:39]
	v_mfma_f32_16x16x32_bf16 v[32:35], v[166:169], v[226:229], v[32:35]
	v_mfma_f32_16x16x32_bf16 v[60:63], v[162:165], v[206:209], v[60:63]
	v_mfma_f32_16x16x32_bf16 v[56:59], v[170:173], v[206:209], v[56:59]
	v_mfma_f32_16x16x32_bf16 v[52:55], v[162:165], v[214:217], v[52:55]
	v_mfma_f32_16x16x32_bf16 v[48:51], v[170:173], v[214:217], v[48:51]
	v_mfma_f32_16x16x32_bf16 v[44:47], v[162:165], v[222:225], v[44:47]
	v_mfma_f32_16x16x32_bf16 v[40:43], v[170:173], v[222:225], v[40:43]
	v_mfma_f32_16x16x32_bf16 v[36:39], v[162:165], v[230:233], v[36:39]
	v_mfma_f32_16x16x32_bf16 v[32:35], v[170:173], v[230:233], v[32:35]
	v_mfma_f32_16x16x32_bf16 v[28:31], v[180:183], v[202:205], v[28:31]
	v_mfma_f32_16x16x32_bf16 v[24:27], v[194:197], v[202:205], v[24:27]
	v_mfma_f32_16x16x32_bf16 v[20:23], v[180:183], v[210:213], v[20:23]
	v_mfma_f32_16x16x32_bf16 v[16:19], v[194:197], v[210:213], v[16:19]
	v_mfma_f32_16x16x32_bf16 v[12:15], v[180:183], v[218:221], v[12:15]
	v_mfma_f32_16x16x32_bf16 v[8:11], v[194:197], v[218:221], v[8:11]
	v_mfma_f32_16x16x32_bf16 v[4:7], v[180:183], v[226:229], v[4:7]
	v_mfma_f32_16x16x32_bf16 v[0:3], v[194:197], v[226:229], v[0:3]
	v_mfma_f32_16x16x32_bf16 v[28:31], v[190:193], v[206:209], v[28:31]
	v_mfma_f32_16x16x32_bf16 v[24:27], v[198:201], v[206:209], v[24:27]
	v_mfma_f32_16x16x32_bf16 v[20:23], v[190:193], v[214:217], v[20:23]
	v_mfma_f32_16x16x32_bf16 v[16:19], v[198:201], v[214:217], v[16:19]
	v_mfma_f32_16x16x32_bf16 v[12:15], v[190:193], v[222:225], v[12:15]
	v_mfma_f32_16x16x32_bf16 v[8:11], v[198:201], v[222:225], v[8:11]
	v_mfma_f32_16x16x32_bf16 v[4:7], v[190:193], v[230:233], v[4:7]
	v_mfma_f32_16x16x32_bf16 v[0:3], v[198:201], v[230:233], v[0:3]
	s_barrier
	s_setprio 0
	s_add_i32 s6, 0, 0x18000
	s_add_i32 s7, 0, 0x1c000
	v_add_u32_e32 v170, s6, v177
	v_add_u32_e32 v198, s7, v177
	ds_read_b128 v[158:161], v170
	ds_read_b128 v[162:165], v170 offset:1024
	ds_read_b128 v[166:169], v170 offset:2048
	ds_read_b128 v[170:173], v170 offset:3072
	ds_read_b128 v[180:183], v198
	ds_read_b128 v[190:193], v198 offset:1024
	ds_read_b128 v[194:197], v198 offset:2048
	ds_read_b128 v[198:201], v198 offset:3072
	s_add_u32 s4, s58, 0x4000
	s_addc_u32 s5, s59, 0
	s_mov_b32 m0, s97
	v_lshl_add_u64 v[236:237], s[4:5], 0, v[128:129]
	ds_read_b128 v[202:205], v179 offset:32768
	ds_read_b128 v[206:209], v179 offset:33792
	ds_read_b128 v[210:213], v179 offset:34816
	ds_read_b128 v[214:217], v179 offset:35840
	ds_read_b128 v[218:221], v179 offset:36864
	ds_read_b128 v[222:225], v179 offset:37888
	ds_read_b128 v[226:229], v179 offset:38912
	ds_read_b128 v[230:233], v179 offset:39936
	global_load_lds_dwordx4 v[236:237], off
	v_lshl_add_u64 v[236:237], s[4:5], 0, v[132:133]
	s_mov_b32 m0, s75
	s_nop 0
	global_load_lds_dwordx4 v[236:237], off
	s_waitcnt vmcnt(8)
	s_waitcnt lgkmcnt(0)
	s_setprio 1
	s_barrier
	v_mfma_f32_16x16x32_bf16 v[124:127], v[158:161], v[202:205], v[124:127]
	v_mfma_f32_16x16x32_bf16 v[120:123], v[166:169], v[202:205], v[120:123]
	v_mfma_f32_16x16x32_bf16 v[116:119], v[158:161], v[210:213], v[116:119]
	v_mfma_f32_16x16x32_bf16 v[112:115], v[166:169], v[210:213], v[112:115]
	v_mfma_f32_16x16x32_bf16 v[108:111], v[158:161], v[218:221], v[108:111]
	v_mfma_f32_16x16x32_bf16 v[104:107], v[166:169], v[218:221], v[104:107]
	v_mfma_f32_16x16x32_bf16 v[100:103], v[158:161], v[226:229], v[100:103]
	v_mfma_f32_16x16x32_bf16 v[96:99], v[166:169], v[226:229], v[96:99]
	v_mfma_f32_16x16x32_bf16 v[124:127], v[162:165], v[206:209], v[124:127]
	v_mfma_f32_16x16x32_bf16 v[120:123], v[170:173], v[206:209], v[120:123]
	v_mfma_f32_16x16x32_bf16 v[116:119], v[162:165], v[214:217], v[116:119]
	v_mfma_f32_16x16x32_bf16 v[112:115], v[170:173], v[214:217], v[112:115]
	v_mfma_f32_16x16x32_bf16 v[108:111], v[162:165], v[222:225], v[108:111]
	v_mfma_f32_16x16x32_bf16 v[104:107], v[170:173], v[222:225], v[104:107]
	v_mfma_f32_16x16x32_bf16 v[100:103], v[162:165], v[230:233], v[100:103]
	v_mfma_f32_16x16x32_bf16 v[96:99], v[170:173], v[230:233], v[96:99]
	v_mfma_f32_16x16x32_bf16 v[92:95], v[180:183], v[202:205], v[92:95]
	v_mfma_f32_16x16x32_bf16 v[88:91], v[194:197], v[202:205], v[88:91]
	v_mfma_f32_16x16x32_bf16 v[84:87], v[180:183], v[210:213], v[84:87]
	v_mfma_f32_16x16x32_bf16 v[80:83], v[194:197], v[210:213], v[80:83]
	v_mfma_f32_16x16x32_bf16 v[76:79], v[180:183], v[218:221], v[76:79]
	v_mfma_f32_16x16x32_bf16 v[72:75], v[194:197], v[218:221], v[72:75]
	v_mfma_f32_16x16x32_bf16 v[68:71], v[180:183], v[226:229], v[68:71]
	v_mfma_f32_16x16x32_bf16 v[64:67], v[194:197], v[226:229], v[64:67]
	v_mfma_f32_16x16x32_bf16 v[92:95], v[190:193], v[206:209], v[92:95]
	v_mfma_f32_16x16x32_bf16 v[88:91], v[198:201], v[206:209], v[88:91]
	v_mfma_f32_16x16x32_bf16 v[84:87], v[190:193], v[214:217], v[84:87]
	v_mfma_f32_16x16x32_bf16 v[80:83], v[198:201], v[214:217], v[80:83]
	v_mfma_f32_16x16x32_bf16 v[76:79], v[190:193], v[222:225], v[76:79]
	v_mfma_f32_16x16x32_bf16 v[72:75], v[198:201], v[222:225], v[72:75]
	v_mfma_f32_16x16x32_bf16 v[68:71], v[190:193], v[230:233], v[68:71]
	v_mfma_f32_16x16x32_bf16 v[64:67], v[198:201], v[230:233], v[64:67]
	s_barrier
; #define PG8_STAGE(bufoff, gbase, voff) do { _Pragma("unroll") for (int _i = 0; _i < 2; ++_i) \
;         __builtin_amdgcn_global_load_lds((const unsigned*)((const char*)(gbase) + (voff)[_i]), (PG8_LAS unsigned*)(lds + (bufoff) + ldsw + _i * 8192), 16, 0, 0); } while (0)
; #define PG8_LDA(dst, b, h) do { _Pragma("unroll") for (int m = 0; m < 4; ++m) _Pragma("unroll") for (int k = 0; k < 2; ++k) dst[m][k] = *(const PG8_LAS bf16x8*)(lds + PG8_SA(b, h) + aoff + m * 2048 + k * 1024); } while (0)
; #define PG8_MMA(ai, bj, At, Bt) do { __builtin_amdgcn_s_setprio(1); _Pragma("unroll") for (int m = 0; m < 4; ++m) _Pragma("unroll") for (int n = 0; n < 2; ++n) _Pragma("unroll") for (int k = 0; k < 2; ++k) \
;         acc[ai][bj][m][n] = __builtin_amdgcn_mfma_f32_16x16x32_bf16(Bt[n][k], At[m][k], acc[ai][bj][m][n], 0, 0, 0); __builtin_amdgcn_s_setprio(0); } while (0)
; #define PG8_WAIT_V(n) asm volatile("s_waitcnt vmcnt(" #n ")" ::: "memory")
; #define PG8_WAIT_L(n) asm volatile("s_waitcnt lgkmcnt(" #n ")" ::: "memory")
; #define PG8_BAR __builtin_amdgcn_s_barrier()
; #define PG8_SCHED __builtin_amdgcn_sched_barrier(0)
; template <class Epi, class Sched, bool ALIGN_EPI = false, bool SP2 = false>
; __device__ __forceinline__ void gemm_phase(PG8_LAS unsigned char* lds, const Gemm g, const Sched& S, const Epi& E) {
;     ...
;         for (int t = 0; t < nt; t += 2) {
;     ...
;             PG8_LDA(At, 1, 1); PG8_STAGE(PG8_SB(1, 0), b3, voffB); PG8_STAGE(PG8_SB(1, 1), b3 + hstepB, voffB); PG8_STAGE(PG8_SA(1, 0), a3, voffA);
;             PG8_WAIT_V(8); PG8_WAIT_L(0); PG8_BAR; PG8_MMA(1, 0, At, B0); PG8_MMA(1, 1, At, B1); PG8_BAR; PG8_SCHED;
	s_setprio 0
	s_add_i32 s4, s6, s77
	v_lshl_add_u64 v[174:175], v[174:175], 0, s[64:65]
	s_mov_b32 m0, s4
	ds_read_b128 v[202:205], v179 offset:49152
	ds_read_b128 v[206:209], v179 offset:50176
	ds_read_b128 v[210:213], v179 offset:51200
	ds_read_b128 v[214:217], v179 offset:52224
	ds_read_b128 v[218:221], v179 offset:53248
	ds_read_b128 v[222:225], v179 offset:54272
	ds_read_b128 v[226:229], v179 offset:55296
	ds_read_b128 v[230:233], v179 offset:56320
	global_load_lds_dwordx4 v[174:175], off
	s_add_i32 m0, s4, 0x2000
	s_add_u32 s4, s52, 0x160080
	v_lshl_add_u64 v[174:175], v[234:235], 0, s[64:65]
	s_addc_u32 s5, s53, 0
	s_add_i32 s6, s7, s77
	global_load_lds_dwordx4 v[174:175], off
	v_lshl_add_u64 v[174:175], s[4:5], 0, v[130:131]
	s_mov_b32 m0, s6
	s_nop 0
	global_load_lds_dwordx4 v[174:175], off
	v_lshl_add_u64 v[174:175], s[4:5], 0, v[134:135]
	s_add_i32 m0, s6, 0x2000
	s_nop 0
	global_load_lds_dwordx4 v[174:175], off
	v_lshl_add_u64 v[174:175], s[50:51], 0, v[128:129]
	s_mov_b32 m0, s43
	s_nop 0
	global_load_lds_dwordx4 v[174:175], off
	v_lshl_add_u64 v[174:175], s[50:51], 0, v[132:133]
	s_mov_b32 m0, s56
	s_nop 0
	global_load_lds_dwordx4 v[174:175], off
	s_waitcnt vmcnt(8)
	s_waitcnt lgkmcnt(0)
	s_setprio 1
	s_barrier
	v_mfma_f32_16x16x32_bf16 v[60:63], v[158:161], v[202:205], v[60:63]
	v_mfma_f32_16x16x32_bf16 v[56:59], v[166:169], v[202:205], v[56:59]
	v_mfma_f32_16x16x32_bf16 v[52:55], v[158:161], v[210:213], v[52:55]
	v_mfma_f32_16x16x32_bf16 v[48:51], v[166:169], v[210:213], v[48:51]
	v_mfma_f32_16x16x32_bf16 v[44:47], v[158:161], v[218:221], v[44:47]
	v_mfma_f32_16x16x32_bf16 v[40:43], v[166:169], v[218:221], v[40:43]
	v_mfma_f32_16x16x32_bf16 v[36:39], v[158:161], v[226:229], v[36:39]
	v_mfma_f32_16x16x32_bf16 v[32:35], v[166:169], v[226:229], v[32:35]
	v_mfma_f32_16x16x32_bf16 v[60:63], v[162:165], v[206:209], v[60:63]
	v_mfma_f32_16x16x32_bf16 v[56:59], v[170:173], v[206:209], v[56:59]
	v_mfma_f32_16x16x32_bf16 v[52:55], v[162:165], v[214:217], v[52:55]
	v_mfma_f32_16x16x32_bf16 v[48:51], v[170:173], v[214:217], v[48:51]
	v_mfma_f32_16x16x32_bf16 v[44:47], v[162:165], v[222:225], v[44:47]
	v_mfma_f32_16x16x32_bf16 v[40:43], v[170:173], v[222:225], v[40:43]
	v_mfma_f32_16x16x32_bf16 v[36:39], v[162:165], v[230:233], v[36:39]
	v_mfma_f32_16x16x32_bf16 v[32:35], v[170:173], v[230:233], v[32:35]
	v_mfma_f32_16x16x32_bf16 v[28:31], v[180:183], v[202:205], v[28:31]
	v_mfma_f32_16x16x32_bf16 v[24:27], v[194:197], v[202:205], v[24:27]
	v_mfma_f32_16x16x32_bf16 v[20:23], v[180:183], v[210:213], v[20:23]
	v_mfma_f32_16x16x32_bf16 v[16:19], v[194:197], v[210:213], v[16:19]
	v_mfma_f32_16x16x32_bf16 v[12:15], v[180:183], v[218:221], v[12:15]
	v_mfma_f32_16x16x32_bf16 v[8:11], v[194:197], v[218:221], v[8:11]
	v_mfma_f32_16x16x32_bf16 v[4:7], v[180:183], v[226:229], v[4:7]
	v_mfma_f32_16x16x32_bf16 v[0:3], v[194:197], v[226:229], v[0:3]
	v_mfma_f32_16x16x32_bf16 v[28:31], v[190:193], v[206:209], v[28:31]
	v_mfma_f32_16x16x32_bf16 v[24:27], v[198:201], v[206:209], v[24:27]
	v_mfma_f32_16x16x32_bf16 v[20:23], v[190:193], v[214:217], v[20:23]
	v_mfma_f32_16x16x32_bf16 v[16:19], v[198:201], v[214:217], v[16:19]
	v_mfma_f32_16x16x32_bf16 v[12:15], v[190:193], v[222:225], v[12:15]
	v_mfma_f32_16x16x32_bf16 v[8:11], v[198:201], v[222:225], v[8:11]
	v_mfma_f32_16x16x32_bf16 v[4:7], v[190:193], v[230:233], v[4:7]
	v_mfma_f32_16x16x32_bf16 v[0:3], v[198:201], v[230:233], v[0:3]
	s_barrier
	s_setprio 0
	s_cmp_ge_i32 s68, s57
	s_cbranch_scc1 .LBB0_1416

; #define PG8_STAGE(bufoff, gbase, voff) do { _Pragma("unroll") for (int _i = 0; _i < 2; ++_i) \
;         __builtin_amdgcn_global_load_lds((const unsigned*)((const char*)(gbase) + (voff)[_i]), (PG8_LAS unsigned*)(lds + (bufoff) + ldsw + _i * 8192), 16, 0, 0); } while (0)
; #define PG8_LDA(dst, b, h) do { _Pragma("unroll") for (int m = 0; m < 4; ++m) _Pragma("unroll") for (int k = 0; k < 2; ++k) dst[m][k] = *(const PG8_LAS bf16x8*)(lds + PG8_SA(b, h) + aoff + m * 2048 + k * 1024); } while (0)
; #define PG8_LDB(dst, b, h) do { _Pragma("unroll") for (int n = 0; n < 2; ++n) _Pragma("unroll") for (int k = 0; k < 2; ++k) dst[n][k] = *(const PG8_LAS bf16x8*)(lds + PG8_SB(b, h) + boff + n * 2048 + k * 1024); } while (0)
; #define PG8_MMA(ai, bj, At, Bt) do { __builtin_amdgcn_s_setprio(1); _Pragma("unroll") for (int m = 0; m < 4; ++m) _Pragma("unroll") for (int n = 0; n < 2; ++n) _Pragma("unroll") for (int k = 0; k < 2; ++k) \
;         acc[ai][bj][m][n] = __builtin_amdgcn_mfma_f32_16x16x32_bf16(Bt[n][k], At[m][k], acc[ai][bj][m][n], 0, 0, 0); __builtin_amdgcn_s_setprio(0); } while (0)
; #define PG8_WAIT_V(n) asm volatile("s_waitcnt vmcnt(" #n ")" ::: "memory")
; #define PG8_WAIT_L(n) asm volatile("s_waitcnt lgkmcnt(" #n ")" ::: "memory")
; #define PG8_BAR __builtin_amdgcn_s_barrier()
; #define PG8_SCHED __builtin_amdgcn_sched_barrier(0)
; template <class Epi, class Sched, bool ALIGN_EPI = false, bool SP2 = false>
; __device__ __forceinline__ void gemm_phase(PG8_LAS unsigned char* lds, const Gemm g, const Sched& S, const Epi& E) {
;     ...
;             const char* a1 = cA + (size_t)(t + 1) * kstA;
;             const char* a2 = last ? nA : cA + (size_t)(t + 2) * kstA; const char* b2 = last ? nB : cB + (size_t)(t + 2) * kstep;
;             const char* a3 = a2 + kstA; const char* b3 = b2 + kstep;
;             if (last && has_next) S.a_ready(nxt);
;             if constexpr (SP2) {
;             PG8_LDB(B0, 0, 0); PG8_LDB(B1, 0, 1); PG8_SCHED; PG8_LDA(At, 0, 0); PG8_STAGE(PG8_SA(1, 1), a1 + hstepA, voffA);
;             PG8_WAIT_V(8); PG8_WAIT_L(0); PG8_BAR; PG8_MMA(0, 0, At, B0); PG8_MMA(0, 1, At, B1); PG8_BAR; PG8_SCHED;
;             PG8_LDA(At, 0, 1); PG8_STAGE(PG8_SB(0, 0), b2, voffB); PG8_STAGE(PG8_SB(0, 1), b2 + hstepB, voffB); PG8_STAGE(PG8_SA(0, 0), a2, voffA);
.LBB0_1657:
	ds_read_b128 v[156:159], v152
	ds_read_b128 v[160:163], v152 offset:1024
	ds_read_b128 v[164:167], v152 offset:2048
	ds_read_b128 v[168:171], v152 offset:3072
	ds_read_b128 v[172:175], v153
	ds_read_b128 v[176:179], v153 offset:1024
	ds_read_b128 v[180:183], v153 offset:2048
	ds_read_b128 v[190:193], v153 offset:3072
	s_add_u32 s52, s50, 0xfff80080
	s_addc_u32 s53, s51, -1
	s_cmp_eq_u32 s63, 28
	s_cselect_b32 s59, s4, s53
	s_cselect_b32 s58, s5, s52
	s_cselect_b32 s53, s12, s41
	s_cselect_b32 s52, s13, s39
	v_lshl_add_u64 v[226:227], s[50:51], 0, v[142:143]
	s_add_i32 m0, s7, 0xc000
	ds_read_b128 v[194:197], v154
	ds_read_b128 v[198:201], v154 offset:1024
	ds_read_b128 v[202:205], v154 offset:2048
	ds_read_b128 v[206:209], v154 offset:3072
	ds_read_b128 v[210:213], v154 offset:4096
	ds_read_b128 v[214:217], v154 offset:5120
	ds_read_b128 v[218:221], v154 offset:6144
	ds_read_b128 v[222:225], v154 offset:7168
	global_load_lds_dwordx4 v[226:227], off
	v_lshl_add_u64 v[226:227], s[50:51], 0, v[144:145]
	s_add_i32 m0, s7, 0xe000
	s_nop 0
	global_load_lds_dwordx4 v[226:227], off
	s_waitcnt vmcnt(8)
	s_waitcnt lgkmcnt(0)
	s_setprio 1
	s_barrier
	v_mfma_f32_16x16x32_bf16 v[124:127], v[156:159], v[194:197], v[124:127]
	v_mfma_f32_16x16x32_bf16 v[120:123], v[164:167], v[194:197], v[120:123]
	v_mfma_f32_16x16x32_bf16 v[108:111], v[156:159], v[202:205], v[108:111]
	v_mfma_f32_16x16x32_bf16 v[104:107], v[164:167], v[202:205], v[104:107]
	v_mfma_f32_16x16x32_bf16 v[92:95], v[156:159], v[210:213], v[92:95]
	v_mfma_f32_16x16x32_bf16 v[88:91], v[164:167], v[210:213], v[88:91]
	v_mfma_f32_16x16x32_bf16 v[76:79], v[156:159], v[218:221], v[76:79]
	v_mfma_f32_16x16x32_bf16 v[72:75], v[164:167], v[218:221], v[72:75]
	v_mfma_f32_16x16x32_bf16 v[124:127], v[160:163], v[198:201], v[124:127]
	v_mfma_f32_16x16x32_bf16 v[120:123], v[168:171], v[198:201], v[120:123]
	v_mfma_f32_16x16x32_bf16 v[108:111], v[160:163], v[206:209], v[108:111]
	v_mfma_f32_16x16x32_bf16 v[104:107], v[168:171], v[206:209], v[104:107]
	v_mfma_f32_16x16x32_bf16 v[92:95], v[160:163], v[214:217], v[92:95]
	v_mfma_f32_16x16x32_bf16 v[88:91], v[168:171], v[214:217], v[88:91]
	v_mfma_f32_16x16x32_bf16 v[76:79], v[160:163], v[222:225], v[76:79]
	v_mfma_f32_16x16x32_bf16 v[72:75], v[168:171], v[222:225], v[72:75]
	v_mfma_f32_16x16x32_bf16 v[116:119], v[172:175], v[194:197], v[116:119]
	v_mfma_f32_16x16x32_bf16 v[112:115], v[180:183], v[194:197], v[112:115]
	v_mfma_f32_16x16x32_bf16 v[100:103], v[172:175], v[202:205], v[100:103]
	v_mfma_f32_16x16x32_bf16 v[96:99], v[180:183], v[202:205], v[96:99]
	v_mfma_f32_16x16x32_bf16 v[84:87], v[172:175], v[210:213], v[84:87]
	v_mfma_f32_16x16x32_bf16 v[80:83], v[180:183], v[210:213], v[80:83]
	v_mfma_f32_16x16x32_bf16 v[68:71], v[172:175], v[218:221], v[68:71]
	v_mfma_f32_16x16x32_bf16 v[64:67], v[180:183], v[218:221], v[64:67]
	v_mfma_f32_16x16x32_bf16 v[116:119], v[176:179], v[198:201], v[116:119]
	v_mfma_f32_16x16x32_bf16 v[112:115], v[190:193], v[198:201], v[112:115]
	v_mfma_f32_16x16x32_bf16 v[100:103], v[176:179], v[206:209], v[100:103]
	v_mfma_f32_16x16x32_bf16 v[96:99], v[190:193], v[206:209], v[96:99]
	v_mfma_f32_16x16x32_bf16 v[84:87], v[176:179], v[214:217], v[84:87]
	v_mfma_f32_16x16x32_bf16 v[80:83], v[190:193], v[214:217], v[80:83]
	v_mfma_f32_16x16x32_bf16 v[68:71], v[176:179], v[222:225], v[68:71]
	v_mfma_f32_16x16x32_bf16 v[64:67], v[190:193], v[222:225], v[64:67]
	s_barrier
	s_setprio 0
	s_add_i32 s64, s56, s6
	v_lshl_add_u64 v[226:227], s[52:53], 0, v[130:131]
	s_mov_b32 m0, s64
	ds_read_b128 v[194:197], v154 offset:16384
	ds_read_b128 v[198:201], v154 offset:17408
	ds_read_b128 v[202:205], v154 offset:18432
	ds_read_b128 v[206:209], v154 offset:19456
	ds_read_b128 v[210:213], v154 offset:20480
	ds_read_b128 v[214:217], v154 offset:21504
	ds_read_b128 v[218:221], v154 offset:22528
	ds_read_b128 v[222:225], v154 offset:23552
	global_load_lds_dwordx4 v[226:227], off
	s_add_i32 m0, s64, 0x2000
	s_add_u32 s64, s52, 0x80000
	v_lshl_add_u64 v[228:229], s[52:53], 0, v[134:135]
	s_addc_u32 s65, s53, 0
	s_add_i32 s66, s57, s6
	global_load_lds_dwordx4 v[228:229], off
	v_lshl_add_u64 v[230:231], s[64:65], 0, v[130:131]
	s_mov_b32 m0, s66
	v_lshl_add_u64 v[232:233], s[58:59], 0, v[132:133]
	global_load_lds_dwordx4 v[230:231], off
	v_lshl_add_u64 v[230:231], s[64:65], 0, v[134:135]
	s_add_i32 m0, s66, 0x2000
	s_nop 0
	global_load_lds_dwordx4 v[230:231], off
	v_lshl_add_u64 v[230:231], s[58:59], 0, v[128:129]
	s_mov_b32 m0, s7
	s_nop 0
	global_load_lds_dwordx4 v[230:231], off
	s_mov_b32 m0, s8
	s_nop 0
	global_load_lds_dwordx4 v[232:233], off
	s_waitcnt vmcnt(8)
	s_waitcnt lgkmcnt(0)
	s_setprio 1
	s_barrier
; #define PG8_STAGE(bufoff, gbase, voff) do { _Pragma("unroll") for (int _i = 0; _i < 2; ++_i) \
;         __builtin_amdgcn_global_load_lds((const unsigned*)((const char*)(gbase) + (voff)[_i]), (PG8_LAS unsigned*)(lds + (bufoff) + ldsw + _i * 8192), 16, 0, 0); } while (0)
; #define PG8_LDA(dst, b, h) do { _Pragma("unroll") for (int m = 0; m < 4; ++m) _Pragma("unroll") for (int k = 0; k < 2; ++k) dst[m][k] = *(const PG8_LAS bf16x8*)(lds + PG8_SA(b, h) + aoff + m * 2048 + k * 1024); } while (0)
; #define PG8_LDB(dst, b, h) do { _Pragma("unroll") for (int n = 0; n < 2; ++n) _Pragma("unroll") for (int k = 0; k < 2; ++k) dst[n][k] = *(const PG8_LAS bf16x8*)(lds + PG8_SB(b, h) + boff + n * 2048 + k * 1024); } while (0)
; #define PG8_MMA(ai, bj, At, Bt) do { __builtin_amdgcn_s_setprio(1); _Pragma("unroll") for (int m = 0; m < 4; ++m) _Pragma("unroll") for (int n = 0; n < 2; ++n) _Pragma("unroll") for (int k = 0; k < 2; ++k) \
;         acc[ai][bj][m][n] = __builtin_amdgcn_mfma_f32_16x16x32_bf16(Bt[n][k], At[m][k], acc[ai][bj][m][n], 0, 0, 0); __builtin_amdgcn_s_setprio(0); } while (0)
; #define PG8_WAIT_V(n) asm volatile("s_waitcnt vmcnt(" #n ")" ::: "memory")
; #define PG8_WAIT_L(n) asm volatile("s_waitcnt lgkmcnt(" #n ")" ::: "memory")
; #define PG8_BAR __builtin_amdgcn_s_barrier()
; #define PG8_SCHED __builtin_amdgcn_sched_barrier(0)
; template <class Epi, class Sched, bool ALIGN_EPI = false, bool SP2 = false>
; __device__ __forceinline__ void gemm_phase(PG8_LAS unsigned char* lds, const Gemm g, const Sched& S, const Epi& E) {
;     ...
;             PG8_WAIT_V(8); PG8_WAIT_L(0); PG8_BAR; PG8_MMA(1, 0, At, B0); PG8_MMA(1, 1, At, B1); PG8_BAR; PG8_SCHED;
;             PG8_LDB(B0, 1, 0); PG8_LDB(B1, 1, 1); PG8_SCHED; PG8_LDA(At, 1, 0); PG8_STAGE(PG8_SA(0, 1), a2 + hstepA, voffA);
;             PG8_WAIT_V(8); PG8_WAIT_L(0); PG8_BAR; PG8_MMA(0, 0, At, B0); PG8_MMA(0, 1, At, B1); PG8_BAR; PG8_SCHED;
	v_mfma_f32_16x16x32_bf16 v[60:63], v[156:159], v[194:197], v[60:63]
	v_mfma_f32_16x16x32_bf16 v[56:59], v[164:167], v[194:197], v[56:59]
	v_mfma_f32_16x16x32_bf16 v[44:47], v[156:159], v[202:205], v[44:47]
	v_mfma_f32_16x16x32_bf16 v[40:43], v[164:167], v[202:205], v[40:43]
	v_mfma_f32_16x16x32_bf16 v[28:31], v[156:159], v[210:213], v[28:31]
	v_mfma_f32_16x16x32_bf16 v[24:27], v[164:167], v[210:213], v[24:27]
	v_mfma_f32_16x16x32_bf16 v[12:15], v[156:159], v[218:221], v[12:15]
	v_mfma_f32_16x16x32_bf16 v[8:11], v[164:167], v[218:221], v[8:11]
	v_mfma_f32_16x16x32_bf16 v[60:63], v[160:163], v[198:201], v[60:63]
	v_mfma_f32_16x16x32_bf16 v[56:59], v[168:171], v[198:201], v[56:59]
	v_mfma_f32_16x16x32_bf16 v[44:47], v[160:163], v[206:209], v[44:47]
	v_mfma_f32_16x16x32_bf16 v[40:43], v[168:171], v[206:209], v[40:43]
	v_mfma_f32_16x16x32_bf16 v[28:31], v[160:163], v[214:217], v[28:31]
	v_mfma_f32_16x16x32_bf16 v[24:27], v[168:171], v[214:217], v[24:27]
	v_mfma_f32_16x16x32_bf16 v[12:15], v[160:163], v[222:225], v[12:15]
	v_mfma_f32_16x16x32_bf16 v[8:11], v[168:171], v[222:225], v[8:11]
	v_mfma_f32_16x16x32_bf16 v[52:55], v[172:175], v[194:197], v[52:55]
	v_mfma_f32_16x16x32_bf16 v[48:51], v[180:183], v[194:197], v[48:51]
	v_mfma_f32_16x16x32_bf16 v[36:39], v[172:175], v[202:205], v[36:39]
	v_mfma_f32_16x16x32_bf16 v[32:35], v[180:183], v[202:205], v[32:35]
	v_mfma_f32_16x16x32_bf16 v[20:23], v[172:175], v[210:213], v[20:23]
	v_mfma_f32_16x16x32_bf16 v[16:19], v[180:183], v[210:213], v[16:19]
	v_mfma_f32_16x16x32_bf16 v[4:7], v[172:175], v[218:221], v[4:7]
	v_mfma_f32_16x16x32_bf16 v[0:3], v[180:183], v[218:221], v[0:3]
	v_mfma_f32_16x16x32_bf16 v[52:55], v[176:179], v[198:201], v[52:55]
	v_mfma_f32_16x16x32_bf16 v[48:51], v[190:193], v[198:201], v[48:51]
	v_mfma_f32_16x16x32_bf16 v[36:39], v[176:179], v[206:209], v[36:39]
	v_mfma_f32_16x16x32_bf16 v[32:35], v[190:193], v[206:209], v[32:35]
	v_mfma_f32_16x16x32_bf16 v[20:23], v[176:179], v[214:217], v[20:23]
	v_mfma_f32_16x16x32_bf16 v[16:19], v[190:193], v[214:217], v[16:19]
	v_mfma_f32_16x16x32_bf16 v[4:7], v[176:179], v[222:225], v[4:7]
	v_mfma_f32_16x16x32_bf16 v[0:3], v[190:193], v[222:225], v[0:3]
	s_barrier
	s_setprio 0
	s_add_i32 s64, 0, 0x18000
	v_add_u32_e32 v155, s64, v150
	s_add_i32 s65, 0, 0x1c000
	ds_read_b128 v[156:159], v155
	ds_read_b128 v[160:163], v155 offset:1024
	ds_read_b128 v[164:167], v155 offset:2048
	ds_read_b128 v[168:171], v155 offset:3072
	v_add_u32_e32 v155, s65, v150
	ds_read_b128 v[172:175], v155
	ds_read_b128 v[176:179], v155 offset:1024
	ds_read_b128 v[180:183], v155 offset:2048
	ds_read_b128 v[190:193], v155 offset:3072
	s_add_u32 s58, s58, 0x80000
	s_addc_u32 s59, s59, 0
	s_mov_b32 m0, s9
	v_lshl_add_u64 v[234:235], s[58:59], 0, v[128:129]
	ds_read_b128 v[194:197], v154 offset:32768
	ds_read_b128 v[198:201], v154 offset:33792
	ds_read_b128 v[202:205], v154 offset:34816
	ds_read_b128 v[206:209], v154 offset:35840
	ds_read_b128 v[210:213], v154 offset:36864
	ds_read_b128 v[214:217], v154 offset:37888
	ds_read_b128 v[218:221], v154 offset:38912
	ds_read_b128 v[222:225], v154 offset:39936
	global_load_lds_dwordx4 v[234:235], off
	v_lshl_add_u64 v[234:235], s[58:59], 0, v[132:133]
	s_mov_b32 m0, s11
	s_nop 0
	global_load_lds_dwordx4 v[234:235], off
	s_waitcnt vmcnt(8)
	s_waitcnt lgkmcnt(0)
	s_setprio 1
	s_barrier
	v_mfma_f32_16x16x32_bf16 v[124:127], v[156:159], v[194:197], v[124:127]
	v_mfma_f32_16x16x32_bf16 v[120:123], v[164:167], v[194:197], v[120:123]
	v_mfma_f32_16x16x32_bf16 v[108:111], v[156:159], v[202:205], v[108:111]
	v_mfma_f32_16x16x32_bf16 v[104:107], v[164:167], v[202:205], v[104:107]
	v_mfma_f32_16x16x32_bf16 v[92:95], v[156:159], v[210:213], v[92:95]
	v_mfma_f32_16x16x32_bf16 v[88:91], v[164:167], v[210:213], v[88:91]
	v_mfma_f32_16x16x32_bf16 v[76:79], v[156:159], v[218:221], v[76:79]
	v_mfma_f32_16x16x32_bf16 v[72:75], v[164:167], v[218:221], v[72:75]
	v_mfma_f32_16x16x32_bf16 v[124:127], v[160:163], v[198:201], v[124:127]
	v_mfma_f32_16x16x32_bf16 v[120:123], v[168:171], v[198:201], v[120:123]
	v_mfma_f32_16x16x32_bf16 v[108:111], v[160:163], v[206:209], v[108:111]
	v_mfma_f32_16x16x32_bf16 v[104:107], v[168:171], v[206:209], v[104:107]
	v_mfma_f32_16x16x32_bf16 v[92:95], v[160:163], v[214:217], v[92:95]
	v_mfma_f32_16x16x32_bf16 v[88:91], v[168:171], v[214:217], v[88:91]
	v_mfma_f32_16x16x32_bf16 v[76:79], v[160:163], v[222:225], v[76:79]
	v_mfma_f32_16x16x32_bf16 v[72:75], v[168:171], v[222:225], v[72:75]
	v_mfma_f32_16x16x32_bf16 v[116:119], v[172:175], v[194:197], v[116:119]
	v_mfma_f32_16x16x32_bf16 v[112:115], v[180:183], v[194:197], v[112:115]
	v_mfma_f32_16x16x32_bf16 v[100:103], v[172:175], v[202:205], v[100:103]
	v_mfma_f32_16x16x32_bf16 v[96:99], v[180:183], v[202:205], v[96:99]
	v_mfma_f32_16x16x32_bf16 v[84:87], v[172:175], v[210:213], v[84:87]
	v_mfma_f32_16x16x32_bf16 v[80:83], v[180:183], v[210:213], v[80:83]
	v_mfma_f32_16x16x32_bf16 v[68:71], v[172:175], v[218:221], v[68:71]
	v_mfma_f32_16x16x32_bf16 v[64:67], v[180:183], v[218:221], v[64:67]
	v_mfma_f32_16x16x32_bf16 v[116:119], v[176:179], v[198:201], v[116:119]
	v_mfma_f32_16x16x32_bf16 v[112:115], v[190:193], v[198:201], v[112:115]
	v_mfma_f32_16x16x32_bf16 v[100:103], v[176:179], v[206:209], v[100:103]
	v_mfma_f32_16x16x32_bf16 v[96:99], v[190:193], v[206:209], v[96:99]
	v_mfma_f32_16x16x32_bf16 v[84:87], v[176:179], v[214:217], v[84:87]
	v_mfma_f32_16x16x32_bf16 v[80:83], v[190:193], v[214:217], v[80:83]
	v_mfma_f32_16x16x32_bf16 v[68:71], v[176:179], v[222:225], v[68:71]
	v_mfma_f32_16x16x32_bf16 v[64:67], v[190:193], v[222:225], v[64:67]
	s_barrier
; #define PG8_STAGE(bufoff, gbase, voff) do { _Pragma("unroll") for (int _i = 0; _i < 2; ++_i) \
;         __builtin_amdgcn_global_load_lds((const unsigned*)((const char*)(gbase) + (voff)[_i]), (PG8_LAS unsigned*)(lds + (bufoff) + ldsw + _i * 8192), 16, 0, 0); } while (0)
; #define PG8_LDA(dst, b, h) do { _Pragma("unroll") for (int m = 0; m < 4; ++m) _Pragma("unroll") for (int k = 0; k < 2; ++k) dst[m][k] = *(const PG8_LAS bf16x8*)(lds + PG8_SA(b, h) + aoff + m * 2048 + k * 1024); } while (0)
; #define PG8_MMA(ai, bj, At, Bt) do { __builtin_amdgcn_s_setprio(1); _Pragma("unroll") for (int m = 0; m < 4; ++m) _Pragma("unroll") for (int n = 0; n < 2; ++n) _Pragma("unroll") for (int k = 0; k < 2; ++k) \
;         acc[ai][bj][m][n] = __builtin_amdgcn_mfma_f32_16x16x32_bf16(Bt[n][k], At[m][k], acc[ai][bj][m][n], 0, 0, 0); __builtin_amdgcn_s_setprio(0); } while (0)
; #define PG8_WAIT_V(n) asm volatile("s_waitcnt vmcnt(" #n ")" ::: "memory")
; #define PG8_WAIT_L(n) asm volatile("s_waitcnt lgkmcnt(" #n ")" ::: "memory")
; #define PG8_BAR __builtin_amdgcn_s_barrier()
; #define PG8_SCHED __builtin_amdgcn_sched_barrier(0)
; template <class Epi, class Sched, bool ALIGN_EPI = false, bool SP2 = false>
; __device__ __forceinline__ void gemm_phase(PG8_LAS unsigned char* lds, const Gemm g, const Sched& S, const Epi& E) {
;     ...
;         for (int t = 0; t < nt; t += 2) {
;     ...
;             PG8_LDA(At, 1, 1); PG8_STAGE(PG8_SB(1, 0), b3, voffB); PG8_STAGE(PG8_SB(1, 1), b3 + hstepB, voffB); PG8_STAGE(PG8_SA(1, 0), a3, voffA);
;             PG8_WAIT_V(8); PG8_WAIT_L(0); PG8_BAR; PG8_MMA(1, 0, At, B0); PG8_MMA(1, 1, At, B1); PG8_BAR; PG8_SCHED;
	s_setprio 0
	s_add_i32 s58, s64, s6
	v_lshl_add_u64 v[226:227], v[226:227], 0, s[20:21]
	s_mov_b32 m0, s58
	ds_read_b128 v[194:197], v154 offset:49152
	ds_read_b128 v[198:201], v154 offset:50176
	ds_read_b128 v[202:205], v154 offset:51200
	ds_read_b128 v[206:209], v154 offset:52224
	ds_read_b128 v[210:213], v154 offset:53248
	ds_read_b128 v[214:217], v154 offset:54272
	ds_read_b128 v[218:221], v154 offset:55296
	ds_read_b128 v[222:225], v154 offset:56320
	global_load_lds_dwordx4 v[226:227], off
	s_add_i32 m0, s58, 0x2000
	s_add_u32 s52, s52, 0x80080
	v_lshl_add_u64 v[226:227], v[228:229], 0, s[20:21]
	s_addc_u32 s53, s53, 0
	s_add_i32 s58, s65, s6
	global_load_lds_dwordx4 v[226:227], off
	v_lshl_add_u64 v[226:227], s[52:53], 0, v[130:131]
	s_mov_b32 m0, s58
	s_nop 0
	global_load_lds_dwordx4 v[226:227], off
	v_lshl_add_u64 v[226:227], s[52:53], 0, v[134:135]
	s_add_i32 m0, s58, 0x2000
	s_nop 0
	global_load_lds_dwordx4 v[226:227], off
	v_lshl_add_u64 v[226:227], v[230:231], 0, s[20:21]
	s_mov_b32 m0, s46
	s_nop 0
	global_load_lds_dwordx4 v[226:227], off
	v_lshl_add_u64 v[226:227], v[232:233], 0, s[20:21]
	s_mov_b32 m0, s47
	s_nop 0
	global_load_lds_dwordx4 v[226:227], off
	s_waitcnt vmcnt(8)
	s_waitcnt lgkmcnt(0)
	s_setprio 1
	s_barrier
	v_mfma_f32_16x16x32_bf16 v[60:63], v[156:159], v[194:197], v[60:63]
	v_mfma_f32_16x16x32_bf16 v[56:59], v[164:167], v[194:197], v[56:59]
	v_mfma_f32_16x16x32_bf16 v[44:47], v[156:159], v[202:205], v[44:47]
	v_mfma_f32_16x16x32_bf16 v[40:43], v[164:167], v[202:205], v[40:43]
	v_mfma_f32_16x16x32_bf16 v[28:31], v[156:159], v[210:213], v[28:31]
	v_mfma_f32_16x16x32_bf16 v[24:27], v[164:167], v[210:213], v[24:27]
	v_mfma_f32_16x16x32_bf16 v[12:15], v[156:159], v[218:221], v[12:15]
	v_mfma_f32_16x16x32_bf16 v[8:11], v[164:167], v[218:221], v[8:11]
	v_mfma_f32_16x16x32_bf16 v[60:63], v[160:163], v[198:201], v[60:63]
	v_mfma_f32_16x16x32_bf16 v[56:59], v[168:171], v[198:201], v[56:59]
	v_mfma_f32_16x16x32_bf16 v[44:47], v[160:163], v[206:209], v[44:47]
	v_mfma_f32_16x16x32_bf16 v[40:43], v[168:171], v[206:209], v[40:43]
	v_mfma_f32_16x16x32_bf16 v[28:31], v[160:163], v[214:217], v[28:31]
	v_mfma_f32_16x16x32_bf16 v[24:27], v[168:171], v[214:217], v[24:27]
	v_mfma_f32_16x16x32_bf16 v[12:15], v[160:163], v[222:225], v[12:15]
	v_mfma_f32_16x16x32_bf16 v[8:11], v[168:171], v[222:225], v[8:11]
	v_mfma_f32_16x16x32_bf16 v[52:55], v[172:175], v[194:197], v[52:55]
	v_mfma_f32_16x16x32_bf16 v[48:51], v[180:183], v[194:197], v[48:51]
	v_mfma_f32_16x16x32_bf16 v[36:39], v[172:175], v[202:205], v[36:39]
	v_mfma_f32_16x16x32_bf16 v[32:35], v[180:183], v[202:205], v[32:35]
	v_mfma_f32_16x16x32_bf16 v[20:23], v[172:175], v[210:213], v[20:23]
	v_mfma_f32_16x16x32_bf16 v[16:19], v[180:183], v[210:213], v[16:19]
	v_mfma_f32_16x16x32_bf16 v[4:7], v[172:175], v[218:221], v[4:7]
	v_mfma_f32_16x16x32_bf16 v[0:3], v[180:183], v[218:221], v[0:3]
	v_mfma_f32_16x16x32_bf16 v[52:55], v[176:179], v[198:201], v[52:55]
	v_mfma_f32_16x16x32_bf16 v[48:51], v[190:193], v[198:201], v[48:51]
	v_mfma_f32_16x16x32_bf16 v[36:39], v[176:179], v[206:209], v[36:39]
	v_mfma_f32_16x16x32_bf16 v[32:35], v[190:193], v[206:209], v[32:35]
	v_mfma_f32_16x16x32_bf16 v[20:23], v[176:179], v[214:217], v[20:23]
	v_mfma_f32_16x16x32_bf16 v[16:19], v[190:193], v[214:217], v[16:19]
	v_mfma_f32_16x16x32_bf16 v[4:7], v[176:179], v[222:225], v[4:7]
	v_mfma_f32_16x16x32_bf16 v[0:3], v[190:193], v[222:225], v[0:3]
	s_barrier
	s_setprio 0
	s_add_i32 s63, s63, 2
	s_add_u32 s50, s50, 0x100
	s_addc_u32 s51, s51, 0
	s_add_u32 s39, s39, 0x100
	s_addc_u32 s41, s41, 0
	s_cmp_gt_u32 s63, 29
	s_cbranch_scc0 .LBB0_1657
	s_and_b64 vcc, exec, s[34:35]
	s_cbranch_vccz .LBB0_1660
	s_barrier

; #define PG8_STAGE(bufoff, gbase, voff) do { _Pragma("unroll") for (int _i = 0; _i < 2; ++_i) \
;         __builtin_amdgcn_global_load_lds((const unsigned*)((const char*)(gbase) + (voff)[_i]), (PG8_LAS unsigned*)(lds + (bufoff) + ldsw + _i * 8192), 16, 0, 0); } while (0)
; #define PG8_LDA(dst, b, h) do { _Pragma("unroll") for (int m = 0; m < 4; ++m) _Pragma("unroll") for (int k = 0; k < 2; ++k) dst[m][k] = *(const PG8_LAS bf16x8*)(lds + PG8_SA(b, h) + aoff + m * 2048 + k * 1024); } while (0)
; #define PG8_LDB(dst, b, h) do { _Pragma("unroll") for (int n = 0; n < 2; ++n) _Pragma("unroll") for (int k = 0; k < 2; ++k) dst[n][k] = *(const PG8_LAS bf16x8*)(lds + PG8_SB(b, h) + boff + n * 2048 + k * 1024); } while (0)
; #define PG8_MMA(ai, bj, At, Bt) do { __builtin_amdgcn_s_setprio(1); _Pragma("unroll") for (int m = 0; m < 4; ++m) _Pragma("unroll") for (int n = 0; n < 2; ++n) _Pragma("unroll") for (int k = 0; k < 2; ++k) \
;         acc[ai][bj][m][n] = __builtin_amdgcn_mfma_f32_16x16x32_bf16(Bt[n][k], At[m][k], acc[ai][bj][m][n], 0, 0, 0); __builtin_amdgcn_s_setprio(0); } while (0)
; #define PG8_WAIT_V(n) asm volatile("s_waitcnt vmcnt(" #n ")" ::: "memory")
; #define PG8_WAIT_L(n) asm volatile("s_waitcnt lgkmcnt(" #n ")" ::: "memory")
; #define PG8_BAR __builtin_amdgcn_s_barrier()
; #define PG8_SCHED __builtin_amdgcn_sched_barrier(0)
; template <class Epi, class Sched, bool ALIGN_EPI = false, bool SP2 = false>
; __device__ __forceinline__ void gemm_phase(PG8_LAS unsigned char* lds, const Gemm g, const Sched& S, const Epi& E) {
;     ...
;             const char* a1 = cA + (size_t)(t + 1) * kstA;
;             const char* a2 = last ? nA : cA + (size_t)(t + 2) * kstA; const char* b2 = last ? nB : cB + (size_t)(t + 2) * kstep;
;             const char* a3 = a2 + kstA; const char* b3 = b2 + kstep;
;             if (last && has_next) S.a_ready(nxt);
;             if constexpr (SP2) {
;             PG8_LDB(B0, 0, 0); PG8_LDB(B1, 0, 1); PG8_SCHED; PG8_LDA(At, 0, 0); PG8_STAGE(PG8_SA(1, 1), a1 + hstepA, voffA);
;             PG8_WAIT_V(8); PG8_WAIT_L(0); PG8_BAR; PG8_MMA(0, 0, At, B0); PG8_MMA(0, 1, At, B1); PG8_BAR; PG8_SCHED;
;             PG8_LDA(At, 0, 1); PG8_STAGE(PG8_SB(0, 0), b2, voffB); PG8_STAGE(PG8_SB(0, 1), b2 + hstepB, voffB); PG8_STAGE(PG8_SA(0, 0), a2, voffA);
.LBB0_1754:
	s_or_b32 s44, s62, 1
	s_add_i32 s62, s62, 2
	s_mov_b32 s63, s45
	s_lshl_b64 s[4:5], s[44:45], 15
	s_lshl_b64 s[6:7], s[62:63], 15
	s_add_u32 s12, s34, s6
	v_add_u32_e32 v170, s10, v177
	v_add_u32_e32 v174, s11, v177
	s_addc_u32 s13, s35, s7
	ds_read_b128 v[158:161], v170
	ds_read_b128 v[162:165], v170 offset:1024
	ds_read_b128 v[166:169], v170 offset:2048
	ds_read_b128 v[170:173], v170 offset:3072
	ds_read_b128 v[180:183], v174
	ds_read_b128 v[190:193], v174 offset:1024
	ds_read_b128 v[194:197], v174 offset:2048
	ds_read_b128 v[198:201], v174 offset:3072
	s_and_b64 s[6:7], s[50:51], exec
	s_cselect_b32 s69, s13, s59
	s_cselect_b32 s68, s12, s58
	s_lshl_b64 s[6:7], s[62:63], 7
	s_add_u32 s12, s40, s6
	s_addc_u32 s13, s41, s7
	s_and_b64 s[6:7], s[50:51], exec
	s_cselect_b32 s53, s13, s61
	s_cselect_b32 s52, s12, s60
	s_add_u32 s50, s68, 0x8000
	s_addc_u32 s51, s69, 0
	s_add_u32 s4, s21, s4
	s_addc_u32 s5, s39, s5
	v_lshl_add_u64 v[174:175], s[4:5], 0, v[128:129]
	s_add_i32 m0, s74, 0xc000
	ds_read_b128 v[202:205], v179
	ds_read_b128 v[206:209], v179 offset:1024
	ds_read_b128 v[210:213], v179 offset:2048
	ds_read_b128 v[214:217], v179 offset:3072
	ds_read_b128 v[218:221], v179 offset:4096
	ds_read_b128 v[222:225], v179 offset:5120
	ds_read_b128 v[226:229], v179 offset:6144
	ds_read_b128 v[230:233], v179 offset:7168
	global_load_lds_dwordx4 v[174:175], off
	v_lshl_add_u64 v[174:175], s[4:5], 0, v[132:133]
	s_add_i32 m0, s74, 0xe000
	s_nop 0
	global_load_lds_dwordx4 v[174:175], off
	s_waitcnt vmcnt(8)
	s_waitcnt lgkmcnt(0)
	s_setprio 1
	s_barrier
	v_mfma_f32_16x16x32_bf16 v[124:127], v[158:161], v[202:205], v[124:127]
	v_mfma_f32_16x16x32_bf16 v[120:123], v[166:169], v[202:205], v[120:123]
	v_mfma_f32_16x16x32_bf16 v[116:119], v[158:161], v[210:213], v[116:119]
	v_mfma_f32_16x16x32_bf16 v[112:115], v[166:169], v[210:213], v[112:115]
	v_mfma_f32_16x16x32_bf16 v[108:111], v[158:161], v[218:221], v[108:111]
	v_mfma_f32_16x16x32_bf16 v[104:107], v[166:169], v[218:221], v[104:107]
	v_mfma_f32_16x16x32_bf16 v[100:103], v[158:161], v[226:229], v[100:103]
	v_mfma_f32_16x16x32_bf16 v[96:99], v[166:169], v[226:229], v[96:99]
	v_mfma_f32_16x16x32_bf16 v[124:127], v[162:165], v[206:209], v[124:127]
	v_mfma_f32_16x16x32_bf16 v[120:123], v[170:173], v[206:209], v[120:123]
	v_mfma_f32_16x16x32_bf16 v[116:119], v[162:165], v[214:217], v[116:119]
	v_mfma_f32_16x16x32_bf16 v[112:115], v[170:173], v[214:217], v[112:115]
	v_mfma_f32_16x16x32_bf16 v[108:111], v[162:165], v[222:225], v[108:111]
	v_mfma_f32_16x16x32_bf16 v[104:107], v[170:173], v[222:225], v[104:107]
	v_mfma_f32_16x16x32_bf16 v[100:103], v[162:165], v[230:233], v[100:103]
	v_mfma_f32_16x16x32_bf16 v[96:99], v[170:173], v[230:233], v[96:99]
	v_mfma_f32_16x16x32_bf16 v[92:95], v[180:183], v[202:205], v[92:95]
	v_mfma_f32_16x16x32_bf16 v[88:91], v[194:197], v[202:205], v[88:91]
	v_mfma_f32_16x16x32_bf16 v[84:87], v[180:183], v[210:213], v[84:87]
	v_mfma_f32_16x16x32_bf16 v[80:83], v[194:197], v[210:213], v[80:83]
	v_mfma_f32_16x16x32_bf16 v[76:79], v[180:183], v[218:221], v[76:79]
	v_mfma_f32_16x16x32_bf16 v[72:75], v[194:197], v[218:221], v[72:75]
	v_mfma_f32_16x16x32_bf16 v[68:71], v[180:183], v[226:229], v[68:71]
	v_mfma_f32_16x16x32_bf16 v[64:67], v[194:197], v[226:229], v[64:67]
	v_mfma_f32_16x16x32_bf16 v[92:95], v[190:193], v[206:209], v[92:95]
	v_mfma_f32_16x16x32_bf16 v[88:91], v[198:201], v[206:209], v[88:91]
	v_mfma_f32_16x16x32_bf16 v[84:87], v[190:193], v[214:217], v[84:87]
	v_mfma_f32_16x16x32_bf16 v[80:83], v[198:201], v[214:217], v[80:83]
	v_mfma_f32_16x16x32_bf16 v[76:79], v[190:193], v[222:225], v[76:79]
	v_mfma_f32_16x16x32_bf16 v[72:75], v[198:201], v[222:225], v[72:75]
	v_mfma_f32_16x16x32_bf16 v[68:71], v[190:193], v[230:233], v[68:71]
	v_mfma_f32_16x16x32_bf16 v[64:67], v[198:201], v[230:233], v[64:67]
	s_barrier
	s_setprio 0
	s_add_i32 s4, s10, s71
	v_lshl_add_u64 v[174:175], s[52:53], 0, v[130:131]
	s_mov_b32 m0, s4
	ds_read_b128 v[202:205], v179 offset:16384
	ds_read_b128 v[206:209], v179 offset:17408
	ds_read_b128 v[210:213], v179 offset:18432
	ds_read_b128 v[214:217], v179 offset:19456
	ds_read_b128 v[218:221], v179 offset:20480
	ds_read_b128 v[222:225], v179 offset:21504
	ds_read_b128 v[226:229], v179 offset:22528
	ds_read_b128 v[230:233], v179 offset:23552
	global_load_lds_dwordx4 v[174:175], off
	s_add_i32 m0, s4, 0x2000
	s_add_u32 s4, s52, 0x160000
	v_lshl_add_u64 v[234:235], s[52:53], 0, v[134:135]
	s_addc_u32 s5, s53, 0
	s_add_i32 s6, s11, s71
	global_load_lds_dwordx4 v[234:235], off
	v_lshl_add_u64 v[236:237], s[4:5], 0, v[130:131]
	s_mov_b32 m0, s6
	s_nop 0
	global_load_lds_dwordx4 v[236:237], off
	v_lshl_add_u64 v[236:237], s[4:5], 0, v[134:135]
	s_add_i32 m0, s6, 0x2000
	s_nop 0
	global_load_lds_dwordx4 v[236:237], off
	v_lshl_add_u64 v[236:237], s[68:69], 0, v[128:129]
	s_mov_b32 m0, s74
	s_nop 0
	global_load_lds_dwordx4 v[236:237], off
	v_lshl_add_u64 v[236:237], s[68:69], 0, v[132:133]
	s_mov_b32 m0, s76
	s_nop 0
	global_load_lds_dwordx4 v[236:237], off
	s_waitcnt vmcnt(8)
	s_waitcnt lgkmcnt(0)
	s_setprio 1
	s_barrier
; #define PG8_STAGE(bufoff, gbase, voff) do { _Pragma("unroll") for (int _i = 0; _i < 2; ++_i) \
;         __builtin_amdgcn_global_load_lds((const unsigned*)((const char*)(gbase) + (voff)[_i]), (PG8_LAS unsigned*)(lds + (bufoff) + ldsw + _i * 8192), 16, 0, 0); } while (0)
; #define PG8_LDA(dst, b, h) do { _Pragma("unroll") for (int m = 0; m < 4; ++m) _Pragma("unroll") for (int k = 0; k < 2; ++k) dst[m][k] = *(const PG8_LAS bf16x8*)(lds + PG8_SA(b, h) + aoff + m * 2048 + k * 1024); } while (0)
; #define PG8_LDB(dst, b, h) do { _Pragma("unroll") for (int n = 0; n < 2; ++n) _Pragma("unroll") for (int k = 0; k < 2; ++k) dst[n][k] = *(const PG8_LAS bf16x8*)(lds + PG8_SB(b, h) + boff + n * 2048 + k * 1024); } while (0)
; #define PG8_MMA(ai, bj, At, Bt) do { __builtin_amdgcn_s_setprio(1); _Pragma("unroll") for (int m = 0; m < 4; ++m) _Pragma("unroll") for (int n = 0; n < 2; ++n) _Pragma("unroll") for (int k = 0; k < 2; ++k) \
;         acc[ai][bj][m][n] = __builtin_amdgcn_mfma_f32_16x16x32_bf16(Bt[n][k], At[m][k], acc[ai][bj][m][n], 0, 0, 0); __builtin_amdgcn_s_setprio(0); } while (0)
; #define PG8_WAIT_V(n) asm volatile("s_waitcnt vmcnt(" #n ")" ::: "memory")
; #define PG8_WAIT_L(n) asm volatile("s_waitcnt lgkmcnt(" #n ")" ::: "memory")
; #define PG8_BAR __builtin_amdgcn_s_barrier()
; #define PG8_SCHED __builtin_amdgcn_sched_barrier(0)
; template <class Epi, class Sched, bool ALIGN_EPI = false, bool SP2 = false>
; __device__ __forceinline__ void gemm_phase(PG8_LAS unsigned char* lds, const Gemm g, const Sched& S, const Epi& E) {
;     ...
;             PG8_WAIT_V(8); PG8_WAIT_L(0); PG8_BAR; PG8_MMA(1, 0, At, B0); PG8_MMA(1, 1, At, B1); PG8_BAR; PG8_SCHED;
;             PG8_LDB(B0, 1, 0); PG8_LDB(B1, 1, 1); PG8_SCHED; PG8_LDA(At, 1, 0); PG8_STAGE(PG8_SA(0, 1), a2 + hstepA, voffA);
;             PG8_WAIT_V(8); PG8_WAIT_L(0); PG8_BAR; PG8_MMA(0, 0, At, B0); PG8_MMA(0, 1, At, B1); PG8_BAR; PG8_SCHED;
	v_mfma_f32_16x16x32_bf16 v[60:63], v[158:161], v[202:205], v[60:63]
	v_mfma_f32_16x16x32_bf16 v[56:59], v[166:169], v[202:205], v[56:59]
	v_mfma_f32_16x16x32_bf16 v[52:55], v[158:161], v[210:213], v[52:55]
	v_mfma_f32_16x16x32_bf16 v[48:51], v[166:169], v[210:213], v[48:51]
	v_mfma_f32_16x16x32_bf16 v[44:47], v[158:161], v[218:221], v[44:47]
	v_mfma_f32_16x16x32_bf16 v[40:43], v[166:169], v[218:221], v[40:43]
	v_mfma_f32_16x16x32_bf16 v[36:39], v[158:161], v[226:229], v[36:39]
	v_mfma_f32_16x16x32_bf16 v[32:35], v[166:169], v[226:229], v[32:35]
	v_mfma_f32_16x16x32_bf16 v[60:63], v[162:165], v[206:209], v[60:63]
	v_mfma_f32_16x16x32_bf16 v[56:59], v[170:173], v[206:209], v[56:59]
	v_mfma_f32_16x16x32_bf16 v[52:55], v[162:165], v[214:217], v[52:55]
	v_mfma_f32_16x16x32_bf16 v[48:51], v[170:173], v[214:217], v[48:51]
	v_mfma_f32_16x16x32_bf16 v[44:47], v[162:165], v[222:225], v[44:47]
	v_mfma_f32_16x16x32_bf16 v[40:43], v[170:173], v[222:225], v[40:43]
	v_mfma_f32_16x16x32_bf16 v[36:39], v[162:165], v[230:233], v[36:39]
	v_mfma_f32_16x16x32_bf16 v[32:35], v[170:173], v[230:233], v[32:35]
	v_mfma_f32_16x16x32_bf16 v[28:31], v[180:183], v[202:205], v[28:31]
	v_mfma_f32_16x16x32_bf16 v[24:27], v[194:197], v[202:205], v[24:27]
	v_mfma_f32_16x16x32_bf16 v[20:23], v[180:183], v[210:213], v[20:23]
	v_mfma_f32_16x16x32_bf16 v[16:19], v[194:197], v[210:213], v[16:19]
	v_mfma_f32_16x16x32_bf16 v[12:15], v[180:183], v[218:221], v[12:15]
	v_mfma_f32_16x16x32_bf16 v[8:11], v[194:197], v[218:221], v[8:11]
	v_mfma_f32_16x16x32_bf16 v[4:7], v[180:183], v[226:229], v[4:7]
	v_mfma_f32_16x16x32_bf16 v[0:3], v[194:197], v[226:229], v[0:3]
	v_mfma_f32_16x16x32_bf16 v[28:31], v[190:193], v[206:209], v[28:31]
	v_mfma_f32_16x16x32_bf16 v[24:27], v[198:201], v[206:209], v[24:27]
	v_mfma_f32_16x16x32_bf16 v[20:23], v[190:193], v[214:217], v[20:23]
	v_mfma_f32_16x16x32_bf16 v[16:19], v[198:201], v[214:217], v[16:19]
	v_mfma_f32_16x16x32_bf16 v[12:15], v[190:193], v[222:225], v[12:15]
	v_mfma_f32_16x16x32_bf16 v[8:11], v[198:201], v[222:225], v[8:11]
	v_mfma_f32_16x16x32_bf16 v[4:7], v[190:193], v[230:233], v[4:7]
	v_mfma_f32_16x16x32_bf16 v[0:3], v[198:201], v[230:233], v[0:3]
	s_barrier
	s_setprio 0
	s_add_i32 s6, 0, 0x18000
	s_add_i32 s7, 0, 0x1c000
	v_add_u32_e32 v170, s6, v177
	v_add_u32_e32 v198, s7, v177
	ds_read_b128 v[158:161], v170
	ds_read_b128 v[162:165], v170 offset:1024
	ds_read_b128 v[166:169], v170 offset:2048
	ds_read_b128 v[170:173], v170 offset:3072
	ds_read_b128 v[180:183], v198
	ds_read_b128 v[190:193], v198 offset:1024
	ds_read_b128 v[194:197], v198 offset:2048
	ds_read_b128 v[198:201], v198 offset:3072
	s_add_u32 s4, s68, 0x4000
	s_addc_u32 s5, s69, 0
	s_mov_b32 m0, s77
	v_lshl_add_u64 v[236:237], s[4:5], 0, v[128:129]
	ds_read_b128 v[202:205], v179 offset:32768
	ds_read_b128 v[206:209], v179 offset:33792
	ds_read_b128 v[210:213], v179 offset:34816
	ds_read_b128 v[214:217], v179 offset:35840
	ds_read_b128 v[218:221], v179 offset:36864
	ds_read_b128 v[222:225], v179 offset:37888
	ds_read_b128 v[226:229], v179 offset:38912
	ds_read_b128 v[230:233], v179 offset:39936
	global_load_lds_dwordx4 v[236:237], off
	v_lshl_add_u64 v[236:237], s[4:5], 0, v[132:133]
	s_mov_b32 m0, s75
	s_nop 0
	global_load_lds_dwordx4 v[236:237], off
	s_waitcnt vmcnt(8)
	s_waitcnt lgkmcnt(0)
	s_setprio 1
	s_barrier
	v_mfma_f32_16x16x32_bf16 v[124:127], v[158:161], v[202:205], v[124:127]
	v_mfma_f32_16x16x32_bf16 v[120:123], v[166:169], v[202:205], v[120:123]
	v_mfma_f32_16x16x32_bf16 v[116:119], v[158:161], v[210:213], v[116:119]
	v_mfma_f32_16x16x32_bf16 v[112:115], v[166:169], v[210:213], v[112:115]
	v_mfma_f32_16x16x32_bf16 v[108:111], v[158:161], v[218:221], v[108:111]
	v_mfma_f32_16x16x32_bf16 v[104:107], v[166:169], v[218:221], v[104:107]
	v_mfma_f32_16x16x32_bf16 v[100:103], v[158:161], v[226:229], v[100:103]
	v_mfma_f32_16x16x32_bf16 v[96:99], v[166:169], v[226:229], v[96:99]
	v_mfma_f32_16x16x32_bf16 v[124:127], v[162:165], v[206:209], v[124:127]
	v_mfma_f32_16x16x32_bf16 v[120:123], v[170:173], v[206:209], v[120:123]
	v_mfma_f32_16x16x32_bf16 v[116:119], v[162:165], v[214:217], v[116:119]
	v_mfma_f32_16x16x32_bf16 v[112:115], v[170:173], v[214:217], v[112:115]
	v_mfma_f32_16x16x32_bf16 v[108:111], v[162:165], v[222:225], v[108:111]
	v_mfma_f32_16x16x32_bf16 v[104:107], v[170:173], v[222:225], v[104:107]
	v_mfma_f32_16x16x32_bf16 v[100:103], v[162:165], v[230:233], v[100:103]
	v_mfma_f32_16x16x32_bf16 v[96:99], v[170:173], v[230:233], v[96:99]
	v_mfma_f32_16x16x32_bf16 v[92:95], v[180:183], v[202:205], v[92:95]
	v_mfma_f32_16x16x32_bf16 v[88:91], v[194:197], v[202:205], v[88:91]
	v_mfma_f32_16x16x32_bf16 v[84:87], v[180:183], v[210:213], v[84:87]
	v_mfma_f32_16x16x32_bf16 v[80:83], v[194:197], v[210:213], v[80:83]
	v_mfma_f32_16x16x32_bf16 v[76:79], v[180:183], v[218:221], v[76:79]
	v_mfma_f32_16x16x32_bf16 v[72:75], v[194:197], v[218:221], v[72:75]
	v_mfma_f32_16x16x32_bf16 v[68:71], v[180:183], v[226:229], v[68:71]
	v_mfma_f32_16x16x32_bf16 v[64:67], v[194:197], v[226:229], v[64:67]
	v_mfma_f32_16x16x32_bf16 v[92:95], v[190:193], v[206:209], v[92:95]
	v_mfma_f32_16x16x32_bf16 v[88:91], v[198:201], v[206:209], v[88:91]
	v_mfma_f32_16x16x32_bf16 v[84:87], v[190:193], v[214:217], v[84:87]
	v_mfma_f32_16x16x32_bf16 v[80:83], v[198:201], v[214:217], v[80:83]
	v_mfma_f32_16x16x32_bf16 v[76:79], v[190:193], v[222:225], v[76:79]
	v_mfma_f32_16x16x32_bf16 v[72:75], v[198:201], v[222:225], v[72:75]
	v_mfma_f32_16x16x32_bf16 v[68:71], v[190:193], v[230:233], v[68:71]
	v_mfma_f32_16x16x32_bf16 v[64:67], v[198:201], v[230:233], v[64:67]
	s_barrier
; #define PG8_STAGE(bufoff, gbase, voff) do { _Pragma("unroll") for (int _i = 0; _i < 2; ++_i) \
;         __builtin_amdgcn_global_load_lds((const unsigned*)((const char*)(gbase) + (voff)[_i]), (PG8_LAS unsigned*)(lds + (bufoff) + ldsw + _i * 8192), 16, 0, 0); } while (0)
; #define PG8_LDA(dst, b, h) do { _Pragma("unroll") for (int m = 0; m < 4; ++m) _Pragma("unroll") for (int k = 0; k < 2; ++k) dst[m][k] = *(const PG8_LAS bf16x8*)(lds + PG8_SA(b, h) + aoff + m * 2048 + k * 1024); } while (0)
; #define PG8_MMA(ai, bj, At, Bt) do { __builtin_amdgcn_s_setprio(1); _Pragma("unroll") for (int m = 0; m < 4; ++m) _Pragma("unroll") for (int n = 0; n < 2; ++n) _Pragma("unroll") for (int k = 0; k < 2; ++k) \
;         acc[ai][bj][m][n] = __builtin_amdgcn_mfma_f32_16x16x32_bf16(Bt[n][k], At[m][k], acc[ai][bj][m][n], 0, 0, 0); __builtin_amdgcn_s_setprio(0); } while (0)
; #define PG8_WAIT_V(n) asm volatile("s_waitcnt vmcnt(" #n ")" ::: "memory")
; #define PG8_WAIT_L(n) asm volatile("s_waitcnt lgkmcnt(" #n ")" ::: "memory")
; #define PG8_BAR __builtin_amdgcn_s_barrier()
; #define PG8_SCHED __builtin_amdgcn_sched_barrier(0)
; template <class Epi, class Sched, bool ALIGN_EPI = false, bool SP2 = false>
; __device__ __forceinline__ void gemm_phase(PG8_LAS unsigned char* lds, const Gemm g, const Sched& S, const Epi& E) {
;     ...
;         for (int t = 0; t < nt; t += 2) {
;     ...
;             PG8_LDA(At, 1, 1); PG8_STAGE(PG8_SB(1, 0), b3, voffB); PG8_STAGE(PG8_SB(1, 1), b3 + hstepB, voffB); PG8_STAGE(PG8_SA(1, 0), a3, voffA);
;             PG8_WAIT_V(8); PG8_WAIT_L(0); PG8_BAR; PG8_MMA(1, 0, At, B0); PG8_MMA(1, 1, At, B1); PG8_BAR; PG8_SCHED;
	s_setprio 0
	s_add_i32 s4, s6, s71
	v_lshl_add_u64 v[174:175], v[174:175], 0, s[54:55]
	s_mov_b32 m0, s4
	ds_read_b128 v[202:205], v179 offset:49152
	ds_read_b128 v[206:209], v179 offset:50176
	ds_read_b128 v[210:213], v179 offset:51200
	ds_read_b128 v[214:217], v179 offset:52224
	ds_read_b128 v[218:221], v179 offset:53248
	ds_read_b128 v[222:225], v179 offset:54272
	ds_read_b128 v[226:229], v179 offset:55296
	ds_read_b128 v[230:233], v179 offset:56320
	global_load_lds_dwordx4 v[174:175], off
	s_add_i32 m0, s4, 0x2000
	s_add_u32 s4, s52, 0x160080
	v_lshl_add_u64 v[174:175], v[234:235], 0, s[54:55]
	s_addc_u32 s5, s53, 0
	s_add_i32 s6, s7, s71
	global_load_lds_dwordx4 v[174:175], off
	v_lshl_add_u64 v[174:175], s[4:5], 0, v[130:131]
	s_mov_b32 m0, s6
	s_nop 0
	global_load_lds_dwordx4 v[174:175], off
	v_lshl_add_u64 v[174:175], s[4:5], 0, v[134:135]
	s_add_i32 m0, s6, 0x2000
	s_nop 0
	global_load_lds_dwordx4 v[174:175], off
	v_lshl_add_u64 v[174:175], s[50:51], 0, v[128:129]
	s_mov_b32 m0, s95
	s_nop 0
	global_load_lds_dwordx4 v[174:175], off
	v_lshl_add_u64 v[174:175], s[50:51], 0, v[132:133]
	s_mov_b32 m0, s96
	s_nop 0
	global_load_lds_dwordx4 v[174:175], off
	s_waitcnt vmcnt(8)
	s_waitcnt lgkmcnt(0)
	s_setprio 1
	s_barrier
	v_mfma_f32_16x16x32_bf16 v[60:63], v[158:161], v[202:205], v[60:63]
	v_mfma_f32_16x16x32_bf16 v[56:59], v[166:169], v[202:205], v[56:59]
	v_mfma_f32_16x16x32_bf16 v[52:55], v[158:161], v[210:213], v[52:55]
	v_mfma_f32_16x16x32_bf16 v[48:51], v[166:169], v[210:213], v[48:51]
	v_mfma_f32_16x16x32_bf16 v[44:47], v[158:161], v[218:221], v[44:47]
	v_mfma_f32_16x16x32_bf16 v[40:43], v[166:169], v[218:221], v[40:43]
	v_mfma_f32_16x16x32_bf16 v[36:39], v[158:161], v[226:229], v[36:39]
	v_mfma_f32_16x16x32_bf16 v[32:35], v[166:169], v[226:229], v[32:35]
	v_mfma_f32_16x16x32_bf16 v[60:63], v[162:165], v[206:209], v[60:63]
	v_mfma_f32_16x16x32_bf16 v[56:59], v[170:173], v[206:209], v[56:59]
	v_mfma_f32_16x16x32_bf16 v[52:55], v[162:165], v[214:217], v[52:55]
	v_mfma_f32_16x16x32_bf16 v[48:51], v[170:173], v[214:217], v[48:51]
	v_mfma_f32_16x16x32_bf16 v[44:47], v[162:165], v[222:225], v[44:47]
	v_mfma_f32_16x16x32_bf16 v[40:43], v[170:173], v[222:225], v[40:43]
	v_mfma_f32_16x16x32_bf16 v[36:39], v[162:165], v[230:233], v[36:39]
	v_mfma_f32_16x16x32_bf16 v[32:35], v[170:173], v[230:233], v[32:35]
	v_mfma_f32_16x16x32_bf16 v[28:31], v[180:183], v[202:205], v[28:31]
	v_mfma_f32_16x16x32_bf16 v[24:27], v[194:197], v[202:205], v[24:27]
	v_mfma_f32_16x16x32_bf16 v[20:23], v[180:183], v[210:213], v[20:23]
	v_mfma_f32_16x16x32_bf16 v[16:19], v[194:197], v[210:213], v[16:19]
	v_mfma_f32_16x16x32_bf16 v[12:15], v[180:183], v[218:221], v[12:15]
	v_mfma_f32_16x16x32_bf16 v[8:11], v[194:197], v[218:221], v[8:11]
	v_mfma_f32_16x16x32_bf16 v[4:7], v[180:183], v[226:229], v[4:7]
	v_mfma_f32_16x16x32_bf16 v[0:3], v[194:197], v[226:229], v[0:3]
	v_mfma_f32_16x16x32_bf16 v[28:31], v[190:193], v[206:209], v[28:31]
	v_mfma_f32_16x16x32_bf16 v[24:27], v[198:201], v[206:209], v[24:27]
	v_mfma_f32_16x16x32_bf16 v[20:23], v[190:193], v[214:217], v[20:23]
	v_mfma_f32_16x16x32_bf16 v[16:19], v[198:201], v[214:217], v[16:19]
	v_mfma_f32_16x16x32_bf16 v[12:15], v[190:193], v[222:225], v[12:15]
	v_mfma_f32_16x16x32_bf16 v[8:11], v[198:201], v[222:225], v[8:11]
	v_mfma_f32_16x16x32_bf16 v[4:7], v[190:193], v[230:233], v[4:7]
	v_mfma_f32_16x16x32_bf16 v[0:3], v[198:201], v[230:233], v[0:3]
	s_barrier
	s_setprio 0
	s_cmp_ge_i32 s62, s97
	s_cbranch_scc1 .LBB0_1766

; #define PG8_STAGE(bufoff, gbase, voff) do { _Pragma("unroll") for (int _i = 0; _i < 2; ++_i) \
;         __builtin_amdgcn_global_load_lds((const unsigned*)((const char*)(gbase) + (voff)[_i]), (PG8_LAS unsigned*)(lds + (bufoff) + ldsw + _i * 8192), 16, 0, 0); } while (0)
; #define PG8_LDA(dst, b, h) do { _Pragma("unroll") for (int m = 0; m < 4; ++m) _Pragma("unroll") for (int k = 0; k < 2; ++k) dst[m][k] = *(const PG8_LAS bf16x8*)(lds + PG8_SA(b, h) + aoff + m * 2048 + k * 1024); } while (0)
; #define PG8_LDB(dst, b, h) do { _Pragma("unroll") for (int n = 0; n < 2; ++n) _Pragma("unroll") for (int k = 0; k < 2; ++k) dst[n][k] = *(const PG8_LAS bf16x8*)(lds + PG8_SB(b, h) + boff + n * 2048 + k * 1024); } while (0)
; #define PG8_MMA(ai, bj, At, Bt) do { __builtin_amdgcn_s_setprio(1); _Pragma("unroll") for (int m = 0; m < 4; ++m) _Pragma("unroll") for (int n = 0; n < 2; ++n) _Pragma("unroll") for (int k = 0; k < 2; ++k) \
;         acc[ai][bj][m][n] = __builtin_amdgcn_mfma_f32_16x16x32_bf16(Bt[n][k], At[m][k], acc[ai][bj][m][n], 0, 0, 0); __builtin_amdgcn_s_setprio(0); } while (0)
; #define PG8_WAIT_V(n) asm volatile("s_waitcnt vmcnt(" #n ")" ::: "memory")
; #define PG8_WAIT_L(n) asm volatile("s_waitcnt lgkmcnt(" #n ")" ::: "memory")
; #define PG8_BAR __builtin_amdgcn_s_barrier()
; #define PG8_SCHED __builtin_amdgcn_sched_barrier(0)
; template <class Epi, class Sched, bool ALIGN_EPI = false, bool SP2 = false>
; __device__ __forceinline__ void gemm_phase(PG8_LAS unsigned char* lds, const Gemm g, const Sched& S, const Epi& E) {
;     ...
;             const char* a1 = cA + (size_t)(t + 1) * kstA;
;             const char* a2 = last ? nA : cA + (size_t)(t + 2) * kstA; const char* b2 = last ? nB : cB + (size_t)(t + 2) * kstep;
;             const char* a3 = a2 + kstA; const char* b3 = b2 + kstep;
;             if (last && has_next) S.a_ready(nxt);
;             if constexpr (SP2) {
;             PG8_LDB(B0, 0, 0); PG8_LDB(B1, 0, 1); PG8_SCHED; PG8_LDA(At, 0, 0); PG8_STAGE(PG8_SA(1, 1), a1 + hstepA, voffA);
;             PG8_WAIT_V(8); PG8_WAIT_L(0); PG8_BAR; PG8_MMA(0, 0, At, B0); PG8_MMA(0, 1, At, B1); PG8_BAR; PG8_SCHED;
;             PG8_LDA(At, 0, 1); PG8_STAGE(PG8_SB(0, 0), b2, voffB); PG8_STAGE(PG8_SB(0, 1), b2 + hstepB, voffB); PG8_STAGE(PG8_SA(0, 0), a2, voffA);
.LBB0_2050:
	ds_read_b128 v[128:131], v159
	ds_read_b128 v[132:135], v159 offset:1024
	ds_read_b128 v[164:167], v159 offset:2048
	ds_read_b128 v[168:171], v159 offset:3072
	ds_read_b128 v[172:175], v160
	ds_read_b128 v[176:179], v160 offset:1024
	ds_read_b128 v[180:183], v160 offset:2048
	ds_read_b128 v[190:193], v160 offset:3072
	s_add_u32 s13, s20, 0xfff80080
	s_addc_u32 s33, s21, -1
	s_cmp_eq_u32 s12, 28
	s_cselect_b32 s41, s1, s33
	s_cselect_b32 s40, s3, s13
	s_cselect_b32 s39, s4, s11
	s_cselect_b32 s38, s5, s10
	v_lshl_add_u64 v[226:227], s[20:21], 0, v[148:149]
	s_add_i32 m0, s7, 0xc000
	ds_read_b128 v[194:197], v161
	ds_read_b128 v[198:201], v161 offset:1024
	ds_read_b128 v[202:205], v161 offset:2048
	ds_read_b128 v[206:209], v161 offset:3072
	ds_read_b128 v[210:213], v161 offset:4096
	ds_read_b128 v[214:217], v161 offset:5120
	ds_read_b128 v[218:221], v161 offset:6144
	ds_read_b128 v[222:225], v161 offset:7168
	global_load_lds_dwordx4 v[226:227], off
	v_lshl_add_u64 v[226:227], s[20:21], 0, v[150:151]
	s_add_i32 m0, s7, 0xe000
	s_nop 0
	global_load_lds_dwordx4 v[226:227], off
	s_waitcnt vmcnt(8)
	s_waitcnt lgkmcnt(0)
	s_setprio 1
	s_barrier
	v_mfma_f32_16x16x32_bf16 v[124:127], v[128:131], v[194:197], v[124:127]
	v_mfma_f32_16x16x32_bf16 v[120:123], v[164:167], v[194:197], v[120:123]
	v_mfma_f32_16x16x32_bf16 v[108:111], v[128:131], v[202:205], v[108:111]
	v_mfma_f32_16x16x32_bf16 v[104:107], v[164:167], v[202:205], v[104:107]
	v_mfma_f32_16x16x32_bf16 v[92:95], v[128:131], v[210:213], v[92:95]
	v_mfma_f32_16x16x32_bf16 v[88:91], v[164:167], v[210:213], v[88:91]
	v_mfma_f32_16x16x32_bf16 v[76:79], v[128:131], v[218:221], v[76:79]
	v_mfma_f32_16x16x32_bf16 v[72:75], v[164:167], v[218:221], v[72:75]
	v_mfma_f32_16x16x32_bf16 v[124:127], v[132:135], v[198:201], v[124:127]
	v_mfma_f32_16x16x32_bf16 v[120:123], v[168:171], v[198:201], v[120:123]
	v_mfma_f32_16x16x32_bf16 v[108:111], v[132:135], v[206:209], v[108:111]
	v_mfma_f32_16x16x32_bf16 v[104:107], v[168:171], v[206:209], v[104:107]
	v_mfma_f32_16x16x32_bf16 v[92:95], v[132:135], v[214:217], v[92:95]
	v_mfma_f32_16x16x32_bf16 v[88:91], v[168:171], v[214:217], v[88:91]
	v_mfma_f32_16x16x32_bf16 v[76:79], v[132:135], v[222:225], v[76:79]
	v_mfma_f32_16x16x32_bf16 v[72:75], v[168:171], v[222:225], v[72:75]
	v_mfma_f32_16x16x32_bf16 v[116:119], v[172:175], v[194:197], v[116:119]
	v_mfma_f32_16x16x32_bf16 v[112:115], v[180:183], v[194:197], v[112:115]
	v_mfma_f32_16x16x32_bf16 v[100:103], v[172:175], v[202:205], v[100:103]
	v_mfma_f32_16x16x32_bf16 v[96:99], v[180:183], v[202:205], v[96:99]
	v_mfma_f32_16x16x32_bf16 v[84:87], v[172:175], v[210:213], v[84:87]
	v_mfma_f32_16x16x32_bf16 v[80:83], v[180:183], v[210:213], v[80:83]
	v_mfma_f32_16x16x32_bf16 v[68:71], v[172:175], v[218:221], v[68:71]
	v_mfma_f32_16x16x32_bf16 v[64:67], v[180:183], v[218:221], v[64:67]
	v_mfma_f32_16x16x32_bf16 v[116:119], v[176:179], v[198:201], v[116:119]
	v_mfma_f32_16x16x32_bf16 v[112:115], v[190:193], v[198:201], v[112:115]
	v_mfma_f32_16x16x32_bf16 v[100:103], v[176:179], v[206:209], v[100:103]
	v_mfma_f32_16x16x32_bf16 v[96:99], v[190:193], v[206:209], v[96:99]
	v_mfma_f32_16x16x32_bf16 v[84:87], v[176:179], v[214:217], v[84:87]
	v_mfma_f32_16x16x32_bf16 v[80:83], v[190:193], v[214:217], v[80:83]
	v_mfma_f32_16x16x32_bf16 v[68:71], v[176:179], v[222:225], v[68:71]
	v_mfma_f32_16x16x32_bf16 v[64:67], v[190:193], v[222:225], v[64:67]
	s_barrier
	s_setprio 0
	s_add_i32 s13, s69, s6
	v_lshl_add_u64 v[226:227], s[38:39], 0, v[138:139]
	s_mov_b32 m0, s13
	ds_read_b128 v[194:197], v161 offset:16384
	ds_read_b128 v[198:201], v161 offset:17408
	ds_read_b128 v[202:205], v161 offset:18432
	ds_read_b128 v[206:209], v161 offset:19456
	ds_read_b128 v[210:213], v161 offset:20480
	ds_read_b128 v[214:217], v161 offset:21504
	ds_read_b128 v[218:221], v161 offset:22528
	ds_read_b128 v[222:225], v161 offset:23552
	global_load_lds_dwordx4 v[226:227], off
	s_add_i32 m0, s13, 0x2000
	s_add_u32 s44, s38, 0x80000
	v_lshl_add_u64 v[228:229], s[38:39], 0, v[142:143]
	s_addc_u32 s45, s39, 0
	s_add_i32 s13, s70, s6
	global_load_lds_dwordx4 v[228:229], off
	v_lshl_add_u64 v[230:231], s[44:45], 0, v[138:139]
	s_mov_b32 m0, s13
	v_lshl_add_u64 v[232:233], s[40:41], 0, v[140:141]
	global_load_lds_dwordx4 v[230:231], off
	v_lshl_add_u64 v[230:231], s[44:45], 0, v[142:143]
	s_add_i32 m0, s13, 0x2000
	s_nop 0
	global_load_lds_dwordx4 v[230:231], off
	v_lshl_add_u64 v[230:231], s[40:41], 0, v[136:137]
	s_mov_b32 m0, s7
	s_nop 0
	global_load_lds_dwordx4 v[230:231], off
	s_mov_b32 m0, s8
	s_nop 0
	global_load_lds_dwordx4 v[232:233], off
	s_waitcnt vmcnt(8)
	s_waitcnt lgkmcnt(0)
	s_setprio 1
	s_barrier
; #define PG8_STAGE(bufoff, gbase, voff) do { _Pragma("unroll") for (int _i = 0; _i < 2; ++_i) \
;         __builtin_amdgcn_global_load_lds((const unsigned*)((const char*)(gbase) + (voff)[_i]), (PG8_LAS unsigned*)(lds + (bufoff) + ldsw + _i * 8192), 16, 0, 0); } while (0)
; #define PG8_LDA(dst, b, h) do { _Pragma("unroll") for (int m = 0; m < 4; ++m) _Pragma("unroll") for (int k = 0; k < 2; ++k) dst[m][k] = *(const PG8_LAS bf16x8*)(lds + PG8_SA(b, h) + aoff + m * 2048 + k * 1024); } while (0)
; #define PG8_LDB(dst, b, h) do { _Pragma("unroll") for (int n = 0; n < 2; ++n) _Pragma("unroll") for (int k = 0; k < 2; ++k) dst[n][k] = *(const PG8_LAS bf16x8*)(lds + PG8_SB(b, h) + boff + n * 2048 + k * 1024); } while (0)
; #define PG8_MMA(ai, bj, At, Bt) do { __builtin_amdgcn_s_setprio(1); _Pragma("unroll") for (int m = 0; m < 4; ++m) _Pragma("unroll") for (int n = 0; n < 2; ++n) _Pragma("unroll") for (int k = 0; k < 2; ++k) \
;         acc[ai][bj][m][n] = __builtin_amdgcn_mfma_f32_16x16x32_bf16(Bt[n][k], At[m][k], acc[ai][bj][m][n], 0, 0, 0); __builtin_amdgcn_s_setprio(0); } while (0)
; #define PG8_WAIT_V(n) asm volatile("s_waitcnt vmcnt(" #n ")" ::: "memory")
; #define PG8_WAIT_L(n) asm volatile("s_waitcnt lgkmcnt(" #n ")" ::: "memory")
; #define PG8_BAR __builtin_amdgcn_s_barrier()
; #define PG8_SCHED __builtin_amdgcn_sched_barrier(0)
; template <class Epi, class Sched, bool ALIGN_EPI = false, bool SP2 = false>
; __device__ __forceinline__ void gemm_phase(PG8_LAS unsigned char* lds, const Gemm g, const Sched& S, const Epi& E) {
;     ...
;             PG8_WAIT_V(8); PG8_WAIT_L(0); PG8_BAR; PG8_MMA(1, 0, At, B0); PG8_MMA(1, 1, At, B1); PG8_BAR; PG8_SCHED;
;             PG8_LDB(B0, 1, 0); PG8_LDB(B1, 1, 1); PG8_SCHED; PG8_LDA(At, 1, 0); PG8_STAGE(PG8_SA(0, 1), a2 + hstepA, voffA);
;             PG8_WAIT_V(8); PG8_WAIT_L(0); PG8_BAR; PG8_MMA(0, 0, At, B0); PG8_MMA(0, 1, At, B1); PG8_BAR; PG8_SCHED;
	v_mfma_f32_16x16x32_bf16 v[60:63], v[128:131], v[194:197], v[60:63]
	v_mfma_f32_16x16x32_bf16 v[56:59], v[164:167], v[194:197], v[56:59]
	v_mfma_f32_16x16x32_bf16 v[44:47], v[128:131], v[202:205], v[44:47]
	v_mfma_f32_16x16x32_bf16 v[40:43], v[164:167], v[202:205], v[40:43]
	v_mfma_f32_16x16x32_bf16 v[28:31], v[128:131], v[210:213], v[28:31]
	v_mfma_f32_16x16x32_bf16 v[24:27], v[164:167], v[210:213], v[24:27]
	v_mfma_f32_16x16x32_bf16 v[12:15], v[128:131], v[218:221], v[12:15]
	v_mfma_f32_16x16x32_bf16 v[8:11], v[164:167], v[218:221], v[8:11]
	v_mfma_f32_16x16x32_bf16 v[60:63], v[132:135], v[198:201], v[60:63]
	v_mfma_f32_16x16x32_bf16 v[56:59], v[168:171], v[198:201], v[56:59]
	v_mfma_f32_16x16x32_bf16 v[44:47], v[132:135], v[206:209], v[44:47]
	v_mfma_f32_16x16x32_bf16 v[40:43], v[168:171], v[206:209], v[40:43]
	v_mfma_f32_16x16x32_bf16 v[28:31], v[132:135], v[214:217], v[28:31]
	v_mfma_f32_16x16x32_bf16 v[24:27], v[168:171], v[214:217], v[24:27]
	v_mfma_f32_16x16x32_bf16 v[12:15], v[132:135], v[222:225], v[12:15]
	v_mfma_f32_16x16x32_bf16 v[8:11], v[168:171], v[222:225], v[8:11]
	v_mfma_f32_16x16x32_bf16 v[52:55], v[172:175], v[194:197], v[52:55]
	v_mfma_f32_16x16x32_bf16 v[48:51], v[180:183], v[194:197], v[48:51]
	v_mfma_f32_16x16x32_bf16 v[36:39], v[172:175], v[202:205], v[36:39]
	v_mfma_f32_16x16x32_bf16 v[32:35], v[180:183], v[202:205], v[32:35]
	v_mfma_f32_16x16x32_bf16 v[20:23], v[172:175], v[210:213], v[20:23]
	v_mfma_f32_16x16x32_bf16 v[16:19], v[180:183], v[210:213], v[16:19]
	v_mfma_f32_16x16x32_bf16 v[4:7], v[172:175], v[218:221], v[4:7]
	v_mfma_f32_16x16x32_bf16 v[0:3], v[180:183], v[218:221], v[0:3]
	v_mfma_f32_16x16x32_bf16 v[52:55], v[176:179], v[198:201], v[52:55]
	v_mfma_f32_16x16x32_bf16 v[48:51], v[190:193], v[198:201], v[48:51]
	v_mfma_f32_16x16x32_bf16 v[36:39], v[176:179], v[206:209], v[36:39]
	v_mfma_f32_16x16x32_bf16 v[32:35], v[190:193], v[206:209], v[32:35]
	v_mfma_f32_16x16x32_bf16 v[20:23], v[176:179], v[214:217], v[20:23]
	v_mfma_f32_16x16x32_bf16 v[16:19], v[190:193], v[214:217], v[16:19]
	v_mfma_f32_16x16x32_bf16 v[4:7], v[176:179], v[222:225], v[4:7]
	v_mfma_f32_16x16x32_bf16 v[0:3], v[190:193], v[222:225], v[0:3]
	s_barrier
	s_setprio 0
	s_add_i32 s13, 0, 0x18000
	v_add_u32_e32 v144, s13, v157
	s_add_i32 s33, 0, 0x1c000
	ds_read_b128 v[128:131], v144
	ds_read_b128 v[132:135], v144 offset:1024
	ds_read_b128 v[164:167], v144 offset:2048
	ds_read_b128 v[168:171], v144 offset:3072
	v_add_u32_e32 v144, s33, v157
	ds_read_b128 v[172:175], v144
	ds_read_b128 v[176:179], v144 offset:1024
	ds_read_b128 v[180:183], v144 offset:2048
	ds_read_b128 v[190:193], v144 offset:3072
	s_add_u32 s40, s40, 0x80000
	s_addc_u32 s41, s41, 0
	s_mov_b32 m0, s9
	v_lshl_add_u64 v[234:235], s[40:41], 0, v[136:137]
	ds_read_b128 v[194:197], v161 offset:32768
	ds_read_b128 v[198:201], v161 offset:33792
	ds_read_b128 v[202:205], v161 offset:34816
	ds_read_b128 v[206:209], v161 offset:35840
	ds_read_b128 v[210:213], v161 offset:36864
	ds_read_b128 v[214:217], v161 offset:37888
	ds_read_b128 v[218:221], v161 offset:38912
	ds_read_b128 v[222:225], v161 offset:39936
	global_load_lds_dwordx4 v[234:235], off
	v_lshl_add_u64 v[234:235], s[40:41], 0, v[140:141]
	s_mov_b32 m0, s35
	s_nop 0
	global_load_lds_dwordx4 v[234:235], off
	s_waitcnt vmcnt(8)
	s_waitcnt lgkmcnt(0)
	s_setprio 1
	s_barrier
	v_mfma_f32_16x16x32_bf16 v[124:127], v[128:131], v[194:197], v[124:127]
	v_mfma_f32_16x16x32_bf16 v[120:123], v[164:167], v[194:197], v[120:123]
	v_mfma_f32_16x16x32_bf16 v[108:111], v[128:131], v[202:205], v[108:111]
	v_mfma_f32_16x16x32_bf16 v[104:107], v[164:167], v[202:205], v[104:107]
	v_mfma_f32_16x16x32_bf16 v[92:95], v[128:131], v[210:213], v[92:95]
	v_mfma_f32_16x16x32_bf16 v[88:91], v[164:167], v[210:213], v[88:91]
	v_mfma_f32_16x16x32_bf16 v[76:79], v[128:131], v[218:221], v[76:79]
	v_mfma_f32_16x16x32_bf16 v[72:75], v[164:167], v[218:221], v[72:75]
	v_mfma_f32_16x16x32_bf16 v[124:127], v[132:135], v[198:201], v[124:127]
	v_mfma_f32_16x16x32_bf16 v[120:123], v[168:171], v[198:201], v[120:123]
	v_mfma_f32_16x16x32_bf16 v[108:111], v[132:135], v[206:209], v[108:111]
	v_mfma_f32_16x16x32_bf16 v[104:107], v[168:171], v[206:209], v[104:107]
	v_mfma_f32_16x16x32_bf16 v[92:95], v[132:135], v[214:217], v[92:95]
	v_mfma_f32_16x16x32_bf16 v[88:91], v[168:171], v[214:217], v[88:91]
	v_mfma_f32_16x16x32_bf16 v[76:79], v[132:135], v[222:225], v[76:79]
	v_mfma_f32_16x16x32_bf16 v[72:75], v[168:171], v[222:225], v[72:75]
	v_mfma_f32_16x16x32_bf16 v[116:119], v[172:175], v[194:197], v[116:119]
	v_mfma_f32_16x16x32_bf16 v[112:115], v[180:183], v[194:197], v[112:115]
	v_mfma_f32_16x16x32_bf16 v[100:103], v[172:175], v[202:205], v[100:103]
	v_mfma_f32_16x16x32_bf16 v[96:99], v[180:183], v[202:205], v[96:99]
	v_mfma_f32_16x16x32_bf16 v[84:87], v[172:175], v[210:213], v[84:87]
	v_mfma_f32_16x16x32_bf16 v[80:83], v[180:183], v[210:213], v[80:83]
	v_mfma_f32_16x16x32_bf16 v[68:71], v[172:175], v[218:221], v[68:71]
	v_mfma_f32_16x16x32_bf16 v[64:67], v[180:183], v[218:221], v[64:67]
	v_mfma_f32_16x16x32_bf16 v[116:119], v[176:179], v[198:201], v[116:119]
	v_mfma_f32_16x16x32_bf16 v[112:115], v[190:193], v[198:201], v[112:115]
	v_mfma_f32_16x16x32_bf16 v[100:103], v[176:179], v[206:209], v[100:103]
	v_mfma_f32_16x16x32_bf16 v[96:99], v[190:193], v[206:209], v[96:99]
	v_mfma_f32_16x16x32_bf16 v[84:87], v[176:179], v[214:217], v[84:87]
	v_mfma_f32_16x16x32_bf16 v[80:83], v[190:193], v[214:217], v[80:83]
	v_mfma_f32_16x16x32_bf16 v[68:71], v[176:179], v[222:225], v[68:71]
	v_mfma_f32_16x16x32_bf16 v[64:67], v[190:193], v[222:225], v[64:67]
	s_barrier
; #define PG8_STAGE(bufoff, gbase, voff) do { _Pragma("unroll") for (int _i = 0; _i < 2; ++_i) \
;         __builtin_amdgcn_global_load_lds((const unsigned*)((const char*)(gbase) + (voff)[_i]), (PG8_LAS unsigned*)(lds + (bufoff) + ldsw + _i * 8192), 16, 0, 0); } while (0)
; #define PG8_LDA(dst, b, h) do { _Pragma("unroll") for (int m = 0; m < 4; ++m) _Pragma("unroll") for (int k = 0; k < 2; ++k) dst[m][k] = *(const PG8_LAS bf16x8*)(lds + PG8_SA(b, h) + aoff + m * 2048 + k * 1024); } while (0)
; #define PG8_MMA(ai, bj, At, Bt) do { __builtin_amdgcn_s_setprio(1); _Pragma("unroll") for (int m = 0; m < 4; ++m) _Pragma("unroll") for (int n = 0; n < 2; ++n) _Pragma("unroll") for (int k = 0; k < 2; ++k) \
;         acc[ai][bj][m][n] = __builtin_amdgcn_mfma_f32_16x16x32_bf16(Bt[n][k], At[m][k], acc[ai][bj][m][n], 0, 0, 0); __builtin_amdgcn_s_setprio(0); } while (0)
; #define PG8_WAIT_V(n) asm volatile("s_waitcnt vmcnt(" #n ")" ::: "memory")
; #define PG8_WAIT_L(n) asm volatile("s_waitcnt lgkmcnt(" #n ")" ::: "memory")
; #define PG8_BAR __builtin_amdgcn_s_barrier()
; #define PG8_SCHED __builtin_amdgcn_sched_barrier(0)
; template <class Epi, class Sched, bool ALIGN_EPI = false, bool SP2 = false>
; __device__ __forceinline__ void gemm_phase(PG8_LAS unsigned char* lds, const Gemm g, const Sched& S, const Epi& E) {
;     ...
;         for (int t = 0; t < nt; t += 2) {
;     ...
;             PG8_LDA(At, 1, 1); PG8_STAGE(PG8_SB(1, 0), b3, voffB); PG8_STAGE(PG8_SB(1, 1), b3 + hstepB, voffB); PG8_STAGE(PG8_SA(1, 0), a3, voffA);
;             PG8_WAIT_V(8); PG8_WAIT_L(0); PG8_BAR; PG8_MMA(1, 0, At, B0); PG8_MMA(1, 1, At, B1); PG8_BAR; PG8_SCHED;
	s_setprio 0
	s_add_i32 s13, s13, s6
	v_lshl_add_u64 v[226:227], v[226:227], 0, s[54:55]
	s_mov_b32 m0, s13
	ds_read_b128 v[194:197], v161 offset:49152
	ds_read_b128 v[198:201], v161 offset:50176
	ds_read_b128 v[202:205], v161 offset:51200
	ds_read_b128 v[206:209], v161 offset:52224
	ds_read_b128 v[210:213], v161 offset:53248
	ds_read_b128 v[214:217], v161 offset:54272
	ds_read_b128 v[218:221], v161 offset:55296
	ds_read_b128 v[222:225], v161 offset:56320
	global_load_lds_dwordx4 v[226:227], off
	s_add_i32 m0, s13, 0x2000
	s_add_u32 s38, s38, 0x80080
	v_lshl_add_u64 v[226:227], v[228:229], 0, s[54:55]
	s_addc_u32 s39, s39, 0
	s_add_i32 s13, s33, s6
	global_load_lds_dwordx4 v[226:227], off
	v_lshl_add_u64 v[226:227], s[38:39], 0, v[138:139]
	s_mov_b32 m0, s13
	s_nop 0
	global_load_lds_dwordx4 v[226:227], off
	v_lshl_add_u64 v[226:227], s[38:39], 0, v[142:143]
	s_add_i32 m0, s13, 0x2000
	s_nop 0
	global_load_lds_dwordx4 v[226:227], off
	v_lshl_add_u64 v[226:227], v[230:231], 0, s[54:55]
	s_mov_b32 m0, s51
	s_nop 0
	global_load_lds_dwordx4 v[226:227], off
	v_lshl_add_u64 v[226:227], v[232:233], 0, s[54:55]
	s_mov_b32 m0, s68
	s_nop 0
	global_load_lds_dwordx4 v[226:227], off
	s_waitcnt vmcnt(8)
	s_waitcnt lgkmcnt(0)
	s_setprio 1
	s_barrier
	v_mfma_f32_16x16x32_bf16 v[60:63], v[128:131], v[194:197], v[60:63]
	v_mfma_f32_16x16x32_bf16 v[56:59], v[164:167], v[194:197], v[56:59]
	v_mfma_f32_16x16x32_bf16 v[44:47], v[128:131], v[202:205], v[44:47]
	v_mfma_f32_16x16x32_bf16 v[40:43], v[164:167], v[202:205], v[40:43]
	v_mfma_f32_16x16x32_bf16 v[28:31], v[128:131], v[210:213], v[28:31]
	v_mfma_f32_16x16x32_bf16 v[24:27], v[164:167], v[210:213], v[24:27]
	v_mfma_f32_16x16x32_bf16 v[12:15], v[128:131], v[218:221], v[12:15]
	v_mfma_f32_16x16x32_bf16 v[8:11], v[164:167], v[218:221], v[8:11]
	v_mfma_f32_16x16x32_bf16 v[60:63], v[132:135], v[198:201], v[60:63]
	v_mfma_f32_16x16x32_bf16 v[56:59], v[168:171], v[198:201], v[56:59]
	v_mfma_f32_16x16x32_bf16 v[44:47], v[132:135], v[206:209], v[44:47]
	v_mfma_f32_16x16x32_bf16 v[40:43], v[168:171], v[206:209], v[40:43]
	v_mfma_f32_16x16x32_bf16 v[28:31], v[132:135], v[214:217], v[28:31]
	v_mfma_f32_16x16x32_bf16 v[24:27], v[168:171], v[214:217], v[24:27]
	v_mfma_f32_16x16x32_bf16 v[12:15], v[132:135], v[222:225], v[12:15]
	v_mfma_f32_16x16x32_bf16 v[8:11], v[168:171], v[222:225], v[8:11]
	v_mfma_f32_16x16x32_bf16 v[52:55], v[172:175], v[194:197], v[52:55]
	v_mfma_f32_16x16x32_bf16 v[48:51], v[180:183], v[194:197], v[48:51]
	v_mfma_f32_16x16x32_bf16 v[36:39], v[172:175], v[202:205], v[36:39]
	v_mfma_f32_16x16x32_bf16 v[32:35], v[180:183], v[202:205], v[32:35]
	v_mfma_f32_16x16x32_bf16 v[20:23], v[172:175], v[210:213], v[20:23]
	v_mfma_f32_16x16x32_bf16 v[16:19], v[180:183], v[210:213], v[16:19]
	v_mfma_f32_16x16x32_bf16 v[4:7], v[172:175], v[218:221], v[4:7]
	v_mfma_f32_16x16x32_bf16 v[0:3], v[180:183], v[218:221], v[0:3]
	v_mfma_f32_16x16x32_bf16 v[52:55], v[176:179], v[198:201], v[52:55]
	v_mfma_f32_16x16x32_bf16 v[48:51], v[190:193], v[198:201], v[48:51]
	v_mfma_f32_16x16x32_bf16 v[36:39], v[176:179], v[206:209], v[36:39]
	v_mfma_f32_16x16x32_bf16 v[32:35], v[190:193], v[206:209], v[32:35]
	v_mfma_f32_16x16x32_bf16 v[20:23], v[176:179], v[214:217], v[20:23]
	v_mfma_f32_16x16x32_bf16 v[16:19], v[190:193], v[214:217], v[16:19]
	v_mfma_f32_16x16x32_bf16 v[4:7], v[176:179], v[222:225], v[4:7]
	v_mfma_f32_16x16x32_bf16 v[0:3], v[190:193], v[222:225], v[0:3]
	s_barrier
	s_setprio 0
	s_add_i32 s12, s12, 2
	s_add_u32 s20, s20, 0x100
	s_addc_u32 s21, s21, 0
	s_add_u32 s10, s10, 0x100
	s_addc_u32 s11, s11, 0
	s_cmp_gt_u32 s12, 29
	s_cbranch_scc0 .LBB0_2050
	s_and_b64 vcc, exec, s[56:57]
	s_cbranch_vccz .LBB0_2053
	s_barrier

; #define PG8_STAGE(bufoff, gbase, voff) do { _Pragma("unroll") for (int _i = 0; _i < 2; ++_i) \
;         __builtin_amdgcn_global_load_lds((const unsigned*)((const char*)(gbase) + (voff)[_i]), (PG8_LAS unsigned*)(lds + (bufoff) + ldsw + _i * 8192), 16, 0, 0); } while (0)
; #define PG8_LDA(dst, b, h) do { _Pragma("unroll") for (int m = 0; m < 4; ++m) _Pragma("unroll") for (int k = 0; k < 2; ++k) dst[m][k] = *(const PG8_LAS bf16x8*)(lds + PG8_SA(b, h) + aoff + m * 2048 + k * 1024); } while (0)
; #define PG8_LDB(dst, b, h) do { _Pragma("unroll") for (int n = 0; n < 2; ++n) _Pragma("unroll") for (int k = 0; k < 2; ++k) dst[n][k] = *(const PG8_LAS bf16x8*)(lds + PG8_SB(b, h) + boff + n * 2048 + k * 1024); } while (0)
; #define PG8_MMA(ai, bj, At, Bt) do { __builtin_amdgcn_s_setprio(1); _Pragma("unroll") for (int m = 0; m < 4; ++m) _Pragma("unroll") for (int n = 0; n < 2; ++n) _Pragma("unroll") for (int k = 0; k < 2; ++k) \
;         acc[ai][bj][m][n] = __builtin_amdgcn_mfma_f32_16x16x32_bf16(Bt[n][k], At[m][k], acc[ai][bj][m][n], 0, 0, 0); __builtin_amdgcn_s_setprio(0); } while (0)
; #define PG8_WAIT_V(n) asm volatile("s_waitcnt vmcnt(" #n ")" ::: "memory")
; #define PG8_WAIT_L(n) asm volatile("s_waitcnt lgkmcnt(" #n ")" ::: "memory")
; #define PG8_BAR __builtin_amdgcn_s_barrier()
; #define PG8_SCHED __builtin_amdgcn_sched_barrier(0)
; template <class Epi, class Sched, bool ALIGN_EPI = false, bool SP2 = false>
; __device__ __forceinline__ void gemm_phase(PG8_LAS unsigned char* lds, const Gemm g, const Sched& S, const Epi& E) {
;     ...
;             const char* a1 = cA + (size_t)(t + 1) * kstA;
;             const char* a2 = last ? nA : cA + (size_t)(t + 2) * kstA; const char* b2 = last ? nB : cB + (size_t)(t + 2) * kstep;
;             const char* a3 = a2 + kstA; const char* b3 = b2 + kstep;
;             if (last && has_next) S.a_ready(nxt);
;             if constexpr (SP2) {
;             PG8_LDB(B0, 0, 0); PG8_LDB(B1, 0, 1); PG8_SCHED; PG8_LDA(At, 0, 0); PG8_STAGE(PG8_SA(1, 1), a1 + hstepA, voffA);
;             PG8_WAIT_V(8); PG8_WAIT_L(0); PG8_BAR; PG8_MMA(0, 0, At, B0); PG8_MMA(0, 1, At, B1); PG8_BAR; PG8_SCHED;
;             PG8_LDA(At, 0, 1); PG8_STAGE(PG8_SB(0, 0), b2, voffB); PG8_STAGE(PG8_SB(0, 1), b2 + hstepB, voffB); PG8_STAGE(PG8_SA(0, 0), a2, voffA);
.LBB0_2749:
	v_add_u32_e32 v176, s77, v180
	v_add_u32_e32 v183, s84, v180
	ds_read_b128 v[132:135], v176
	ds_read_b128 v[136:139], v176 offset:1024
	ds_read_b128 v[140:143], v176 offset:2048
	ds_read_b128 v[176:179], v176 offset:3072
	ds_read_b128 v[190:193], v183
	ds_read_b128 v[194:197], v183 offset:1024
	ds_read_b128 v[198:201], v183 offset:2048
	ds_read_b128 v[202:205], v183 offset:3072
	s_add_u32 s4, s46, s62
	s_addc_u32 s5, s47, s63
	s_add_u32 s12, s48, s62
	s_addc_u32 s13, s49, s63
	s_cmp_eq_u32 s7, s1
	s_cselect_b32 s67, s59, s5
	s_cselect_b32 s66, s58, s4
	s_cselect_b32 s65, s61, s13
	s_cselect_b32 s64, s60, s12
	v_lshl_add_u64 v[238:239], s[46:47], 0, v[130:131]
	s_add_i32 m0, s9, 0xc000
	ds_read_b128 v[206:209], v182
	ds_read_b128 v[210:213], v182 offset:1024
	ds_read_b128 v[214:217], v182 offset:2048
	ds_read_b128 v[218:221], v182 offset:3072
	ds_read_b128 v[222:225], v182 offset:4096
	ds_read_b128 v[226:229], v182 offset:5120
	ds_read_b128 v[230:233], v182 offset:6144
	ds_read_b128 v[234:237], v182 offset:7168
	global_load_lds_dwordx4 v[238:239], off
	v_lshl_add_u64 v[238:239], s[46:47], 0, v[128:129]
	s_add_i32 m0, s9, 0xe000
	s_nop 0
	global_load_lds_dwordx4 v[238:239], off
	s_waitcnt vmcnt(8)
	s_waitcnt lgkmcnt(0)
	s_setprio 1
	s_barrier
	v_mfma_f32_16x16x32_bf16 v[124:127], v[132:135], v[206:209], v[124:127]
	v_mfma_f32_16x16x32_bf16 v[120:123], v[140:143], v[206:209], v[120:123]
	v_mfma_f32_16x16x32_bf16 v[116:119], v[132:135], v[214:217], v[116:119]
	v_mfma_f32_16x16x32_bf16 v[112:115], v[140:143], v[214:217], v[112:115]
	v_mfma_f32_16x16x32_bf16 v[108:111], v[132:135], v[222:225], v[108:111]
	v_mfma_f32_16x16x32_bf16 v[104:107], v[140:143], v[222:225], v[104:107]
	v_mfma_f32_16x16x32_bf16 v[100:103], v[132:135], v[230:233], v[100:103]
	v_mfma_f32_16x16x32_bf16 v[96:99], v[140:143], v[230:233], v[96:99]
	v_mfma_f32_16x16x32_bf16 v[124:127], v[136:139], v[210:213], v[124:127]
	v_mfma_f32_16x16x32_bf16 v[120:123], v[176:179], v[210:213], v[120:123]
	v_mfma_f32_16x16x32_bf16 v[116:119], v[136:139], v[218:221], v[116:119]
	v_mfma_f32_16x16x32_bf16 v[112:115], v[176:179], v[218:221], v[112:115]
	v_mfma_f32_16x16x32_bf16 v[108:111], v[136:139], v[226:229], v[108:111]
	v_mfma_f32_16x16x32_bf16 v[104:107], v[176:179], v[226:229], v[104:107]
	v_mfma_f32_16x16x32_bf16 v[100:103], v[136:139], v[234:237], v[100:103]
	v_mfma_f32_16x16x32_bf16 v[96:99], v[176:179], v[234:237], v[96:99]
	v_mfma_f32_16x16x32_bf16 v[92:95], v[190:193], v[206:209], v[92:95]
	v_mfma_f32_16x16x32_bf16 v[88:91], v[198:201], v[206:209], v[88:91]
	v_mfma_f32_16x16x32_bf16 v[84:87], v[190:193], v[214:217], v[84:87]
	v_mfma_f32_16x16x32_bf16 v[80:83], v[198:201], v[214:217], v[80:83]
	v_mfma_f32_16x16x32_bf16 v[76:79], v[190:193], v[222:225], v[76:79]
	v_mfma_f32_16x16x32_bf16 v[72:75], v[198:201], v[222:225], v[72:75]
	v_mfma_f32_16x16x32_bf16 v[68:71], v[190:193], v[230:233], v[68:71]
	v_mfma_f32_16x16x32_bf16 v[64:67], v[198:201], v[230:233], v[64:67]
	v_mfma_f32_16x16x32_bf16 v[92:95], v[194:197], v[210:213], v[92:95]
	v_mfma_f32_16x16x32_bf16 v[88:91], v[202:205], v[210:213], v[88:91]
	v_mfma_f32_16x16x32_bf16 v[84:87], v[194:197], v[218:221], v[84:87]
	v_mfma_f32_16x16x32_bf16 v[80:83], v[202:205], v[218:221], v[80:83]
	v_mfma_f32_16x16x32_bf16 v[76:79], v[194:197], v[226:229], v[76:79]
	v_mfma_f32_16x16x32_bf16 v[72:75], v[202:205], v[226:229], v[72:75]
	v_mfma_f32_16x16x32_bf16 v[68:71], v[194:197], v[234:237], v[68:71]
	v_mfma_f32_16x16x32_bf16 v[64:67], v[202:205], v[234:237], v[64:67]
	s_barrier
	s_setprio 0
	s_add_i32 s4, s77, s8
	v_lshl_add_u64 v[238:239], s[64:65], 0, v[146:147]
	s_mov_b32 m0, s4
	ds_read_b128 v[206:209], v182 offset:16384
	ds_read_b128 v[210:213], v182 offset:17408
	ds_read_b128 v[214:217], v182 offset:18432
	ds_read_b128 v[218:221], v182 offset:19456
	ds_read_b128 v[222:225], v182 offset:20480
	ds_read_b128 v[226:229], v182 offset:21504
	ds_read_b128 v[230:233], v182 offset:22528
	ds_read_b128 v[234:237], v182 offset:23552
	global_load_lds_dwordx4 v[238:239], off
	s_add_i32 m0, s4, 0x2000
	s_add_u32 s4, s64, 0x80000
	v_lshl_add_u64 v[240:241], s[64:65], 0, v[150:151]
	s_addc_u32 s5, s65, 0
	s_add_i32 s12, s84, s8
	global_load_lds_dwordx4 v[240:241], off
	v_lshl_add_u64 v[242:243], s[4:5], 0, v[146:147]
	s_mov_b32 m0, s12
	v_lshl_add_u64 v[244:245], s[66:67], 0, v[148:149]
	global_load_lds_dwordx4 v[242:243], off
	v_lshl_add_u64 v[242:243], s[4:5], 0, v[150:151]
	s_add_i32 m0, s12, 0x2000
	s_nop 0
	global_load_lds_dwordx4 v[242:243], off
	v_lshl_add_u64 v[242:243], s[66:67], 0, v[144:145]
	s_mov_b32 m0, s9
	s_nop 0
	global_load_lds_dwordx4 v[242:243], off
	s_mov_b32 m0, s37
	s_nop 0
	global_load_lds_dwordx4 v[244:245], off
	s_waitcnt vmcnt(8)
	s_waitcnt lgkmcnt(0)
	s_setprio 1
	s_barrier
; #define PG8_STAGE(bufoff, gbase, voff) do { _Pragma("unroll") for (int _i = 0; _i < 2; ++_i) \
;         __builtin_amdgcn_global_load_lds((const unsigned*)((const char*)(gbase) + (voff)[_i]), (PG8_LAS unsigned*)(lds + (bufoff) + ldsw + _i * 8192), 16, 0, 0); } while (0)
; #define PG8_LDA(dst, b, h) do { _Pragma("unroll") for (int m = 0; m < 4; ++m) _Pragma("unroll") for (int k = 0; k < 2; ++k) dst[m][k] = *(const PG8_LAS bf16x8*)(lds + PG8_SA(b, h) + aoff + m * 2048 + k * 1024); } while (0)
; #define PG8_LDB(dst, b, h) do { _Pragma("unroll") for (int n = 0; n < 2; ++n) _Pragma("unroll") for (int k = 0; k < 2; ++k) dst[n][k] = *(const PG8_LAS bf16x8*)(lds + PG8_SB(b, h) + boff + n * 2048 + k * 1024); } while (0)
; #define PG8_MMA(ai, bj, At, Bt) do { __builtin_amdgcn_s_setprio(1); _Pragma("unroll") for (int m = 0; m < 4; ++m) _Pragma("unroll") for (int n = 0; n < 2; ++n) _Pragma("unroll") for (int k = 0; k < 2; ++k) \
;         acc[ai][bj][m][n] = __builtin_amdgcn_mfma_f32_16x16x32_bf16(Bt[n][k], At[m][k], acc[ai][bj][m][n], 0, 0, 0); __builtin_amdgcn_s_setprio(0); } while (0)
; #define PG8_WAIT_V(n) asm volatile("s_waitcnt vmcnt(" #n ")" ::: "memory")
; #define PG8_WAIT_L(n) asm volatile("s_waitcnt lgkmcnt(" #n ")" ::: "memory")
; #define PG8_BAR __builtin_amdgcn_s_barrier()
; #define PG8_SCHED __builtin_amdgcn_sched_barrier(0)
; template <class Epi, class Sched, bool ALIGN_EPI = false, bool SP2 = false>
; __device__ __forceinline__ void gemm_phase(PG8_LAS unsigned char* lds, const Gemm g, const Sched& S, const Epi& E) {
;     ...
;             PG8_WAIT_V(8); PG8_WAIT_L(0); PG8_BAR; PG8_MMA(1, 0, At, B0); PG8_MMA(1, 1, At, B1); PG8_BAR; PG8_SCHED;
;             PG8_LDB(B0, 1, 0); PG8_LDB(B1, 1, 1); PG8_SCHED; PG8_LDA(At, 1, 0); PG8_STAGE(PG8_SA(0, 1), a2 + hstepA, voffA);
;             PG8_WAIT_V(8); PG8_WAIT_L(0); PG8_BAR; PG8_MMA(0, 0, At, B0); PG8_MMA(0, 1, At, B1); PG8_BAR; PG8_SCHED;
	v_mfma_f32_16x16x32_bf16 v[60:63], v[132:135], v[206:209], v[60:63]
	v_mfma_f32_16x16x32_bf16 v[56:59], v[140:143], v[206:209], v[56:59]
	v_mfma_f32_16x16x32_bf16 v[52:55], v[132:135], v[214:217], v[52:55]
	v_mfma_f32_16x16x32_bf16 v[48:51], v[140:143], v[214:217], v[48:51]
	v_mfma_f32_16x16x32_bf16 v[44:47], v[132:135], v[222:225], v[44:47]
	v_mfma_f32_16x16x32_bf16 v[40:43], v[140:143], v[222:225], v[40:43]
	v_mfma_f32_16x16x32_bf16 v[36:39], v[132:135], v[230:233], v[36:39]
	v_mfma_f32_16x16x32_bf16 v[32:35], v[140:143], v[230:233], v[32:35]
	v_mfma_f32_16x16x32_bf16 v[60:63], v[136:139], v[210:213], v[60:63]
	v_mfma_f32_16x16x32_bf16 v[56:59], v[176:179], v[210:213], v[56:59]
	v_mfma_f32_16x16x32_bf16 v[52:55], v[136:139], v[218:221], v[52:55]
	v_mfma_f32_16x16x32_bf16 v[48:51], v[176:179], v[218:221], v[48:51]
	v_mfma_f32_16x16x32_bf16 v[44:47], v[136:139], v[226:229], v[44:47]
	v_mfma_f32_16x16x32_bf16 v[40:43], v[176:179], v[226:229], v[40:43]
	v_mfma_f32_16x16x32_bf16 v[36:39], v[136:139], v[234:237], v[36:39]
	v_mfma_f32_16x16x32_bf16 v[32:35], v[176:179], v[234:237], v[32:35]
	v_mfma_f32_16x16x32_bf16 v[28:31], v[190:193], v[206:209], v[28:31]
	v_mfma_f32_16x16x32_bf16 v[24:27], v[198:201], v[206:209], v[24:27]
	v_mfma_f32_16x16x32_bf16 v[20:23], v[190:193], v[214:217], v[20:23]
	v_mfma_f32_16x16x32_bf16 v[16:19], v[198:201], v[214:217], v[16:19]
	v_mfma_f32_16x16x32_bf16 v[12:15], v[190:193], v[222:225], v[12:15]
	v_mfma_f32_16x16x32_bf16 v[8:11], v[198:201], v[222:225], v[8:11]
	v_mfma_f32_16x16x32_bf16 v[4:7], v[190:193], v[230:233], v[4:7]
	v_mfma_f32_16x16x32_bf16 v[0:3], v[198:201], v[230:233], v[0:3]
	v_mfma_f32_16x16x32_bf16 v[28:31], v[194:197], v[210:213], v[28:31]
	v_mfma_f32_16x16x32_bf16 v[24:27], v[202:205], v[210:213], v[24:27]
	v_mfma_f32_16x16x32_bf16 v[20:23], v[194:197], v[218:221], v[20:23]
	v_mfma_f32_16x16x32_bf16 v[16:19], v[202:205], v[218:221], v[16:19]
	v_mfma_f32_16x16x32_bf16 v[12:15], v[194:197], v[226:229], v[12:15]
	v_mfma_f32_16x16x32_bf16 v[8:11], v[202:205], v[226:229], v[8:11]
	v_mfma_f32_16x16x32_bf16 v[4:7], v[194:197], v[234:237], v[4:7]
	v_mfma_f32_16x16x32_bf16 v[0:3], v[202:205], v[234:237], v[0:3]
	s_barrier
	s_setprio 0
	s_add_i32 s12, 0, 0x18000
	s_add_i32 s13, 0, 0x1c000
	v_add_u32_e32 v176, s12, v180
	v_add_u32_e32 v183, s13, v180
	ds_read_b128 v[132:135], v176
	ds_read_b128 v[136:139], v176 offset:1024
	ds_read_b128 v[140:143], v176 offset:2048
	ds_read_b128 v[176:179], v176 offset:3072
	ds_read_b128 v[190:193], v183
	ds_read_b128 v[194:197], v183 offset:1024
	ds_read_b128 v[198:201], v183 offset:2048
	ds_read_b128 v[202:205], v183 offset:3072
	s_add_u32 s4, s66, 0x80000
	s_addc_u32 s5, s67, 0
	s_mov_b32 m0, s70
	v_lshl_add_u64 v[246:247], s[4:5], 0, v[144:145]
	ds_read_b128 v[206:209], v182 offset:32768
	ds_read_b128 v[210:213], v182 offset:33792
	ds_read_b128 v[214:217], v182 offset:34816
	ds_read_b128 v[218:221], v182 offset:35840
	ds_read_b128 v[222:225], v182 offset:36864
	ds_read_b128 v[226:229], v182 offset:37888
	ds_read_b128 v[230:233], v182 offset:38912
	ds_read_b128 v[234:237], v182 offset:39936
	global_load_lds_dwordx4 v[246:247], off
	v_lshl_add_u64 v[246:247], s[4:5], 0, v[148:149]
	s_mov_b32 m0, s71
	s_nop 0
	global_load_lds_dwordx4 v[246:247], off
	s_waitcnt vmcnt(8)
	s_waitcnt lgkmcnt(0)
	s_setprio 1
	s_barrier
	v_mfma_f32_16x16x32_bf16 v[124:127], v[132:135], v[206:209], v[124:127]
	v_mfma_f32_16x16x32_bf16 v[120:123], v[140:143], v[206:209], v[120:123]
	v_mfma_f32_16x16x32_bf16 v[116:119], v[132:135], v[214:217], v[116:119]
	v_mfma_f32_16x16x32_bf16 v[112:115], v[140:143], v[214:217], v[112:115]
	v_mfma_f32_16x16x32_bf16 v[108:111], v[132:135], v[222:225], v[108:111]
	v_mfma_f32_16x16x32_bf16 v[104:107], v[140:143], v[222:225], v[104:107]
	v_mfma_f32_16x16x32_bf16 v[100:103], v[132:135], v[230:233], v[100:103]
	v_mfma_f32_16x16x32_bf16 v[96:99], v[140:143], v[230:233], v[96:99]
	v_mfma_f32_16x16x32_bf16 v[124:127], v[136:139], v[210:213], v[124:127]
	v_mfma_f32_16x16x32_bf16 v[120:123], v[176:179], v[210:213], v[120:123]
	v_mfma_f32_16x16x32_bf16 v[116:119], v[136:139], v[218:221], v[116:119]
	v_mfma_f32_16x16x32_bf16 v[112:115], v[176:179], v[218:221], v[112:115]
	v_mfma_f32_16x16x32_bf16 v[108:111], v[136:139], v[226:229], v[108:111]
	v_mfma_f32_16x16x32_bf16 v[104:107], v[176:179], v[226:229], v[104:107]
	v_mfma_f32_16x16x32_bf16 v[100:103], v[136:139], v[234:237], v[100:103]
	v_mfma_f32_16x16x32_bf16 v[96:99], v[176:179], v[234:237], v[96:99]
	v_mfma_f32_16x16x32_bf16 v[92:95], v[190:193], v[206:209], v[92:95]
	v_mfma_f32_16x16x32_bf16 v[88:91], v[198:201], v[206:209], v[88:91]
	v_mfma_f32_16x16x32_bf16 v[84:87], v[190:193], v[214:217], v[84:87]
	v_mfma_f32_16x16x32_bf16 v[80:83], v[198:201], v[214:217], v[80:83]
	v_mfma_f32_16x16x32_bf16 v[76:79], v[190:193], v[222:225], v[76:79]
	v_mfma_f32_16x16x32_bf16 v[72:75], v[198:201], v[222:225], v[72:75]
	v_mfma_f32_16x16x32_bf16 v[68:71], v[190:193], v[230:233], v[68:71]
	v_mfma_f32_16x16x32_bf16 v[64:67], v[198:201], v[230:233], v[64:67]
	v_mfma_f32_16x16x32_bf16 v[92:95], v[194:197], v[210:213], v[92:95]
	v_mfma_f32_16x16x32_bf16 v[88:91], v[202:205], v[210:213], v[88:91]
	v_mfma_f32_16x16x32_bf16 v[84:87], v[194:197], v[218:221], v[84:87]
	v_mfma_f32_16x16x32_bf16 v[80:83], v[202:205], v[218:221], v[80:83]
	v_mfma_f32_16x16x32_bf16 v[76:79], v[194:197], v[226:229], v[76:79]
	v_mfma_f32_16x16x32_bf16 v[72:75], v[202:205], v[226:229], v[72:75]
	v_mfma_f32_16x16x32_bf16 v[68:71], v[194:197], v[234:237], v[68:71]
	v_mfma_f32_16x16x32_bf16 v[64:67], v[202:205], v[234:237], v[64:67]
	s_barrier
; #define PG8_STAGE(bufoff, gbase, voff) do { _Pragma("unroll") for (int _i = 0; _i < 2; ++_i) \
;         __builtin_amdgcn_global_load_lds((const unsigned*)((const char*)(gbase) + (voff)[_i]), (PG8_LAS unsigned*)(lds + (bufoff) + ldsw + _i * 8192), 16, 0, 0); } while (0)
; #define PG8_LDA(dst, b, h) do { _Pragma("unroll") for (int m = 0; m < 4; ++m) _Pragma("unroll") for (int k = 0; k < 2; ++k) dst[m][k] = *(const PG8_LAS bf16x8*)(lds + PG8_SA(b, h) + aoff + m * 2048 + k * 1024); } while (0)
; #define PG8_MMA(ai, bj, At, Bt) do { __builtin_amdgcn_s_setprio(1); _Pragma("unroll") for (int m = 0; m < 4; ++m) _Pragma("unroll") for (int n = 0; n < 2; ++n) _Pragma("unroll") for (int k = 0; k < 2; ++k) \
;         acc[ai][bj][m][n] = __builtin_amdgcn_mfma_f32_16x16x32_bf16(Bt[n][k], At[m][k], acc[ai][bj][m][n], 0, 0, 0); __builtin_amdgcn_s_setprio(0); } while (0)
; #define PG8_WAIT_V(n) asm volatile("s_waitcnt vmcnt(" #n ")" ::: "memory")
; #define PG8_WAIT_L(n) asm volatile("s_waitcnt lgkmcnt(" #n ")" ::: "memory")
; #define PG8_BAR __builtin_amdgcn_s_barrier()
; #define PG8_SCHED __builtin_amdgcn_sched_barrier(0)
; template <class Epi, class Sched, bool ALIGN_EPI = false, bool SP2 = false>
; __device__ __forceinline__ void gemm_phase(PG8_LAS unsigned char* lds, const Gemm g, const Sched& S, const Epi& E) {
;     ...
;         for (int t = 0; t < nt; t += 2) {
;     ...
;             PG8_LDA(At, 1, 1); PG8_STAGE(PG8_SB(1, 0), b3, voffB); PG8_STAGE(PG8_SB(1, 1), b3 + hstepB, voffB); PG8_STAGE(PG8_SA(1, 0), a3, voffA);
;             PG8_WAIT_V(8); PG8_WAIT_L(0); PG8_BAR; PG8_MMA(1, 0, At, B0); PG8_MMA(1, 1, At, B1); PG8_BAR; PG8_SCHED;
	s_setprio 0
	s_add_i32 s4, s12, s8
	v_lshl_add_u64 v[238:239], v[238:239], 0, s[52:53]
	s_mov_b32 m0, s4
	ds_read_b128 v[206:209], v182 offset:49152
	ds_read_b128 v[210:213], v182 offset:50176
	ds_read_b128 v[214:217], v182 offset:51200
	ds_read_b128 v[218:221], v182 offset:52224
	ds_read_b128 v[222:225], v182 offset:53248
	ds_read_b128 v[226:229], v182 offset:54272
	ds_read_b128 v[230:233], v182 offset:55296
	ds_read_b128 v[234:237], v182 offset:56320
	global_load_lds_dwordx4 v[238:239], off
	s_add_i32 m0, s4, 0x2000
	s_add_u32 s4, s64, 0x80080
	v_lshl_add_u64 v[238:239], v[240:241], 0, s[52:53]
	s_addc_u32 s5, s65, 0
	s_add_i32 s12, s13, s8
	global_load_lds_dwordx4 v[238:239], off
	v_lshl_add_u64 v[238:239], s[4:5], 0, v[146:147]
	s_mov_b32 m0, s12
	s_nop 0
	global_load_lds_dwordx4 v[238:239], off
	v_lshl_add_u64 v[238:239], s[4:5], 0, v[150:151]
	s_add_i32 m0, s12, 0x2000
	s_nop 0
	global_load_lds_dwordx4 v[238:239], off
	v_lshl_add_u64 v[238:239], v[242:243], 0, s[52:53]
	s_mov_b32 m0, s74
	s_nop 0
	global_load_lds_dwordx4 v[238:239], off
	v_lshl_add_u64 v[238:239], v[244:245], 0, s[52:53]
	s_mov_b32 m0, s75
	s_nop 0
	global_load_lds_dwordx4 v[238:239], off
	s_waitcnt vmcnt(8)
	s_waitcnt lgkmcnt(0)
	s_setprio 1
	s_barrier
	v_mfma_f32_16x16x32_bf16 v[60:63], v[132:135], v[206:209], v[60:63]
	v_mfma_f32_16x16x32_bf16 v[56:59], v[140:143], v[206:209], v[56:59]
	v_mfma_f32_16x16x32_bf16 v[52:55], v[132:135], v[214:217], v[52:55]
	v_mfma_f32_16x16x32_bf16 v[48:51], v[140:143], v[214:217], v[48:51]
	v_mfma_f32_16x16x32_bf16 v[44:47], v[132:135], v[222:225], v[44:47]
	v_mfma_f32_16x16x32_bf16 v[40:43], v[140:143], v[222:225], v[40:43]
	v_mfma_f32_16x16x32_bf16 v[36:39], v[132:135], v[230:233], v[36:39]
	v_mfma_f32_16x16x32_bf16 v[32:35], v[140:143], v[230:233], v[32:35]
	v_mfma_f32_16x16x32_bf16 v[60:63], v[136:139], v[210:213], v[60:63]
	v_mfma_f32_16x16x32_bf16 v[56:59], v[176:179], v[210:213], v[56:59]
	v_mfma_f32_16x16x32_bf16 v[52:55], v[136:139], v[218:221], v[52:55]
	v_mfma_f32_16x16x32_bf16 v[48:51], v[176:179], v[218:221], v[48:51]
	v_mfma_f32_16x16x32_bf16 v[44:47], v[136:139], v[226:229], v[44:47]
	v_mfma_f32_16x16x32_bf16 v[40:43], v[176:179], v[226:229], v[40:43]
	v_mfma_f32_16x16x32_bf16 v[36:39], v[136:139], v[234:237], v[36:39]
	v_mfma_f32_16x16x32_bf16 v[32:35], v[176:179], v[234:237], v[32:35]
	v_mfma_f32_16x16x32_bf16 v[28:31], v[190:193], v[206:209], v[28:31]
	v_mfma_f32_16x16x32_bf16 v[24:27], v[198:201], v[206:209], v[24:27]
	v_mfma_f32_16x16x32_bf16 v[20:23], v[190:193], v[214:217], v[20:23]
	v_mfma_f32_16x16x32_bf16 v[16:19], v[198:201], v[214:217], v[16:19]
	v_mfma_f32_16x16x32_bf16 v[12:15], v[190:193], v[222:225], v[12:15]
	v_mfma_f32_16x16x32_bf16 v[8:11], v[198:201], v[222:225], v[8:11]
	v_mfma_f32_16x16x32_bf16 v[4:7], v[190:193], v[230:233], v[4:7]
	v_mfma_f32_16x16x32_bf16 v[0:3], v[198:201], v[230:233], v[0:3]
	v_mfma_f32_16x16x32_bf16 v[28:31], v[194:197], v[210:213], v[28:31]
	v_mfma_f32_16x16x32_bf16 v[24:27], v[202:205], v[210:213], v[24:27]
	v_mfma_f32_16x16x32_bf16 v[20:23], v[194:197], v[218:221], v[20:23]
	v_mfma_f32_16x16x32_bf16 v[16:19], v[202:205], v[218:221], v[16:19]
	v_mfma_f32_16x16x32_bf16 v[12:15], v[194:197], v[226:229], v[12:15]
	v_mfma_f32_16x16x32_bf16 v[8:11], v[202:205], v[226:229], v[8:11]
	v_mfma_f32_16x16x32_bf16 v[4:7], v[194:197], v[234:237], v[4:7]
	v_mfma_f32_16x16x32_bf16 v[0:3], v[202:205], v[234:237], v[0:3]
	s_barrier
	s_setprio 0
	s_add_i32 s4, s1, 2
	s_add_u32 s62, s62, 0x100
	s_addc_u32 s63, s63, 0
	v_lshl_add_u64 v[130:131], v[130:131], 0, s[34:35]
	v_lshl_add_u64 v[128:129], v[128:129], 0, s[34:35]
	s_cmp_ge_i32 s1, s7
	s_mov_b32 s1, s4
	s_cbranch_scc0 .LBB0_2749
	s_and_b64 vcc, exec, s[54:55]
	s_cbranch_vccz .LBB0_2752
	s_barrier

; #define PG8_STAGE(bufoff, gbase, voff) do { _Pragma("unroll") for (int _i = 0; _i < 2; ++_i) \
;         __builtin_amdgcn_global_load_lds((const unsigned*)((const char*)(gbase) + (voff)[_i]), (PG8_LAS unsigned*)(lds + (bufoff) + ldsw + _i * 8192), 16, 0, 0); } while (0)
; #define PG8_LDA(dst, b, h) do { _Pragma("unroll") for (int m = 0; m < 4; ++m) _Pragma("unroll") for (int k = 0; k < 2; ++k) dst[m][k] = *(const PG8_LAS bf16x8*)(lds + PG8_SA(b, h) + aoff + m * 2048 + k * 1024); } while (0)
; #define PG8_LDB(dst, b, h) do { _Pragma("unroll") for (int n = 0; n < 2; ++n) _Pragma("unroll") for (int k = 0; k < 2; ++k) dst[n][k] = *(const PG8_LAS bf16x8*)(lds + PG8_SB(b, h) + boff + n * 2048 + k * 1024); } while (0)
; #define PG8_MMA(ai, bj, At, Bt) do { __builtin_amdgcn_s_setprio(1); _Pragma("unroll") for (int m = 0; m < 4; ++m) _Pragma("unroll") for (int n = 0; n < 2; ++n) _Pragma("unroll") for (int k = 0; k < 2; ++k) \
;         acc[ai][bj][m][n] = __builtin_amdgcn_mfma_f32_16x16x32_bf16(Bt[n][k], At[m][k], acc[ai][bj][m][n], 0, 0, 0); __builtin_amdgcn_s_setprio(0); } while (0)
; #define PG8_WAIT_V(n) asm volatile("s_waitcnt vmcnt(" #n ")" ::: "memory")
; #define PG8_WAIT_L(n) asm volatile("s_waitcnt lgkmcnt(" #n ")" ::: "memory")
; #define PG8_BAR __builtin_amdgcn_s_barrier()
; #define PG8_SCHED __builtin_amdgcn_sched_barrier(0)
; template <class Epi, class Sched, bool ALIGN_EPI = false, bool SP2 = false>
; __device__ __forceinline__ void gemm_phase(PG8_LAS unsigned char* lds, const Gemm g, const Sched& S, const Epi& E) {
;     ...
;             const char* a1 = cA + (size_t)(t + 1) * kstA;
;             const char* a2 = last ? nA : cA + (size_t)(t + 2) * kstA; const char* b2 = last ? nB : cB + (size_t)(t + 2) * kstep;
;             const char* a3 = a2 + kstA; const char* b3 = b2 + kstep;
;             if (last && has_next) S.a_ready(nxt);
;             if constexpr (SP2) {
;             PG8_LDB(B0, 0, 0); PG8_LDB(B1, 0, 1); PG8_SCHED; PG8_LDA(At, 0, 0); PG8_STAGE(PG8_SA(1, 1), a1 + hstepA, voffA);
;             PG8_WAIT_V(8); PG8_WAIT_L(0); PG8_BAR; PG8_MMA(0, 0, At, B0); PG8_MMA(0, 1, At, B1); PG8_BAR; PG8_SCHED;
;             PG8_LDA(At, 0, 1); PG8_STAGE(PG8_SB(0, 0), b2, voffB); PG8_STAGE(PG8_SB(0, 1), b2 + hstepB, voffB); PG8_STAGE(PG8_SA(0, 0), a2, voffA);
.LBB0_3058:
	ds_read_b128 v[156:159], v152
	ds_read_b128 v[160:163], v152 offset:1024
	ds_read_b128 v[164:167], v152 offset:2048
	ds_read_b128 v[168:171], v152 offset:3072
	ds_read_b128 v[172:175], v153
	ds_read_b128 v[176:179], v153 offset:1024
	ds_read_b128 v[180:183], v153 offset:2048
	ds_read_b128 v[190:193], v153 offset:3072
	s_add_u32 s42, s40, 0xfff80080
	s_addc_u32 s43, s41, -1
	s_cmp_eq_u32 s35, 28
	s_cselect_b32 s45, s4, s43
	s_cselect_b32 s44, s5, s42
	s_cselect_b32 s43, s12, s23
	s_cselect_b32 s42, s13, s21
	v_lshl_add_u64 v[226:227], s[40:41], 0, v[142:143]
	s_add_i32 m0, s8, 0xc000
	ds_read_b128 v[194:197], v154
	ds_read_b128 v[198:201], v154 offset:1024
	ds_read_b128 v[202:205], v154 offset:2048
	ds_read_b128 v[206:209], v154 offset:3072
	ds_read_b128 v[210:213], v154 offset:4096
	ds_read_b128 v[214:217], v154 offset:5120
	ds_read_b128 v[218:221], v154 offset:6144
	ds_read_b128 v[222:225], v154 offset:7168
	global_load_lds_dwordx4 v[226:227], off
	v_lshl_add_u64 v[226:227], s[40:41], 0, v[144:145]
	s_add_i32 m0, s8, 0xe000
	s_nop 0
	global_load_lds_dwordx4 v[226:227], off
	s_waitcnt vmcnt(8)
	s_waitcnt lgkmcnt(0)
	s_setprio 1
	s_barrier
	v_mfma_f32_16x16x32_bf16 v[124:127], v[156:159], v[194:197], v[124:127]
	v_mfma_f32_16x16x32_bf16 v[120:123], v[164:167], v[194:197], v[120:123]
	v_mfma_f32_16x16x32_bf16 v[108:111], v[156:159], v[202:205], v[108:111]
	v_mfma_f32_16x16x32_bf16 v[104:107], v[164:167], v[202:205], v[104:107]
	v_mfma_f32_16x16x32_bf16 v[92:95], v[156:159], v[210:213], v[92:95]
	v_mfma_f32_16x16x32_bf16 v[88:91], v[164:167], v[210:213], v[88:91]
	v_mfma_f32_16x16x32_bf16 v[76:79], v[156:159], v[218:221], v[76:79]
	v_mfma_f32_16x16x32_bf16 v[72:75], v[164:167], v[218:221], v[72:75]
	v_mfma_f32_16x16x32_bf16 v[124:127], v[160:163], v[198:201], v[124:127]
	v_mfma_f32_16x16x32_bf16 v[120:123], v[168:171], v[198:201], v[120:123]
	v_mfma_f32_16x16x32_bf16 v[108:111], v[160:163], v[206:209], v[108:111]
	v_mfma_f32_16x16x32_bf16 v[104:107], v[168:171], v[206:209], v[104:107]
	v_mfma_f32_16x16x32_bf16 v[92:95], v[160:163], v[214:217], v[92:95]
	v_mfma_f32_16x16x32_bf16 v[88:91], v[168:171], v[214:217], v[88:91]
	v_mfma_f32_16x16x32_bf16 v[76:79], v[160:163], v[222:225], v[76:79]
	v_mfma_f32_16x16x32_bf16 v[72:75], v[168:171], v[222:225], v[72:75]
	v_mfma_f32_16x16x32_bf16 v[116:119], v[172:175], v[194:197], v[116:119]
	v_mfma_f32_16x16x32_bf16 v[112:115], v[180:183], v[194:197], v[112:115]
	v_mfma_f32_16x16x32_bf16 v[100:103], v[172:175], v[202:205], v[100:103]
	v_mfma_f32_16x16x32_bf16 v[96:99], v[180:183], v[202:205], v[96:99]
	v_mfma_f32_16x16x32_bf16 v[84:87], v[172:175], v[210:213], v[84:87]
	v_mfma_f32_16x16x32_bf16 v[80:83], v[180:183], v[210:213], v[80:83]
	v_mfma_f32_16x16x32_bf16 v[68:71], v[172:175], v[218:221], v[68:71]
	v_mfma_f32_16x16x32_bf16 v[64:67], v[180:183], v[218:221], v[64:67]
	v_mfma_f32_16x16x32_bf16 v[116:119], v[176:179], v[198:201], v[116:119]
	v_mfma_f32_16x16x32_bf16 v[112:115], v[190:193], v[198:201], v[112:115]
	v_mfma_f32_16x16x32_bf16 v[100:103], v[176:179], v[206:209], v[100:103]
	v_mfma_f32_16x16x32_bf16 v[96:99], v[190:193], v[206:209], v[96:99]
	v_mfma_f32_16x16x32_bf16 v[84:87], v[176:179], v[214:217], v[84:87]
	v_mfma_f32_16x16x32_bf16 v[80:83], v[190:193], v[214:217], v[80:83]
	v_mfma_f32_16x16x32_bf16 v[68:71], v[176:179], v[222:225], v[68:71]
	v_mfma_f32_16x16x32_bf16 v[64:67], v[190:193], v[222:225], v[64:67]
	s_barrier
	s_setprio 0
	s_add_i32 s53, s50, s7
	v_lshl_add_u64 v[226:227], s[42:43], 0, v[130:131]
	s_mov_b32 m0, s53
	ds_read_b128 v[194:197], v154 offset:16384
	ds_read_b128 v[198:201], v154 offset:17408
	ds_read_b128 v[202:205], v154 offset:18432
	ds_read_b128 v[206:209], v154 offset:19456
	ds_read_b128 v[210:213], v154 offset:20480
	ds_read_b128 v[214:217], v154 offset:21504
	ds_read_b128 v[218:221], v154 offset:22528
	ds_read_b128 v[222:225], v154 offset:23552
	global_load_lds_dwordx4 v[226:227], off
	s_add_i32 m0, s53, 0x2000
	s_add_u32 s54, s42, 0x80000
	v_lshl_add_u64 v[228:229], s[42:43], 0, v[134:135]
	s_addc_u32 s55, s43, 0
	s_add_i32 s53, s51, s7
	global_load_lds_dwordx4 v[228:229], off
	v_lshl_add_u64 v[230:231], s[54:55], 0, v[130:131]
	s_mov_b32 m0, s53
	v_lshl_add_u64 v[232:233], s[44:45], 0, v[132:133]
	global_load_lds_dwordx4 v[230:231], off
	v_lshl_add_u64 v[230:231], s[54:55], 0, v[134:135]
	s_add_i32 m0, s53, 0x2000
	s_nop 0
	global_load_lds_dwordx4 v[230:231], off
	v_lshl_add_u64 v[230:231], s[44:45], 0, v[128:129]
	s_mov_b32 m0, s8
	s_nop 0
	global_load_lds_dwordx4 v[230:231], off
	s_mov_b32 m0, s9
	s_nop 0
	global_load_lds_dwordx4 v[232:233], off
	s_waitcnt vmcnt(8)
	s_waitcnt lgkmcnt(0)
	s_setprio 1
	s_barrier
; #define PG8_STAGE(bufoff, gbase, voff) do { _Pragma("unroll") for (int _i = 0; _i < 2; ++_i) \
;         __builtin_amdgcn_global_load_lds((const unsigned*)((const char*)(gbase) + (voff)[_i]), (PG8_LAS unsigned*)(lds + (bufoff) + ldsw + _i * 8192), 16, 0, 0); } while (0)
; #define PG8_LDA(dst, b, h) do { _Pragma("unroll") for (int m = 0; m < 4; ++m) _Pragma("unroll") for (int k = 0; k < 2; ++k) dst[m][k] = *(const PG8_LAS bf16x8*)(lds + PG8_SA(b, h) + aoff + m * 2048 + k * 1024); } while (0)
; #define PG8_LDB(dst, b, h) do { _Pragma("unroll") for (int n = 0; n < 2; ++n) _Pragma("unroll") for (int k = 0; k < 2; ++k) dst[n][k] = *(const PG8_LAS bf16x8*)(lds + PG8_SB(b, h) + boff + n * 2048 + k * 1024); } while (0)
; #define PG8_MMA(ai, bj, At, Bt) do { __builtin_amdgcn_s_setprio(1); _Pragma("unroll") for (int m = 0; m < 4; ++m) _Pragma("unroll") for (int n = 0; n < 2; ++n) _Pragma("unroll") for (int k = 0; k < 2; ++k) \
;         acc[ai][bj][m][n] = __builtin_amdgcn_mfma_f32_16x16x32_bf16(Bt[n][k], At[m][k], acc[ai][bj][m][n], 0, 0, 0); __builtin_amdgcn_s_setprio(0); } while (0)
; #define PG8_WAIT_V(n) asm volatile("s_waitcnt vmcnt(" #n ")" ::: "memory")
; #define PG8_WAIT_L(n) asm volatile("s_waitcnt lgkmcnt(" #n ")" ::: "memory")
; #define PG8_BAR __builtin_amdgcn_s_barrier()
; #define PG8_SCHED __builtin_amdgcn_sched_barrier(0)
; template <class Epi, class Sched, bool ALIGN_EPI = false, bool SP2 = false>
; __device__ __forceinline__ void gemm_phase(PG8_LAS unsigned char* lds, const Gemm g, const Sched& S, const Epi& E) {
;     ...
;             PG8_WAIT_V(8); PG8_WAIT_L(0); PG8_BAR; PG8_MMA(1, 0, At, B0); PG8_MMA(1, 1, At, B1); PG8_BAR; PG8_SCHED;
;             PG8_LDB(B0, 1, 0); PG8_LDB(B1, 1, 1); PG8_SCHED; PG8_LDA(At, 1, 0); PG8_STAGE(PG8_SA(0, 1), a2 + hstepA, voffA);
;             PG8_WAIT_V(8); PG8_WAIT_L(0); PG8_BAR; PG8_MMA(0, 0, At, B0); PG8_MMA(0, 1, At, B1); PG8_BAR; PG8_SCHED;
	v_mfma_f32_16x16x32_bf16 v[60:63], v[156:159], v[194:197], v[60:63]
	v_mfma_f32_16x16x32_bf16 v[56:59], v[164:167], v[194:197], v[56:59]
	v_mfma_f32_16x16x32_bf16 v[44:47], v[156:159], v[202:205], v[44:47]
	v_mfma_f32_16x16x32_bf16 v[40:43], v[164:167], v[202:205], v[40:43]
	v_mfma_f32_16x16x32_bf16 v[28:31], v[156:159], v[210:213], v[28:31]
	v_mfma_f32_16x16x32_bf16 v[24:27], v[164:167], v[210:213], v[24:27]
	v_mfma_f32_16x16x32_bf16 v[12:15], v[156:159], v[218:221], v[12:15]
	v_mfma_f32_16x16x32_bf16 v[8:11], v[164:167], v[218:221], v[8:11]
	v_mfma_f32_16x16x32_bf16 v[60:63], v[160:163], v[198:201], v[60:63]
	v_mfma_f32_16x16x32_bf16 v[56:59], v[168:171], v[198:201], v[56:59]
	v_mfma_f32_16x16x32_bf16 v[44:47], v[160:163], v[206:209], v[44:47]
	v_mfma_f32_16x16x32_bf16 v[40:43], v[168:171], v[206:209], v[40:43]
	v_mfma_f32_16x16x32_bf16 v[28:31], v[160:163], v[214:217], v[28:31]
	v_mfma_f32_16x16x32_bf16 v[24:27], v[168:171], v[214:217], v[24:27]
	v_mfma_f32_16x16x32_bf16 v[12:15], v[160:163], v[222:225], v[12:15]
	v_mfma_f32_16x16x32_bf16 v[8:11], v[168:171], v[222:225], v[8:11]
	v_mfma_f32_16x16x32_bf16 v[52:55], v[172:175], v[194:197], v[52:55]
	v_mfma_f32_16x16x32_bf16 v[48:51], v[180:183], v[194:197], v[48:51]
	v_mfma_f32_16x16x32_bf16 v[36:39], v[172:175], v[202:205], v[36:39]
	v_mfma_f32_16x16x32_bf16 v[32:35], v[180:183], v[202:205], v[32:35]
	v_mfma_f32_16x16x32_bf16 v[20:23], v[172:175], v[210:213], v[20:23]
	v_mfma_f32_16x16x32_bf16 v[16:19], v[180:183], v[210:213], v[16:19]
	v_mfma_f32_16x16x32_bf16 v[4:7], v[172:175], v[218:221], v[4:7]
	v_mfma_f32_16x16x32_bf16 v[0:3], v[180:183], v[218:221], v[0:3]
	v_mfma_f32_16x16x32_bf16 v[52:55], v[176:179], v[198:201], v[52:55]
	v_mfma_f32_16x16x32_bf16 v[48:51], v[190:193], v[198:201], v[48:51]
	v_mfma_f32_16x16x32_bf16 v[36:39], v[176:179], v[206:209], v[36:39]
	v_mfma_f32_16x16x32_bf16 v[32:35], v[190:193], v[206:209], v[32:35]
	v_mfma_f32_16x16x32_bf16 v[20:23], v[176:179], v[214:217], v[20:23]
	v_mfma_f32_16x16x32_bf16 v[16:19], v[190:193], v[214:217], v[16:19]
	v_mfma_f32_16x16x32_bf16 v[4:7], v[176:179], v[222:225], v[4:7]
	v_mfma_f32_16x16x32_bf16 v[0:3], v[190:193], v[222:225], v[0:3]
	s_barrier
	s_setprio 0
	s_add_i32 s53, 0, 0x18000
	v_add_u32_e32 v155, s53, v150
	s_add_i32 s54, 0, 0x1c000
	ds_read_b128 v[156:159], v155
	ds_read_b128 v[160:163], v155 offset:1024
	ds_read_b128 v[164:167], v155 offset:2048
	ds_read_b128 v[168:171], v155 offset:3072
	v_add_u32_e32 v155, s54, v150
	ds_read_b128 v[172:175], v155
	ds_read_b128 v[176:179], v155 offset:1024
	ds_read_b128 v[180:183], v155 offset:2048
	ds_read_b128 v[190:193], v155 offset:3072
	s_add_u32 s44, s44, 0x80000
	s_addc_u32 s45, s45, 0
	s_mov_b32 m0, s10
	v_lshl_add_u64 v[234:235], s[44:45], 0, v[128:129]
	ds_read_b128 v[194:197], v154 offset:32768
	ds_read_b128 v[198:201], v154 offset:33792
	ds_read_b128 v[202:205], v154 offset:34816
	ds_read_b128 v[206:209], v154 offset:35840
	ds_read_b128 v[210:213], v154 offset:36864
	ds_read_b128 v[214:217], v154 offset:37888
	ds_read_b128 v[218:221], v154 offset:38912
	ds_read_b128 v[222:225], v154 offset:39936
	global_load_lds_dwordx4 v[234:235], off
	v_lshl_add_u64 v[234:235], s[44:45], 0, v[132:133]
	s_mov_b32 m0, s11
	s_nop 0
	global_load_lds_dwordx4 v[234:235], off
	s_waitcnt vmcnt(8)
	s_waitcnt lgkmcnt(0)
	s_setprio 1
	s_barrier
	v_mfma_f32_16x16x32_bf16 v[124:127], v[156:159], v[194:197], v[124:127]
	v_mfma_f32_16x16x32_bf16 v[120:123], v[164:167], v[194:197], v[120:123]
	v_mfma_f32_16x16x32_bf16 v[108:111], v[156:159], v[202:205], v[108:111]
	v_mfma_f32_16x16x32_bf16 v[104:107], v[164:167], v[202:205], v[104:107]
	v_mfma_f32_16x16x32_bf16 v[92:95], v[156:159], v[210:213], v[92:95]
	v_mfma_f32_16x16x32_bf16 v[88:91], v[164:167], v[210:213], v[88:91]
	v_mfma_f32_16x16x32_bf16 v[76:79], v[156:159], v[218:221], v[76:79]
	v_mfma_f32_16x16x32_bf16 v[72:75], v[164:167], v[218:221], v[72:75]
	v_mfma_f32_16x16x32_bf16 v[124:127], v[160:163], v[198:201], v[124:127]
	v_mfma_f32_16x16x32_bf16 v[120:123], v[168:171], v[198:201], v[120:123]
	v_mfma_f32_16x16x32_bf16 v[108:111], v[160:163], v[206:209], v[108:111]
	v_mfma_f32_16x16x32_bf16 v[104:107], v[168:171], v[206:209], v[104:107]
	v_mfma_f32_16x16x32_bf16 v[92:95], v[160:163], v[214:217], v[92:95]
	v_mfma_f32_16x16x32_bf16 v[88:91], v[168:171], v[214:217], v[88:91]
	v_mfma_f32_16x16x32_bf16 v[76:79], v[160:163], v[222:225], v[76:79]
	v_mfma_f32_16x16x32_bf16 v[72:75], v[168:171], v[222:225], v[72:75]
	v_mfma_f32_16x16x32_bf16 v[116:119], v[172:175], v[194:197], v[116:119]
	v_mfma_f32_16x16x32_bf16 v[112:115], v[180:183], v[194:197], v[112:115]
	v_mfma_f32_16x16x32_bf16 v[100:103], v[172:175], v[202:205], v[100:103]
	v_mfma_f32_16x16x32_bf16 v[96:99], v[180:183], v[202:205], v[96:99]
	v_mfma_f32_16x16x32_bf16 v[84:87], v[172:175], v[210:213], v[84:87]
	v_mfma_f32_16x16x32_bf16 v[80:83], v[180:183], v[210:213], v[80:83]
	v_mfma_f32_16x16x32_bf16 v[68:71], v[172:175], v[218:221], v[68:71]
	v_mfma_f32_16x16x32_bf16 v[64:67], v[180:183], v[218:221], v[64:67]
	v_mfma_f32_16x16x32_bf16 v[116:119], v[176:179], v[198:201], v[116:119]
	v_mfma_f32_16x16x32_bf16 v[112:115], v[190:193], v[198:201], v[112:115]
	v_mfma_f32_16x16x32_bf16 v[100:103], v[176:179], v[206:209], v[100:103]
	v_mfma_f32_16x16x32_bf16 v[96:99], v[190:193], v[206:209], v[96:99]
	v_mfma_f32_16x16x32_bf16 v[84:87], v[176:179], v[214:217], v[84:87]
	v_mfma_f32_16x16x32_bf16 v[80:83], v[190:193], v[214:217], v[80:83]
	v_mfma_f32_16x16x32_bf16 v[68:71], v[176:179], v[222:225], v[68:71]
	v_mfma_f32_16x16x32_bf16 v[64:67], v[190:193], v[222:225], v[64:67]
	s_barrier
; #define PG8_STAGE(bufoff, gbase, voff) do { _Pragma("unroll") for (int _i = 0; _i < 2; ++_i) \
;         __builtin_amdgcn_global_load_lds((const unsigned*)((const char*)(gbase) + (voff)[_i]), (PG8_LAS unsigned*)(lds + (bufoff) + ldsw + _i * 8192), 16, 0, 0); } while (0)
; #define PG8_LDA(dst, b, h) do { _Pragma("unroll") for (int m = 0; m < 4; ++m) _Pragma("unroll") for (int k = 0; k < 2; ++k) dst[m][k] = *(const PG8_LAS bf16x8*)(lds + PG8_SA(b, h) + aoff + m * 2048 + k * 1024); } while (0)
; #define PG8_MMA(ai, bj, At, Bt) do { __builtin_amdgcn_s_setprio(1); _Pragma("unroll") for (int m = 0; m < 4; ++m) _Pragma("unroll") for (int n = 0; n < 2; ++n) _Pragma("unroll") for (int k = 0; k < 2; ++k) \
;         acc[ai][bj][m][n] = __builtin_amdgcn_mfma_f32_16x16x32_bf16(Bt[n][k], At[m][k], acc[ai][bj][m][n], 0, 0, 0); __builtin_amdgcn_s_setprio(0); } while (0)
; #define PG8_WAIT_V(n) asm volatile("s_waitcnt vmcnt(" #n ")" ::: "memory")
; #define PG8_WAIT_L(n) asm volatile("s_waitcnt lgkmcnt(" #n ")" ::: "memory")
; #define PG8_BAR __builtin_amdgcn_s_barrier()
; #define PG8_SCHED __builtin_amdgcn_sched_barrier(0)
; template <class Epi, class Sched, bool ALIGN_EPI = false, bool SP2 = false>
; __device__ __forceinline__ void gemm_phase(PG8_LAS unsigned char* lds, const Gemm g, const Sched& S, const Epi& E) {
;     ...
;             PG8_LDA(At, 1, 1); PG8_STAGE(PG8_SB(1, 0), b3, voffB); PG8_STAGE(PG8_SB(1, 1), b3 + hstepB, voffB); PG8_STAGE(PG8_SA(1, 0), a3, voffA);
;             PG8_WAIT_V(8); PG8_WAIT_L(0); PG8_BAR; PG8_MMA(1, 0, At, B0); PG8_MMA(1, 1, At, B1); PG8_BAR; PG8_SCHED;
	s_setprio 0
	s_add_i32 s44, s53, s7
	v_lshl_add_u64 v[226:227], v[226:227], 0, s[16:17]
	s_mov_b32 m0, s44
	ds_read_b128 v[194:197], v154 offset:49152
	ds_read_b128 v[198:201], v154 offset:50176
	ds_read_b128 v[202:205], v154 offset:51200
	ds_read_b128 v[206:209], v154 offset:52224
	ds_read_b128 v[210:213], v154 offset:53248
	ds_read_b128 v[214:217], v154 offset:54272
	ds_read_b128 v[218:221], v154 offset:55296
	ds_read_b128 v[222:225], v154 offset:56320
	global_load_lds_dwordx4 v[226:227], off
	s_add_i32 m0, s44, 0x2000
	s_add_u32 s42, s42, 0x80080
	v_lshl_add_u64 v[226:227], v[228:229], 0, s[16:17]
	s_addc_u32 s43, s43, 0
	s_add_i32 s44, s54, s7
	global_load_lds_dwordx4 v[226:227], off
	v_lshl_add_u64 v[226:227], s[42:43], 0, v[130:131]
	s_mov_b32 m0, s44
	s_nop 0
	global_load_lds_dwordx4 v[226:227], off
	v_lshl_add_u64 v[226:227], s[42:43], 0, v[134:135]
	s_add_i32 m0, s44, 0x2000
	s_nop 0
	global_load_lds_dwordx4 v[226:227], off
	v_lshl_add_u64 v[226:227], v[230:231], 0, s[16:17]
	s_mov_b32 m0, s48
	s_nop 0
	global_load_lds_dwordx4 v[226:227], off
	v_lshl_add_u64 v[226:227], v[232:233], 0, s[16:17]
	s_mov_b32 m0, s49
	s_nop 0
	global_load_lds_dwordx4 v[226:227], off
	s_waitcnt vmcnt(8)
	s_waitcnt lgkmcnt(0)
	s_setprio 1
	s_barrier
	v_mfma_f32_16x16x32_bf16 v[60:63], v[156:159], v[194:197], v[60:63]
	v_mfma_f32_16x16x32_bf16 v[56:59], v[164:167], v[194:197], v[56:59]
	v_mfma_f32_16x16x32_bf16 v[44:47], v[156:159], v[202:205], v[44:47]
	v_mfma_f32_16x16x32_bf16 v[40:43], v[164:167], v[202:205], v[40:43]
	v_mfma_f32_16x16x32_bf16 v[28:31], v[156:159], v[210:213], v[28:31]
	v_mfma_f32_16x16x32_bf16 v[24:27], v[164:167], v[210:213], v[24:27]
	v_mfma_f32_16x16x32_bf16 v[12:15], v[156:159], v[218:221], v[12:15]
	v_mfma_f32_16x16x32_bf16 v[8:11], v[164:167], v[218:221], v[8:11]
	v_mfma_f32_16x16x32_bf16 v[60:63], v[160:163], v[198:201], v[60:63]
	v_mfma_f32_16x16x32_bf16 v[56:59], v[168:171], v[198:201], v[56:59]
	v_mfma_f32_16x16x32_bf16 v[44:47], v[160:163], v[206:209], v[44:47]
	v_mfma_f32_16x16x32_bf16 v[40:43], v[168:171], v[206:209], v[40:43]
	v_mfma_f32_16x16x32_bf16 v[28:31], v[160:163], v[214:217], v[28:31]
	v_mfma_f32_16x16x32_bf16 v[24:27], v[168:171], v[214:217], v[24:27]
	v_mfma_f32_16x16x32_bf16 v[12:15], v[160:163], v[222:225], v[12:15]
	v_mfma_f32_16x16x32_bf16 v[8:11], v[168:171], v[222:225], v[8:11]
	v_mfma_f32_16x16x32_bf16 v[52:55], v[172:175], v[194:197], v[52:55]
	v_mfma_f32_16x16x32_bf16 v[48:51], v[180:183], v[194:197], v[48:51]
	v_mfma_f32_16x16x32_bf16 v[36:39], v[172:175], v[202:205], v[36:39]
	v_mfma_f32_16x16x32_bf16 v[32:35], v[180:183], v[202:205], v[32:35]
	v_mfma_f32_16x16x32_bf16 v[20:23], v[172:175], v[210:213], v[20:23]
	v_mfma_f32_16x16x32_bf16 v[16:19], v[180:183], v[210:213], v[16:19]
	v_mfma_f32_16x16x32_bf16 v[4:7], v[172:175], v[218:221], v[4:7]
	v_mfma_f32_16x16x32_bf16 v[0:3], v[180:183], v[218:221], v[0:3]
	v_mfma_f32_16x16x32_bf16 v[52:55], v[176:179], v[198:201], v[52:55]
	v_mfma_f32_16x16x32_bf16 v[48:51], v[190:193], v[198:201], v[48:51]
	v_mfma_f32_16x16x32_bf16 v[36:39], v[176:179], v[206:209], v[36:39]
	v_mfma_f32_16x16x32_bf16 v[32:35], v[190:193], v[206:209], v[32:35]
	v_mfma_f32_16x16x32_bf16 v[20:23], v[176:179], v[214:217], v[20:23]
	v_mfma_f32_16x16x32_bf16 v[16:19], v[190:193], v[214:217], v[16:19]
	v_mfma_f32_16x16x32_bf16 v[4:7], v[176:179], v[222:225], v[4:7]
	v_mfma_f32_16x16x32_bf16 v[0:3], v[190:193], v[222:225], v[0:3]
	s_barrier
	s_setprio 0
	s_add_i32 s35, s35, 2
	s_add_u32 s40, s40, 0x100
	s_addc_u32 s41, s41, 0
	s_add_u32 s21, s21, 0x100
	s_addc_u32 s23, s23, 0
	s_cmp_gt_u32 s35, 29
	s_cbranch_scc0 .LBB0_3058
	s_and_b64 vcc, exec, s[18:19]
	s_cbranch_vccz .LBB0_3061
	s_barrier

; #define PG8_STAGE(bufoff, gbase, voff) do { _Pragma("unroll") for (int _i = 0; _i < 2; ++_i) \
;         __builtin_amdgcn_global_load_lds((const unsigned*)((const char*)(gbase) + (voff)[_i]), (PG8_LAS unsigned*)(lds + (bufoff) + ldsw + _i * 8192), 16, 0, 0); } while (0)
; #define PG8_LDA(dst, b, h) do { _Pragma("unroll") for (int m = 0; m < 4; ++m) _Pragma("unroll") for (int k = 0; k < 2; ++k) dst[m][k] = *(const PG8_LAS bf16x8*)(lds + PG8_SA(b, h) + aoff + m * 2048 + k * 1024); } while (0)
; #define PG8_LDB(dst, b, h) do { _Pragma("unroll") for (int n = 0; n < 2; ++n) _Pragma("unroll") for (int k = 0; k < 2; ++k) dst[n][k] = *(const PG8_LAS bf16x8*)(lds + PG8_SB(b, h) + boff + n * 2048 + k * 1024); } while (0)
; #define PG8_MMA(ai, bj, At, Bt) do { __builtin_amdgcn_s_setprio(1); _Pragma("unroll") for (int m = 0; m < 4; ++m) _Pragma("unroll") for (int n = 0; n < 2; ++n) _Pragma("unroll") for (int k = 0; k < 2; ++k) \
;         acc[ai][bj][m][n] = __builtin_amdgcn_mfma_f32_16x16x32_bf16(Bt[n][k], At[m][k], acc[ai][bj][m][n], 0, 0, 0); __builtin_amdgcn_s_setprio(0); } while (0)
; #define PG8_WAIT_V(n) asm volatile("s_waitcnt vmcnt(" #n ")" ::: "memory")
; #define PG8_WAIT_L(n) asm volatile("s_waitcnt lgkmcnt(" #n ")" ::: "memory")
; #define PG8_BAR __builtin_amdgcn_s_barrier()
; #define PG8_SCHED __builtin_amdgcn_sched_barrier(0)
; template <class Epi, class Sched, bool ALIGN_EPI = false, bool SP2 = false>
; __device__ __forceinline__ void gemm_phase(PG8_LAS unsigned char* lds, const Gemm g, const Sched& S, const Epi& E) {
;     ...
;             const char* a1 = cA + (size_t)(t + 1) * kstA;
;             const char* a2 = last ? nA : cA + (size_t)(t + 2) * kstA; const char* b2 = last ? nB : cB + (size_t)(t + 2) * kstep;
;             const char* a3 = a2 + kstA; const char* b3 = b2 + kstep;
;             if (last && has_next) S.a_ready(nxt);
;             if constexpr (SP2) {
;             PG8_LDB(B0, 0, 0); PG8_LDB(B1, 0, 1); PG8_SCHED; PG8_LDA(At, 0, 0); PG8_STAGE(PG8_SA(1, 1), a1 + hstepA, voffA);
;             PG8_WAIT_V(8); PG8_WAIT_L(0); PG8_BAR; PG8_MMA(0, 0, At, B0); PG8_MMA(0, 1, At, B1); PG8_BAR; PG8_SCHED;
;             PG8_LDA(At, 0, 1); PG8_STAGE(PG8_SB(0, 0), b2, voffB); PG8_STAGE(PG8_SB(0, 1), b2 + hstepB, voffB); PG8_STAGE(PG8_SA(0, 0), a2, voffA);
.LBB0_3147:
	v_add_u32_e32 v176, s64, v178
	ds_read_b128 v[164:167], v176
	ds_read_b128 v[168:171], v176 offset:1024
	ds_read_b128 v[172:175], v176 offset:2048
	ds_read_b128 v[190:193], v176 offset:3072
	v_add_u32_e32 v176, s65, v178
	ds_read_b128 v[194:197], v176
	ds_read_b128 v[198:201], v176 offset:1024
	ds_read_b128 v[202:205], v176 offset:2048
	ds_read_b128 v[206:209], v176 offset:3072
	s_add_u32 s12, s20, s46
	s_addc_u32 s13, s21, s47
	s_cmp_eq_u32 s7, s5
	s_cselect_b32 s52, s42, s12
	s_cselect_b32 s53, s43, s13
	s_cselect_b32 s51, s45, s4
	s_cselect_b32 s50, s44, s1
	s_add_u32 s48, s52, 0x8000
	s_addc_u32 s49, s53, 0
	v_lshl_add_u64 v[176:177], s[20:21], 0, v[162:163]
	s_add_i32 m0, s55, 0xc000
	ds_read_b128 v[210:213], v180
	ds_read_b128 v[214:217], v180 offset:1024
	ds_read_b128 v[218:221], v180 offset:2048
	ds_read_b128 v[222:225], v180 offset:3072
	ds_read_b128 v[226:229], v180 offset:4096
	ds_read_b128 v[230:233], v180 offset:5120
	ds_read_b128 v[234:237], v180 offset:6144
	ds_read_b128 v[238:241], v180 offset:7168
	global_load_lds_dwordx4 v[176:177], off
	v_lshl_add_u64 v[176:177], s[20:21], 0, v[160:161]
	s_add_i32 m0, s55, 0xe000
	s_nop 0
	global_load_lds_dwordx4 v[176:177], off
	s_waitcnt vmcnt(8)
	s_waitcnt lgkmcnt(0)
	s_setprio 1
	s_barrier
	v_mfma_f32_16x16x32_bf16 v[124:127], v[164:167], v[210:213], v[124:127]
	v_mfma_f32_16x16x32_bf16 v[120:123], v[172:175], v[210:213], v[120:123]
	v_mfma_f32_16x16x32_bf16 v[116:119], v[164:167], v[218:221], v[116:119]
	v_mfma_f32_16x16x32_bf16 v[112:115], v[172:175], v[218:221], v[112:115]
	v_mfma_f32_16x16x32_bf16 v[108:111], v[164:167], v[226:229], v[108:111]
	v_mfma_f32_16x16x32_bf16 v[104:107], v[172:175], v[226:229], v[104:107]
	v_mfma_f32_16x16x32_bf16 v[100:103], v[164:167], v[234:237], v[100:103]
	v_mfma_f32_16x16x32_bf16 v[96:99], v[172:175], v[234:237], v[96:99]
	v_mfma_f32_16x16x32_bf16 v[124:127], v[168:171], v[214:217], v[124:127]
	v_mfma_f32_16x16x32_bf16 v[120:123], v[190:193], v[214:217], v[120:123]
	v_mfma_f32_16x16x32_bf16 v[116:119], v[168:171], v[222:225], v[116:119]
	v_mfma_f32_16x16x32_bf16 v[112:115], v[190:193], v[222:225], v[112:115]
	v_mfma_f32_16x16x32_bf16 v[108:111], v[168:171], v[230:233], v[108:111]
	v_mfma_f32_16x16x32_bf16 v[104:107], v[190:193], v[230:233], v[104:107]
	v_mfma_f32_16x16x32_bf16 v[100:103], v[168:171], v[238:241], v[100:103]
	v_mfma_f32_16x16x32_bf16 v[96:99], v[190:193], v[238:241], v[96:99]
	v_mfma_f32_16x16x32_bf16 v[92:95], v[194:197], v[210:213], v[92:95]
	v_mfma_f32_16x16x32_bf16 v[88:91], v[202:205], v[210:213], v[88:91]
	v_mfma_f32_16x16x32_bf16 v[84:87], v[194:197], v[218:221], v[84:87]
	v_mfma_f32_16x16x32_bf16 v[80:83], v[202:205], v[218:221], v[80:83]
	v_mfma_f32_16x16x32_bf16 v[76:79], v[194:197], v[226:229], v[76:79]
	v_mfma_f32_16x16x32_bf16 v[72:75], v[202:205], v[226:229], v[72:75]
	v_mfma_f32_16x16x32_bf16 v[68:71], v[194:197], v[234:237], v[68:71]
	v_mfma_f32_16x16x32_bf16 v[64:67], v[202:205], v[234:237], v[64:67]
	v_mfma_f32_16x16x32_bf16 v[92:95], v[198:201], v[214:217], v[92:95]
	v_mfma_f32_16x16x32_bf16 v[88:91], v[206:209], v[214:217], v[88:91]
	v_mfma_f32_16x16x32_bf16 v[84:87], v[198:201], v[222:225], v[84:87]
	v_mfma_f32_16x16x32_bf16 v[80:83], v[206:209], v[222:225], v[80:83]
	v_mfma_f32_16x16x32_bf16 v[76:79], v[198:201], v[230:233], v[76:79]
	v_mfma_f32_16x16x32_bf16 v[72:75], v[206:209], v[230:233], v[72:75]
	v_mfma_f32_16x16x32_bf16 v[68:71], v[198:201], v[238:241], v[68:71]
	v_mfma_f32_16x16x32_bf16 v[64:67], v[206:209], v[238:241], v[64:67]
	s_barrier
	s_setprio 0
	s_add_i32 s12, s64, s54
	v_lshl_add_u64 v[176:177], s[50:51], 0, v[130:131]
	s_mov_b32 m0, s12
	ds_read_b128 v[210:213], v180 offset:16384
	ds_read_b128 v[214:217], v180 offset:17408
	ds_read_b128 v[218:221], v180 offset:18432
	ds_read_b128 v[222:225], v180 offset:19456
	ds_read_b128 v[226:229], v180 offset:20480
	ds_read_b128 v[230:233], v180 offset:21504
	ds_read_b128 v[234:237], v180 offset:22528
	ds_read_b128 v[238:241], v180 offset:23552
	global_load_lds_dwordx4 v[176:177], off
	s_add_i32 m0, s12, 0x2000
	s_add_u32 s12, s50, 0x160000
	v_lshl_add_u64 v[182:183], s[50:51], 0, v[134:135]
	s_addc_u32 s13, s51, 0
	s_add_i32 s17, s65, s54
	global_load_lds_dwordx4 v[182:183], off
	v_lshl_add_u64 v[242:243], s[12:13], 0, v[130:131]
	s_mov_b32 m0, s17
	s_nop 0
	global_load_lds_dwordx4 v[242:243], off
	v_lshl_add_u64 v[242:243], s[12:13], 0, v[134:135]
	s_add_i32 m0, s17, 0x2000
	s_nop 0
	global_load_lds_dwordx4 v[242:243], off
	v_lshl_add_u64 v[242:243], s[52:53], 0, v[128:129]
	s_mov_b32 m0, s55
	s_nop 0
	global_load_lds_dwordx4 v[242:243], off
	v_lshl_add_u64 v[242:243], s[52:53], 0, v[132:133]
	s_mov_b32 m0, s56
	s_nop 0
	global_load_lds_dwordx4 v[242:243], off
	s_waitcnt vmcnt(8)
	s_waitcnt lgkmcnt(0)
	s_setprio 1
	s_barrier
; #define PG8_STAGE(bufoff, gbase, voff) do { _Pragma("unroll") for (int _i = 0; _i < 2; ++_i) \
;         __builtin_amdgcn_global_load_lds((const unsigned*)((const char*)(gbase) + (voff)[_i]), (PG8_LAS unsigned*)(lds + (bufoff) + ldsw + _i * 8192), 16, 0, 0); } while (0)
; #define PG8_LDA(dst, b, h) do { _Pragma("unroll") for (int m = 0; m < 4; ++m) _Pragma("unroll") for (int k = 0; k < 2; ++k) dst[m][k] = *(const PG8_LAS bf16x8*)(lds + PG8_SA(b, h) + aoff + m * 2048 + k * 1024); } while (0)
; #define PG8_LDB(dst, b, h) do { _Pragma("unroll") for (int n = 0; n < 2; ++n) _Pragma("unroll") for (int k = 0; k < 2; ++k) dst[n][k] = *(const PG8_LAS bf16x8*)(lds + PG8_SB(b, h) + boff + n * 2048 + k * 1024); } while (0)
; #define PG8_MMA(ai, bj, At, Bt) do { __builtin_amdgcn_s_setprio(1); _Pragma("unroll") for (int m = 0; m < 4; ++m) _Pragma("unroll") for (int n = 0; n < 2; ++n) _Pragma("unroll") for (int k = 0; k < 2; ++k) \
;         acc[ai][bj][m][n] = __builtin_amdgcn_mfma_f32_16x16x32_bf16(Bt[n][k], At[m][k], acc[ai][bj][m][n], 0, 0, 0); __builtin_amdgcn_s_setprio(0); } while (0)
; #define PG8_WAIT_V(n) asm volatile("s_waitcnt vmcnt(" #n ")" ::: "memory")
; #define PG8_WAIT_L(n) asm volatile("s_waitcnt lgkmcnt(" #n ")" ::: "memory")
; #define PG8_BAR __builtin_amdgcn_s_barrier()
; #define PG8_SCHED __builtin_amdgcn_sched_barrier(0)
; template <class Epi, class Sched, bool ALIGN_EPI = false, bool SP2 = false>
; __device__ __forceinline__ void gemm_phase(PG8_LAS unsigned char* lds, const Gemm g, const Sched& S, const Epi& E) {
;     ...
;             PG8_WAIT_V(8); PG8_WAIT_L(0); PG8_BAR; PG8_MMA(1, 0, At, B0); PG8_MMA(1, 1, At, B1); PG8_BAR; PG8_SCHED;
;             PG8_LDB(B0, 1, 0); PG8_LDB(B1, 1, 1); PG8_SCHED; PG8_LDA(At, 1, 0); PG8_STAGE(PG8_SA(0, 1), a2 + hstepA, voffA);
;             PG8_WAIT_V(8); PG8_WAIT_L(0); PG8_BAR; PG8_MMA(0, 0, At, B0); PG8_MMA(0, 1, At, B1); PG8_BAR; PG8_SCHED;
	v_mfma_f32_16x16x32_bf16 v[60:63], v[164:167], v[210:213], v[60:63]
	v_mfma_f32_16x16x32_bf16 v[56:59], v[172:175], v[210:213], v[56:59]
	v_mfma_f32_16x16x32_bf16 v[52:55], v[164:167], v[218:221], v[52:55]
	v_mfma_f32_16x16x32_bf16 v[48:51], v[172:175], v[218:221], v[48:51]
	v_mfma_f32_16x16x32_bf16 v[44:47], v[164:167], v[226:229], v[44:47]
	v_mfma_f32_16x16x32_bf16 v[40:43], v[172:175], v[226:229], v[40:43]
	v_mfma_f32_16x16x32_bf16 v[36:39], v[164:167], v[234:237], v[36:39]
	v_mfma_f32_16x16x32_bf16 v[32:35], v[172:175], v[234:237], v[32:35]
	v_mfma_f32_16x16x32_bf16 v[60:63], v[168:171], v[214:217], v[60:63]
	v_mfma_f32_16x16x32_bf16 v[56:59], v[190:193], v[214:217], v[56:59]
	v_mfma_f32_16x16x32_bf16 v[52:55], v[168:171], v[222:225], v[52:55]
	v_mfma_f32_16x16x32_bf16 v[48:51], v[190:193], v[222:225], v[48:51]
	v_mfma_f32_16x16x32_bf16 v[44:47], v[168:171], v[230:233], v[44:47]
	v_mfma_f32_16x16x32_bf16 v[40:43], v[190:193], v[230:233], v[40:43]
	v_mfma_f32_16x16x32_bf16 v[36:39], v[168:171], v[238:241], v[36:39]
	v_mfma_f32_16x16x32_bf16 v[32:35], v[190:193], v[238:241], v[32:35]
	v_mfma_f32_16x16x32_bf16 v[28:31], v[194:197], v[210:213], v[28:31]
	v_mfma_f32_16x16x32_bf16 v[24:27], v[202:205], v[210:213], v[24:27]
	v_mfma_f32_16x16x32_bf16 v[20:23], v[194:197], v[218:221], v[20:23]
	v_mfma_f32_16x16x32_bf16 v[16:19], v[202:205], v[218:221], v[16:19]
	v_mfma_f32_16x16x32_bf16 v[12:15], v[194:197], v[226:229], v[12:15]
	v_mfma_f32_16x16x32_bf16 v[8:11], v[202:205], v[226:229], v[8:11]
	v_mfma_f32_16x16x32_bf16 v[4:7], v[194:197], v[234:237], v[4:7]
	v_mfma_f32_16x16x32_bf16 v[0:3], v[202:205], v[234:237], v[0:3]
	v_mfma_f32_16x16x32_bf16 v[28:31], v[198:201], v[214:217], v[28:31]
	v_mfma_f32_16x16x32_bf16 v[24:27], v[206:209], v[214:217], v[24:27]
	v_mfma_f32_16x16x32_bf16 v[20:23], v[198:201], v[222:225], v[20:23]
	v_mfma_f32_16x16x32_bf16 v[16:19], v[206:209], v[222:225], v[16:19]
	v_mfma_f32_16x16x32_bf16 v[12:15], v[198:201], v[230:233], v[12:15]
	v_mfma_f32_16x16x32_bf16 v[8:11], v[206:209], v[230:233], v[8:11]
	v_mfma_f32_16x16x32_bf16 v[4:7], v[198:201], v[238:241], v[4:7]
	v_mfma_f32_16x16x32_bf16 v[0:3], v[206:209], v[238:241], v[0:3]
	s_barrier
	s_setprio 0
	s_add_i32 s17, 0, 0x18000
	v_add_u32_e32 v181, s17, v178
	s_add_i32 s19, 0, 0x1c000
	ds_read_b128 v[164:167], v181
	ds_read_b128 v[168:171], v181 offset:1024
	ds_read_b128 v[172:175], v181 offset:2048
	ds_read_b128 v[190:193], v181 offset:3072
	v_add_u32_e32 v181, s19, v178
	ds_read_b128 v[194:197], v181
	ds_read_b128 v[198:201], v181 offset:1024
	ds_read_b128 v[202:205], v181 offset:2048
	ds_read_b128 v[206:209], v181 offset:3072
	s_add_u32 s12, s52, 0x4000
	s_addc_u32 s13, s53, 0
	s_mov_b32 m0, s57
	v_lshl_add_u64 v[242:243], s[12:13], 0, v[128:129]
	ds_read_b128 v[210:213], v180 offset:32768
	ds_read_b128 v[214:217], v180 offset:33792
	ds_read_b128 v[218:221], v180 offset:34816
	ds_read_b128 v[222:225], v180 offset:35840
	ds_read_b128 v[226:229], v180 offset:36864
	ds_read_b128 v[230:233], v180 offset:37888
	ds_read_b128 v[234:237], v180 offset:38912
	ds_read_b128 v[238:241], v180 offset:39936
	global_load_lds_dwordx4 v[242:243], off
	v_lshl_add_u64 v[242:243], s[12:13], 0, v[132:133]
	s_mov_b32 m0, s58
	s_nop 0
	global_load_lds_dwordx4 v[242:243], off
	s_waitcnt vmcnt(8)
	s_waitcnt lgkmcnt(0)
	s_setprio 1
	s_barrier
	v_mfma_f32_16x16x32_bf16 v[124:127], v[164:167], v[210:213], v[124:127]
	v_mfma_f32_16x16x32_bf16 v[120:123], v[172:175], v[210:213], v[120:123]
	v_mfma_f32_16x16x32_bf16 v[116:119], v[164:167], v[218:221], v[116:119]
	v_mfma_f32_16x16x32_bf16 v[112:115], v[172:175], v[218:221], v[112:115]
	v_mfma_f32_16x16x32_bf16 v[108:111], v[164:167], v[226:229], v[108:111]
	v_mfma_f32_16x16x32_bf16 v[104:107], v[172:175], v[226:229], v[104:107]
	v_mfma_f32_16x16x32_bf16 v[100:103], v[164:167], v[234:237], v[100:103]
	v_mfma_f32_16x16x32_bf16 v[96:99], v[172:175], v[234:237], v[96:99]
	v_mfma_f32_16x16x32_bf16 v[124:127], v[168:171], v[214:217], v[124:127]
	v_mfma_f32_16x16x32_bf16 v[120:123], v[190:193], v[214:217], v[120:123]
	v_mfma_f32_16x16x32_bf16 v[116:119], v[168:171], v[222:225], v[116:119]
	v_mfma_f32_16x16x32_bf16 v[112:115], v[190:193], v[222:225], v[112:115]
	v_mfma_f32_16x16x32_bf16 v[108:111], v[168:171], v[230:233], v[108:111]
	v_mfma_f32_16x16x32_bf16 v[104:107], v[190:193], v[230:233], v[104:107]
	v_mfma_f32_16x16x32_bf16 v[100:103], v[168:171], v[238:241], v[100:103]
	v_mfma_f32_16x16x32_bf16 v[96:99], v[190:193], v[238:241], v[96:99]
	v_mfma_f32_16x16x32_bf16 v[92:95], v[194:197], v[210:213], v[92:95]
	v_mfma_f32_16x16x32_bf16 v[88:91], v[202:205], v[210:213], v[88:91]
	v_mfma_f32_16x16x32_bf16 v[84:87], v[194:197], v[218:221], v[84:87]
	v_mfma_f32_16x16x32_bf16 v[80:83], v[202:205], v[218:221], v[80:83]
	v_mfma_f32_16x16x32_bf16 v[76:79], v[194:197], v[226:229], v[76:79]
	v_mfma_f32_16x16x32_bf16 v[72:75], v[202:205], v[226:229], v[72:75]
	v_mfma_f32_16x16x32_bf16 v[68:71], v[194:197], v[234:237], v[68:71]
	v_mfma_f32_16x16x32_bf16 v[64:67], v[202:205], v[234:237], v[64:67]
	v_mfma_f32_16x16x32_bf16 v[92:95], v[198:201], v[214:217], v[92:95]
	v_mfma_f32_16x16x32_bf16 v[88:91], v[206:209], v[214:217], v[88:91]
	v_mfma_f32_16x16x32_bf16 v[84:87], v[198:201], v[222:225], v[84:87]
	v_mfma_f32_16x16x32_bf16 v[80:83], v[206:209], v[222:225], v[80:83]
	v_mfma_f32_16x16x32_bf16 v[76:79], v[198:201], v[230:233], v[76:79]
	v_mfma_f32_16x16x32_bf16 v[72:75], v[206:209], v[230:233], v[72:75]
	v_mfma_f32_16x16x32_bf16 v[68:71], v[198:201], v[238:241], v[68:71]
	v_mfma_f32_16x16x32_bf16 v[64:67], v[206:209], v[238:241], v[64:67]
	s_barrier
; #define PG8_STAGE(bufoff, gbase, voff) do { _Pragma("unroll") for (int _i = 0; _i < 2; ++_i) \
;         __builtin_amdgcn_global_load_lds((const unsigned*)((const char*)(gbase) + (voff)[_i]), (PG8_LAS unsigned*)(lds + (bufoff) + ldsw + _i * 8192), 16, 0, 0); } while (0)
; #define PG8_LDA(dst, b, h) do { _Pragma("unroll") for (int m = 0; m < 4; ++m) _Pragma("unroll") for (int k = 0; k < 2; ++k) dst[m][k] = *(const PG8_LAS bf16x8*)(lds + PG8_SA(b, h) + aoff + m * 2048 + k * 1024); } while (0)
; #define PG8_MMA(ai, bj, At, Bt) do { __builtin_amdgcn_s_setprio(1); _Pragma("unroll") for (int m = 0; m < 4; ++m) _Pragma("unroll") for (int n = 0; n < 2; ++n) _Pragma("unroll") for (int k = 0; k < 2; ++k) \
;         acc[ai][bj][m][n] = __builtin_amdgcn_mfma_f32_16x16x32_bf16(Bt[n][k], At[m][k], acc[ai][bj][m][n], 0, 0, 0); __builtin_amdgcn_s_setprio(0); } while (0)
; #define PG8_WAIT_V(n) asm volatile("s_waitcnt vmcnt(" #n ")" ::: "memory")
; #define PG8_WAIT_L(n) asm volatile("s_waitcnt lgkmcnt(" #n ")" ::: "memory")
; #define PG8_BAR __builtin_amdgcn_s_barrier()
; #define PG8_SCHED __builtin_amdgcn_sched_barrier(0)
; template <class Epi, class Sched, bool ALIGN_EPI = false, bool SP2 = false>
; __device__ __forceinline__ void gemm_phase(PG8_LAS unsigned char* lds, const Gemm g, const Sched& S, const Epi& E) {
;     ...
;             PG8_LDA(At, 1, 1); PG8_STAGE(PG8_SB(1, 0), b3, voffB); PG8_STAGE(PG8_SB(1, 1), b3 + hstepB, voffB); PG8_STAGE(PG8_SA(1, 0), a3, voffA);
;             PG8_WAIT_V(8); PG8_WAIT_L(0); PG8_BAR; PG8_MMA(1, 0, At, B0); PG8_MMA(1, 1, At, B1); PG8_BAR; PG8_SCHED;
	s_setprio 0
	s_add_i32 s12, s17, s54
	v_lshl_add_u64 v[176:177], v[176:177], 0, s[30:31]
	s_mov_b32 m0, s12
	ds_read_b128 v[210:213], v180 offset:49152
	ds_read_b128 v[214:217], v180 offset:50176
	ds_read_b128 v[218:221], v180 offset:51200
	ds_read_b128 v[222:225], v180 offset:52224
	ds_read_b128 v[226:229], v180 offset:53248
	ds_read_b128 v[230:233], v180 offset:54272
	ds_read_b128 v[234:237], v180 offset:55296
	ds_read_b128 v[238:241], v180 offset:56320
	global_load_lds_dwordx4 v[176:177], off
	s_add_i32 m0, s12, 0x2000
	s_add_u32 s12, s50, 0x160080
	v_lshl_add_u64 v[176:177], v[182:183], 0, s[30:31]
	s_addc_u32 s13, s51, 0
	s_add_i32 s17, s19, s54
	global_load_lds_dwordx4 v[176:177], off
	v_lshl_add_u64 v[176:177], s[12:13], 0, v[130:131]
	s_mov_b32 m0, s17
	s_nop 0
	global_load_lds_dwordx4 v[176:177], off
	v_lshl_add_u64 v[176:177], s[12:13], 0, v[134:135]
	s_add_i32 m0, s17, 0x2000
	s_nop 0
	global_load_lds_dwordx4 v[176:177], off
	v_lshl_add_u64 v[176:177], s[48:49], 0, v[128:129]
	s_mov_b32 m0, s62
	s_nop 0
	global_load_lds_dwordx4 v[176:177], off
	v_lshl_add_u64 v[176:177], s[48:49], 0, v[132:133]
	s_mov_b32 m0, s63
	s_nop 0
	global_load_lds_dwordx4 v[176:177], off
	s_waitcnt vmcnt(8)
	s_waitcnt lgkmcnt(0)
	s_setprio 1
	s_barrier
	v_mfma_f32_16x16x32_bf16 v[60:63], v[164:167], v[210:213], v[60:63]
	v_mfma_f32_16x16x32_bf16 v[56:59], v[172:175], v[210:213], v[56:59]
	v_mfma_f32_16x16x32_bf16 v[52:55], v[164:167], v[218:221], v[52:55]
	v_mfma_f32_16x16x32_bf16 v[48:51], v[172:175], v[218:221], v[48:51]
	v_mfma_f32_16x16x32_bf16 v[44:47], v[164:167], v[226:229], v[44:47]
	v_mfma_f32_16x16x32_bf16 v[40:43], v[172:175], v[226:229], v[40:43]
	v_mfma_f32_16x16x32_bf16 v[36:39], v[164:167], v[234:237], v[36:39]
	v_mfma_f32_16x16x32_bf16 v[32:35], v[172:175], v[234:237], v[32:35]
	v_mfma_f32_16x16x32_bf16 v[60:63], v[168:171], v[214:217], v[60:63]
	v_mfma_f32_16x16x32_bf16 v[56:59], v[190:193], v[214:217], v[56:59]
	v_mfma_f32_16x16x32_bf16 v[52:55], v[168:171], v[222:225], v[52:55]
	v_mfma_f32_16x16x32_bf16 v[48:51], v[190:193], v[222:225], v[48:51]
	v_mfma_f32_16x16x32_bf16 v[44:47], v[168:171], v[230:233], v[44:47]
	v_mfma_f32_16x16x32_bf16 v[40:43], v[190:193], v[230:233], v[40:43]
	v_mfma_f32_16x16x32_bf16 v[36:39], v[168:171], v[238:241], v[36:39]
	v_mfma_f32_16x16x32_bf16 v[32:35], v[190:193], v[238:241], v[32:35]
	v_mfma_f32_16x16x32_bf16 v[28:31], v[194:197], v[210:213], v[28:31]
	v_mfma_f32_16x16x32_bf16 v[24:27], v[202:205], v[210:213], v[24:27]
	v_mfma_f32_16x16x32_bf16 v[20:23], v[194:197], v[218:221], v[20:23]
	v_mfma_f32_16x16x32_bf16 v[16:19], v[202:205], v[218:221], v[16:19]
	v_mfma_f32_16x16x32_bf16 v[12:15], v[194:197], v[226:229], v[12:15]
	v_mfma_f32_16x16x32_bf16 v[8:11], v[202:205], v[226:229], v[8:11]
	v_mfma_f32_16x16x32_bf16 v[4:7], v[194:197], v[234:237], v[4:7]
	v_mfma_f32_16x16x32_bf16 v[0:3], v[202:205], v[234:237], v[0:3]
	v_mfma_f32_16x16x32_bf16 v[28:31], v[198:201], v[214:217], v[28:31]
	v_mfma_f32_16x16x32_bf16 v[24:27], v[206:209], v[214:217], v[24:27]
	v_mfma_f32_16x16x32_bf16 v[20:23], v[198:201], v[222:225], v[20:23]
	v_mfma_f32_16x16x32_bf16 v[16:19], v[206:209], v[222:225], v[16:19]
	v_mfma_f32_16x16x32_bf16 v[12:15], v[198:201], v[230:233], v[12:15]
	v_mfma_f32_16x16x32_bf16 v[8:11], v[206:209], v[230:233], v[8:11]
	v_mfma_f32_16x16x32_bf16 v[4:7], v[198:201], v[238:241], v[4:7]
	v_mfma_f32_16x16x32_bf16 v[0:3], v[206:209], v[238:241], v[0:3]
	s_barrier
	s_setprio 0
	s_add_i32 s12, s5, 2
	s_add_u32 s46, s46, 0x10000
	s_addc_u32 s47, s47, 0
	s_add_u32 s1, s1, 0x100
	s_addc_u32 s4, s4, 0
	v_lshl_add_u64 v[162:163], v[162:163], 0, s[38:39]
	v_lshl_add_u64 v[160:161], v[160:161], 0, s[38:39]
	s_cmp_ge_i32 s5, s7
	s_mov_b32 s5, s12
	s_cbranch_scc0 .LBB0_3147
	s_and_b64 vcc, exec, s[36:37]
	s_cbranch_vccz .LBB0_3150
	s_barrier
